# PEER u-side dot products via exact fp4->bf16 cvt + v_dot2c_f32_bf16 (f32 accumulate) instead of cvt_f32+pk_fma; fewer VALU per gathered row
# speedup vs baseline: 1.0300x; 1.0300x over previous
; #define GAS __attribute__((address_space(1)))
; __device__ __forceinline__ void peer_gather_f4p(const float* X, const int* __restrict__ IDX, const float* __restrict__ G, ...
;     ...
;     for (int kt = 0; kt < 4; ++kt) {
;         const int row = blockIdx.x * 32 + wave * 4 + kt;
;         int lane = tid_ & 63; asm volatile("" : "+v"(lane));
;         f32x2 xr[16];
; #pragma unroll
;         for (int j = 0; j < 8; ++j) {
;             if (RES_BF16) {
;                 const u32x2 t2 = *(const GAS u32x2*)((const GAS bf16_t*)xbout + (size_t)row * D + 256 * j + lane * 4);
;                 xr[2 * j] = f32x2{__uint_as_float(t2[0] << 16), __uint_as_float(t2[0] & 0xffff0000u)}; xr[2 * j + 1] = f32x2{__uint_as_float(t2[1] << 16), __uint_as_float(t2[1] & 0xffff0000u)};
;             } else {
;                 const f32x4 t4 = *(const GAS f32x4*)((const GAS float*)X + (size_t)row * D + 256 * j + lane * 4);
;                 xr[2 * j] = f32x2{t4[0], t4[1]}; xr[2 * j + 1] = f32x2{t4[2], t4[3]};
;             }
;         }
;         const int k0 = keys[kt * 128 + lane], k1 = keys[kt * 128 + 64 + lane];
;         const int kn = keys[((kt + 1) & 3) * 128 + lane];
;         const GAS unsigned char* nbase = (kt < 3) ? Ug : Vg;
.LBB0_531:
	s_add_i32 s12, s26, s62
	s_ashr_i32 s13, s12, 31
	v_mov_b32_e32 v42, v1
	s_lshl_b64 s[12:13], s[12:13], 12
	s_add_u32 s12, s15, s12
	v_lshlrev_b32_e32 v32, 2, v42
	s_addc_u32 s13, s18, s13
	v_ashrrev_i32_e32 v33, 31, v32
	v_lshl_add_u64 v[34:35], v[32:33], 1, s[12:13]
	global_load_dwordx2 v[4:5], v[34:35], off
	global_load_dwordx2 v[8:9], v[34:35], off offset:512
	global_load_dwordx2 v[12:13], v[34:35], off offset:1024
	global_load_dwordx2 v[16:17], v[34:35], off offset:1536
	global_load_dwordx2 v[20:21], v[34:35], off offset:2048
	global_load_dwordx2 v[24:25], v[34:35], off offset:2560
	global_load_dwordx2 v[28:29], v[34:35], off offset:3072
	s_lshl_b32 s12, s26, 9
	global_load_dwordx2 v[34:35], v[34:35], off offset:3584
	s_add_i32 s12, s14, s12
	s_add_i32 s19, s26, 1
	v_add_u32_e32 v2, s12, v32
	s_lshl_b32 s12, s19, 9
	s_and_b32 s12, s12, 0x600
	s_add_i32 s12, s14, s12
	ds_read2st64_b32 v[38:39], v2 offset1:1
	v_add_u32_e32 v2, s12, v32
	ds_read_b32 v2, v2
	v_and_b32_e32 v43, 8, v42
	v_cmp_eq_u32_e64 s[48:49], 0, v43
	v_and_b32_e32 v43, 4, v42
	v_lshlrev_b32_e32 v32, 4, v42
	v_cmp_eq_u32_e64 s[46:47], 0, v43
	v_and_b32_e32 v43, 2, v42
	v_and_b32_e32 v44, 15, v42
	v_ashrrev_i32_e32 v33, 31, v32
	v_cmp_eq_u32_e64 s[44:45], 0, v43
	v_and_b32_e32 v43, 1, v42
	v_cmp_gt_i32_e32 vcc, 16, v42
	v_add_u32_e32 v42, s17, v44
	s_lshl_b32 s27, s26, 7
	v_lshl_add_u64 v[40:41], s[54:55], 0, v[32:33]
	v_cmp_eq_u32_e64 s[42:43], 0, v43
	v_lshl_add_u32 v45, v42, 2, s16
	s_mov_b32 s28, 31
	s_mov_b32 s29, 0
	s_waitcnt vmcnt(7)
	v_mov_b32_e32 v6, v4
	v_mov_b32_e32 v4, v5
	s_waitcnt vmcnt(6)
	v_mov_b32_e32 v10, v8
	v_mov_b32_e32 v8, v9
	s_waitcnt vmcnt(5)
	v_mov_b32_e32 v14, v12
	v_mov_b32_e32 v12, v13
	s_waitcnt vmcnt(4)
	v_mov_b32_e32 v18, v16
	v_mov_b32_e32 v16, v17
	s_waitcnt vmcnt(3)
	v_mov_b32_e32 v22, v20
	v_mov_b32_e32 v20, v21
	s_waitcnt vmcnt(2)
	v_mov_b32_e32 v26, v24
	v_mov_b32_e32 v24, v25
	s_waitcnt vmcnt(1)
	v_mov_b32_e32 v30, v28
	v_mov_b32_e32 v28, v29
	s_waitcnt vmcnt(0)
	v_mov_b32_e32 v36, v34
	v_mov_b32_e32 v34, v35
	s_branch .LBB0_533

; #define P4_FOR16(M) M(0) M(1) M(2) M(3) M(4) M(5) M(6) M(7) M(8) M(9) M(10) M(11) M(12) M(13) M(14) M(15)
; #define P4_U(i) { P4_DOT(b##i, part[i]); const int nk_ = __builtin_amdgcn_readlane(ksel, nb + i); P4_LOAD(b##i, Ug, nk_); }
; #define P4_U(i) { P4_DOT(b##i, part[i]); const int nk_ = __builtin_amdgcn_readlane(kn, i); P4_LOAD(b##i, nbase, nk_); }
; __device__ __forceinline__ void peer_gather_f4p(const float* X, const int* __restrict__ IDX, const float* __restrict__ G, ...
;     ...
; #pragma unroll 1
;         for (int bt = 0; bt < 7; ++bt) {
;             const int ksel = (bt + 1 < 4) ? k0 : k1;
;             const int nb = (16 * (bt + 1)) & 63;
;     ...
;             P4_FOR16(P4_U)
;     ...
;             P4_RED(bt);
;         }
.LBB0_533:
	s_mov_b32 s87, s86
	s_waitcnt vmcnt(15)
	v_cvt_scalef32_pk_bf16_fp4 v48, v64, 1.0
	v_mov_b32_e32 v56, 0
	v_cvt_scalef32_pk_bf16_fp4 v50, v64, 1.0 op_sel:[1,0,0]
	v_cvt_scalef32_pk_bf16_fp4 v52, v64, 1.0 op_sel:[0,1,0]
	v_cvt_scalef32_pk_bf16_fp4 v54, v64, 1.0 op_sel:[1,1,0]
	v_dot2c_f32_bf16_e32 v56, v48, v6
	v_mov_b32_e32 v48, 0
	v_dot2c_f32_bf16_e32 v48, v50, v4
	v_dot2c_f32_bf16_e32 v56, v52, v10
	s_cmp_lt_u32 s29, 3
	v_dot2c_f32_bf16_e32 v48, v54, v8
	v_cvt_scalef32_pk_bf16_fp4 v50, v65, 1.0
	v_cvt_scalef32_pk_bf16_fp4 v52, v65, 1.0 op_sel:[1,0,0]
	v_cvt_scalef32_pk_bf16_fp4 v54, v65, 1.0 op_sel:[0,1,0]
	v_cvt_scalef32_pk_bf16_fp4 v58, v65, 1.0 op_sel:[1,1,0]
	s_cselect_b64 s[50:51], -1, 0
	v_dot2c_f32_bf16_e32 v56, v50, v14
	v_dot2c_f32_bf16_e32 v48, v52, v12
	s_waitcnt lgkmcnt(1)
	v_cndmask_b32_e64 v46, v39, v38, s[50:51]
	v_dot2c_f32_bf16_e32 v56, v54, v18
	v_dot2c_f32_bf16_e32 v48, v58, v16
	v_cvt_scalef32_pk_bf16_fp4 v50, v66, 1.0
	v_cvt_scalef32_pk_bf16_fp4 v52, v66, 1.0 op_sel:[1,0,0]
	v_cvt_scalef32_pk_bf16_fp4 v54, v66, 1.0 op_sel:[0,1,0]
	v_cvt_scalef32_pk_bf16_fp4 v58, v66, 1.0 op_sel:[1,1,0]
	s_add_i32 s12, s28, -15
	v_dot2c_f32_bf16_e32 v56, v50, v22
	v_dot2c_f32_bf16_e32 v48, v52, v20
	v_readlane_b32 s12, v46, s12
	v_dot2c_f32_bf16_e32 v56, v54, v26
	v_dot2c_f32_bf16_e32 v48, v58, v24
	v_cvt_scalef32_pk_bf16_fp4 v50, v67, 1.0
	v_cvt_scalef32_pk_bf16_fp4 v52, v67, 1.0 op_sel:[1,0,0]
	v_cvt_scalef32_pk_bf16_fp4 v54, v67, 1.0 op_sel:[0,1,0]
	v_cvt_scalef32_pk_bf16_fp4 v58, v67, 1.0 op_sel:[1,1,0]
	s_lshr_b32 s12, s12, 7
	v_dot2c_f32_bf16_e32 v56, v50, v30
	v_dot2c_f32_bf16_e32 v48, v52, v28
	s_mov_b32 s13, s86
	v_dot2c_f32_bf16_e32 v56, v54, v36
	v_dot2c_f32_bf16_e32 v48, v58, v34
	s_lshl_b64 s[12:13], s[12:13], 10
	s_nop 2
	v_add_f32_e32 v47, v56, v48
	v_lshl_add_u64 v[48:49], v[40:41], 0, s[12:13]
	global_load_dwordx4 v[64:67], v[48:49], off
	s_waitcnt vmcnt(15)
	v_cvt_scalef32_pk_bf16_fp4 v48, v68, 1.0
	v_mov_b32_e32 v56, 0
	v_cvt_scalef32_pk_bf16_fp4 v50, v68, 1.0 op_sel:[1,0,0]
	v_cvt_scalef32_pk_bf16_fp4 v52, v68, 1.0 op_sel:[0,1,0]
	v_cvt_scalef32_pk_bf16_fp4 v54, v68, 1.0 op_sel:[1,1,0]
	v_dot2c_f32_bf16_e32 v56, v48, v6
	v_mov_b32_e32 v48, 0
	v_dot2c_f32_bf16_e32 v48, v50, v4
	v_dot2c_f32_bf16_e32 v56, v52, v10
	s_add_i32 s12, s28, -14
	v_dot2c_f32_bf16_e32 v48, v54, v8
	v_cvt_scalef32_pk_bf16_fp4 v50, v69, 1.0
	v_cvt_scalef32_pk_bf16_fp4 v52, v69, 1.0 op_sel:[1,0,0]
	v_cvt_scalef32_pk_bf16_fp4 v54, v69, 1.0 op_sel:[0,1,0]
	v_cvt_scalef32_pk_bf16_fp4 v58, v69, 1.0 op_sel:[1,1,0]
	v_readlane_b32 s12, v46, s12
	v_dot2c_f32_bf16_e32 v56, v50, v14
	v_dot2c_f32_bf16_e32 v48, v52, v12
	s_lshr_b32 s12, s12, 7
	v_dot2c_f32_bf16_e32 v56, v54, v18
	v_dot2c_f32_bf16_e32 v48, v58, v16
	v_cvt_scalef32_pk_bf16_fp4 v50, v70, 1.0
	v_cvt_scalef32_pk_bf16_fp4 v52, v70, 1.0 op_sel:[1,0,0]
	v_cvt_scalef32_pk_bf16_fp4 v54, v70, 1.0 op_sel:[0,1,0]
	v_cvt_scalef32_pk_bf16_fp4 v58, v70, 1.0 op_sel:[1,1,0]
	s_mov_b32 s13, s86
	v_dot2c_f32_bf16_e32 v56, v50, v22
	v_dot2c_f32_bf16_e32 v48, v52, v20
	s_lshl_b64 s[12:13], s[12:13], 10
	v_dot2c_f32_bf16_e32 v56, v54, v26
	v_dot2c_f32_bf16_e32 v48, v58, v24
	v_cvt_scalef32_pk_bf16_fp4 v50, v71, 1.0
	v_cvt_scalef32_pk_bf16_fp4 v52, v71, 1.0 op_sel:[1,0,0]
	v_cvt_scalef32_pk_bf16_fp4 v54, v71, 1.0 op_sel:[0,1,0]
	v_cvt_scalef32_pk_bf16_fp4 v58, v71, 1.0 op_sel:[1,1,0]
	v_mov_b32_e32 v100, 0
	v_dot2c_f32_bf16_e32 v56, v50, v30
	v_dot2c_f32_bf16_e32 v48, v52, v28
	v_mov_b32_e32 v42, 0
	v_dot2c_f32_bf16_e32 v56, v54, v36
	v_dot2c_f32_bf16_e32 v48, v58, v34
	v_mov_b32_e32 v58, 0
	s_nop 2
	v_add_f32_e32 v48, v56, v48
	v_lshl_add_u64 v[50:51], v[40:41], 0, s[12:13]
	global_load_dwordx4 v[68:71], v[50:51], off
	s_waitcnt vmcnt(15)
	v_cvt_scalef32_pk_bf16_fp4 v50, v72, 1.0
	v_cvt_scalef32_pk_bf16_fp4 v52, v72, 1.0 op_sel:[1,0,0]
	v_cvt_scalef32_pk_bf16_fp4 v54, v72, 1.0 op_sel:[0,1,0]
	v_cvt_scalef32_pk_bf16_fp4 v56, v72, 1.0 op_sel:[1,1,0]
	s_add_i32 s12, s28, -13
	v_dot2c_f32_bf16_e32 v58, v50, v6
	v_mov_b32_e32 v50, 0
	v_dot2c_f32_bf16_e32 v50, v52, v4
	v_dot2c_f32_bf16_e32 v58, v54, v10
	v_readlane_b32 s12, v46, s12
	v_dot2c_f32_bf16_e32 v50, v56, v8
	v_cvt_scalef32_pk_bf16_fp4 v52, v73, 1.0
	v_cvt_scalef32_pk_bf16_fp4 v54, v73, 1.0 op_sel:[1,0,0]
	v_cvt_scalef32_pk_bf16_fp4 v56, v73, 1.0 op_sel:[0,1,0]
	v_cvt_scalef32_pk_bf16_fp4 v60, v73, 1.0 op_sel:[1,1,0]
	s_lshr_b32 s12, s12, 7
	v_dot2c_f32_bf16_e32 v58, v52, v14
	v_dot2c_f32_bf16_e32 v50, v54, v12
	s_mov_b32 s13, s86
	v_dot2c_f32_bf16_e32 v58, v56, v18
	v_dot2c_f32_bf16_e32 v50, v60, v16
	v_cvt_scalef32_pk_bf16_fp4 v52, v74, 1.0
	v_cvt_scalef32_pk_bf16_fp4 v54, v74, 1.0 op_sel:[1,0,0]
	v_cvt_scalef32_pk_bf16_fp4 v56, v74, 1.0 op_sel:[0,1,0]
	v_cvt_scalef32_pk_bf16_fp4 v60, v74, 1.0 op_sel:[1,1,0]
	s_lshl_b64 s[12:13], s[12:13], 10
	v_dot2c_f32_bf16_e32 v58, v52, v22
	v_dot2c_f32_bf16_e32 v50, v54, v20
	s_nop 0
	v_dot2c_f32_bf16_e32 v58, v56, v26
	v_dot2c_f32_bf16_e32 v50, v60, v24
	v_cvt_scalef32_pk_bf16_fp4 v52, v75, 1.0
	v_cvt_scalef32_pk_bf16_fp4 v54, v75, 1.0 op_sel:[1,0,0]
	v_cvt_scalef32_pk_bf16_fp4 v56, v75, 1.0 op_sel:[0,1,0]
	v_cvt_scalef32_pk_bf16_fp4 v60, v75, 1.0 op_sel:[1,1,0]
	s_nop 0
	v_dot2c_f32_bf16_e32 v58, v52, v30
	v_dot2c_f32_bf16_e32 v50, v54, v28
	s_nop 0
	v_dot2c_f32_bf16_e32 v58, v56, v36
	v_dot2c_f32_bf16_e32 v50, v60, v34
	s_nop 0
	s_nop 2
	v_add_f32_e32 v49, v58, v50
	v_lshl_add_u64 v[50:51], v[40:41], 0, s[12:13]
	global_load_dwordx4 v[72:75], v[50:51], off
	s_waitcnt vmcnt(15)
; #define P4_FOR16(M) M(0) M(1) M(2) M(3) M(4) M(5) M(6) M(7) M(8) M(9) M(10) M(11) M(12) M(13) M(14) M(15)
; #define P4_U(i) { P4_DOT(b##i, part[i]); const int nk_ = __builtin_amdgcn_readlane(ksel, nb + i); P4_LOAD(b##i, Ug, nk_); }
; #define P4_U(i) { P4_DOT(b##i, part[i]); const int nk_ = __builtin_amdgcn_readlane(kn, i); P4_LOAD(b##i, nbase, nk_); }
; __device__ __forceinline__ void peer_gather_f4p(const float* X, const int* __restrict__ IDX, const float* __restrict__ G, ...
;     ...
; #pragma unroll 1
;         for (int bt = 0; bt < 7; ++bt) {
;             const int ksel = (bt + 1 < 4) ? k0 : k1;
;             const int nb = (16 * (bt + 1)) & 63;
;     ...
;             P4_FOR16(P4_U)
;     ...
;             P4_RED(bt);
;         }
	v_cvt_scalef32_pk_bf16_fp4 v50, v76, 1.0
	v_mov_b32_e32 v58, 0
	v_cvt_scalef32_pk_bf16_fp4 v52, v76, 1.0 op_sel:[1,0,0]
	v_cvt_scalef32_pk_bf16_fp4 v54, v76, 1.0 op_sel:[0,1,0]
	v_cvt_scalef32_pk_bf16_fp4 v56, v76, 1.0 op_sel:[1,1,0]
	v_dot2c_f32_bf16_e32 v58, v50, v6
	v_mov_b32_e32 v50, 0
	v_dot2c_f32_bf16_e32 v50, v52, v4
	v_dot2c_f32_bf16_e32 v58, v54, v10
	s_add_i32 s12, s28, -12
	v_dot2c_f32_bf16_e32 v50, v56, v8
	v_cvt_scalef32_pk_bf16_fp4 v52, v77, 1.0
	v_cvt_scalef32_pk_bf16_fp4 v54, v77, 1.0 op_sel:[1,0,0]
	v_cvt_scalef32_pk_bf16_fp4 v56, v77, 1.0 op_sel:[0,1,0]
	v_cvt_scalef32_pk_bf16_fp4 v60, v77, 1.0 op_sel:[1,1,0]
	v_readlane_b32 s12, v46, s12
	v_dot2c_f32_bf16_e32 v58, v52, v14
	v_dot2c_f32_bf16_e32 v50, v54, v12
	s_lshr_b32 s12, s12, 7
	v_dot2c_f32_bf16_e32 v58, v56, v18
	v_dot2c_f32_bf16_e32 v50, v60, v16
	v_cvt_scalef32_pk_bf16_fp4 v52, v78, 1.0
	v_cvt_scalef32_pk_bf16_fp4 v54, v78, 1.0 op_sel:[1,0,0]
	v_cvt_scalef32_pk_bf16_fp4 v56, v78, 1.0 op_sel:[0,1,0]
	v_cvt_scalef32_pk_bf16_fp4 v60, v78, 1.0 op_sel:[1,1,0]
	s_mov_b32 s13, s86
	v_dot2c_f32_bf16_e32 v58, v52, v22
	v_dot2c_f32_bf16_e32 v50, v54, v20
	s_lshl_b64 s[12:13], s[12:13], 10
	v_dot2c_f32_bf16_e32 v58, v56, v26
	v_dot2c_f32_bf16_e32 v50, v60, v24
	v_cvt_scalef32_pk_bf16_fp4 v52, v79, 1.0
	v_cvt_scalef32_pk_bf16_fp4 v54, v79, 1.0 op_sel:[1,0,0]
	v_cvt_scalef32_pk_bf16_fp4 v56, v79, 1.0 op_sel:[0,1,0]
	v_cvt_scalef32_pk_bf16_fp4 v60, v79, 1.0 op_sel:[1,1,0]
	s_nop 0
	v_dot2c_f32_bf16_e32 v58, v52, v30
	v_dot2c_f32_bf16_e32 v50, v54, v28
	s_nop 0
	v_dot2c_f32_bf16_e32 v58, v56, v36
	v_dot2c_f32_bf16_e32 v50, v60, v34
	v_mov_b32_e32 v60, 0
	s_nop 2
	v_add_f32_e32 v50, v58, v50
	v_lshl_add_u64 v[52:53], v[40:41], 0, s[12:13]
	global_load_dwordx4 v[76:79], v[52:53], off
	s_waitcnt vmcnt(15)
	v_cvt_scalef32_pk_bf16_fp4 v52, v80, 1.0
	v_cvt_scalef32_pk_bf16_fp4 v54, v80, 1.0 op_sel:[1,0,0]
	v_cvt_scalef32_pk_bf16_fp4 v56, v80, 1.0 op_sel:[0,1,0]
	v_cvt_scalef32_pk_bf16_fp4 v58, v80, 1.0 op_sel:[1,1,0]
	s_add_i32 s12, s28, -11
	v_dot2c_f32_bf16_e32 v60, v52, v6
	v_mov_b32_e32 v52, 0
	v_dot2c_f32_bf16_e32 v52, v54, v4
	v_dot2c_f32_bf16_e32 v60, v56, v10
	v_readlane_b32 s12, v46, s12
	v_dot2c_f32_bf16_e32 v52, v58, v8
	v_cvt_scalef32_pk_bf16_fp4 v54, v81, 1.0
	v_cvt_scalef32_pk_bf16_fp4 v56, v81, 1.0 op_sel:[1,0,0]
	v_cvt_scalef32_pk_bf16_fp4 v58, v81, 1.0 op_sel:[0,1,0]
	v_cvt_scalef32_pk_bf16_fp4 v62, v81, 1.0 op_sel:[1,1,0]
	s_lshr_b32 s12, s12, 7
	v_dot2c_f32_bf16_e32 v60, v54, v14
	v_dot2c_f32_bf16_e32 v52, v56, v12
	s_mov_b32 s13, s86
	v_dot2c_f32_bf16_e32 v60, v58, v18
	v_dot2c_f32_bf16_e32 v52, v62, v16
	v_cvt_scalef32_pk_bf16_fp4 v54, v82, 1.0
	v_cvt_scalef32_pk_bf16_fp4 v56, v82, 1.0 op_sel:[1,0,0]
	v_cvt_scalef32_pk_bf16_fp4 v58, v82, 1.0 op_sel:[0,1,0]
	v_cvt_scalef32_pk_bf16_fp4 v62, v82, 1.0 op_sel:[1,1,0]
	s_lshl_b64 s[12:13], s[12:13], 10
	v_dot2c_f32_bf16_e32 v60, v54, v22
	v_dot2c_f32_bf16_e32 v52, v56, v20
	s_nop 0
	v_dot2c_f32_bf16_e32 v60, v58, v26
	v_dot2c_f32_bf16_e32 v52, v62, v24
	v_cvt_scalef32_pk_bf16_fp4 v54, v83, 1.0
	v_cvt_scalef32_pk_bf16_fp4 v56, v83, 1.0 op_sel:[1,0,0]
	v_cvt_scalef32_pk_bf16_fp4 v58, v83, 1.0 op_sel:[0,1,0]
	v_cvt_scalef32_pk_bf16_fp4 v62, v83, 1.0 op_sel:[1,1,0]
	s_nop 0
	v_dot2c_f32_bf16_e32 v60, v54, v30
	v_dot2c_f32_bf16_e32 v52, v56, v28
	s_nop 0
	v_dot2c_f32_bf16_e32 v60, v58, v36
	v_dot2c_f32_bf16_e32 v52, v62, v34
	s_nop 0
	s_nop 2
	v_add_f32_e32 v51, v60, v52
	v_lshl_add_u64 v[52:53], v[40:41], 0, s[12:13]
	global_load_dwordx4 v[80:83], v[52:53], off
	s_waitcnt vmcnt(15)
	v_cvt_scalef32_pk_bf16_fp4 v52, v84, 1.0
	v_mov_b32_e32 v60, 0
	v_cvt_scalef32_pk_bf16_fp4 v54, v84, 1.0 op_sel:[1,0,0]
	v_cvt_scalef32_pk_bf16_fp4 v56, v84, 1.0 op_sel:[0,1,0]
	v_cvt_scalef32_pk_bf16_fp4 v58, v84, 1.0 op_sel:[1,1,0]
	v_dot2c_f32_bf16_e32 v60, v52, v6
	v_mov_b32_e32 v52, 0
	v_dot2c_f32_bf16_e32 v52, v54, v4
	v_dot2c_f32_bf16_e32 v60, v56, v10
	s_add_i32 s12, s28, -10
	v_dot2c_f32_bf16_e32 v52, v58, v8
	v_cvt_scalef32_pk_bf16_fp4 v54, v85, 1.0
	v_cvt_scalef32_pk_bf16_fp4 v56, v85, 1.0 op_sel:[1,0,0]
	v_cvt_scalef32_pk_bf16_fp4 v58, v85, 1.0 op_sel:[0,1,0]
	v_cvt_scalef32_pk_bf16_fp4 v62, v85, 1.0 op_sel:[1,1,0]
	v_readlane_b32 s12, v46, s12
	v_dot2c_f32_bf16_e32 v60, v54, v14
	v_dot2c_f32_bf16_e32 v52, v56, v12
	s_lshr_b32 s12, s12, 7
	v_dot2c_f32_bf16_e32 v60, v58, v18
	v_dot2c_f32_bf16_e32 v52, v62, v16
	v_cvt_scalef32_pk_bf16_fp4 v54, v86, 1.0
	v_cvt_scalef32_pk_bf16_fp4 v56, v86, 1.0 op_sel:[1,0,0]
	v_cvt_scalef32_pk_bf16_fp4 v58, v86, 1.0 op_sel:[0,1,0]
	v_cvt_scalef32_pk_bf16_fp4 v62, v86, 1.0 op_sel:[1,1,0]
	s_mov_b32 s13, s86
	v_dot2c_f32_bf16_e32 v60, v54, v22
	v_dot2c_f32_bf16_e32 v52, v56, v20
	s_lshl_b64 s[12:13], s[12:13], 10
	v_dot2c_f32_bf16_e32 v60, v58, v26
	v_dot2c_f32_bf16_e32 v52, v62, v24
	v_cvt_scalef32_pk_bf16_fp4 v54, v87, 1.0
	v_cvt_scalef32_pk_bf16_fp4 v56, v87, 1.0 op_sel:[1,0,0]
	v_cvt_scalef32_pk_bf16_fp4 v58, v87, 1.0 op_sel:[0,1,0]
	v_cvt_scalef32_pk_bf16_fp4 v62, v87, 1.0 op_sel:[1,1,0]
	s_nop 0
	v_dot2c_f32_bf16_e32 v60, v54, v30
	v_dot2c_f32_bf16_e32 v52, v56, v28
	s_nop 0
	v_dot2c_f32_bf16_e32 v60, v58, v36
	v_dot2c_f32_bf16_e32 v52, v62, v34
	v_mov_b32_e32 v62, 0
	s_nop 2
	v_add_f32_e32 v52, v60, v52
	v_lshl_add_u64 v[54:55], v[40:41], 0, s[12:13]
	global_load_dwordx4 v[84:87], v[54:55], off
	s_waitcnt vmcnt(15)
; #define P4_FOR16(M) M(0) M(1) M(2) M(3) M(4) M(5) M(6) M(7) M(8) M(9) M(10) M(11) M(12) M(13) M(14) M(15)
; #define P4_U(i) { P4_DOT(b##i, part[i]); const int nk_ = __builtin_amdgcn_readlane(ksel, nb + i); P4_LOAD(b##i, Ug, nk_); }
; #define P4_U(i) { P4_DOT(b##i, part[i]); const int nk_ = __builtin_amdgcn_readlane(kn, i); P4_LOAD(b##i, nbase, nk_); }
; __device__ __forceinline__ void peer_gather_f4p(const float* X, const int* __restrict__ IDX, const float* __restrict__ G, ...
;     ...
; #pragma unroll 1
;         for (int bt = 0; bt < 7; ++bt) {
;             const int ksel = (bt + 1 < 4) ? k0 : k1;
;             const int nb = (16 * (bt + 1)) & 63;
;     ...
;             P4_FOR16(P4_U)
;     ...
;             P4_RED(bt);
;         }
	v_cvt_scalef32_pk_bf16_fp4 v54, v88, 1.0
	v_cvt_scalef32_pk_bf16_fp4 v56, v88, 1.0 op_sel:[1,0,0]
	v_cvt_scalef32_pk_bf16_fp4 v58, v88, 1.0 op_sel:[0,1,0]
	v_cvt_scalef32_pk_bf16_fp4 v60, v88, 1.0 op_sel:[1,1,0]
	s_add_i32 s12, s28, -9
	v_dot2c_f32_bf16_e32 v62, v54, v6
	v_mov_b32_e32 v54, 0
	v_dot2c_f32_bf16_e32 v54, v56, v4
	v_dot2c_f32_bf16_e32 v62, v58, v10
	v_readlane_b32 s12, v46, s12
	v_dot2c_f32_bf16_e32 v54, v60, v8
	v_cvt_scalef32_pk_bf16_fp4 v56, v89, 1.0
	v_cvt_scalef32_pk_bf16_fp4 v58, v89, 1.0 op_sel:[1,0,0]
	v_cvt_scalef32_pk_bf16_fp4 v60, v89, 1.0 op_sel:[0,1,0]
	v_cvt_scalef32_pk_bf16_fp4 v88, v89, 1.0 op_sel:[1,1,0]
	s_lshr_b32 s12, s12, 7
	v_dot2c_f32_bf16_e32 v62, v56, v14
	v_dot2c_f32_bf16_e32 v54, v58, v12
	s_mov_b32 s13, s86
	v_dot2c_f32_bf16_e32 v62, v60, v18
	v_dot2c_f32_bf16_e32 v54, v88, v16
	v_cvt_scalef32_pk_bf16_fp4 v56, v90, 1.0
	v_cvt_scalef32_pk_bf16_fp4 v58, v90, 1.0 op_sel:[1,0,0]
	v_cvt_scalef32_pk_bf16_fp4 v60, v90, 1.0 op_sel:[0,1,0]
	v_cvt_scalef32_pk_bf16_fp4 v88, v90, 1.0 op_sel:[1,1,0]
	s_lshl_b64 s[12:13], s[12:13], 10
	v_dot2c_f32_bf16_e32 v62, v56, v22
	v_dot2c_f32_bf16_e32 v54, v58, v20
	s_nop 0
	v_dot2c_f32_bf16_e32 v62, v60, v26
	v_dot2c_f32_bf16_e32 v54, v88, v24
	v_cvt_scalef32_pk_bf16_fp4 v56, v91, 1.0
	v_cvt_scalef32_pk_bf16_fp4 v58, v91, 1.0 op_sel:[1,0,0]
	v_cvt_scalef32_pk_bf16_fp4 v60, v91, 1.0 op_sel:[0,1,0]
	v_cvt_scalef32_pk_bf16_fp4 v88, v91, 1.0 op_sel:[1,1,0]
	s_nop 0
	v_dot2c_f32_bf16_e32 v62, v56, v30
	v_dot2c_f32_bf16_e32 v54, v58, v28
	s_nop 0
	v_dot2c_f32_bf16_e32 v62, v60, v36
	v_dot2c_f32_bf16_e32 v54, v88, v34
	s_nop 0
	s_nop 2
	v_add_f32_e32 v53, v62, v54
	v_lshl_add_u64 v[54:55], v[40:41], 0, s[12:13]
	global_load_dwordx4 v[88:91], v[54:55], off
	s_waitcnt vmcnt(15)
	v_cvt_scalef32_pk_bf16_fp4 v54, v92, 1.0
	v_mov_b32_e32 v62, 0
	v_cvt_scalef32_pk_bf16_fp4 v56, v92, 1.0 op_sel:[1,0,0]
	v_cvt_scalef32_pk_bf16_fp4 v58, v92, 1.0 op_sel:[0,1,0]
	v_cvt_scalef32_pk_bf16_fp4 v60, v92, 1.0 op_sel:[1,1,0]
	v_dot2c_f32_bf16_e32 v62, v54, v6
	v_mov_b32_e32 v54, 0
	v_dot2c_f32_bf16_e32 v54, v56, v4
	v_dot2c_f32_bf16_e32 v62, v58, v10
	s_add_i32 s12, s28, -8
	v_dot2c_f32_bf16_e32 v54, v60, v8
	v_cvt_scalef32_pk_bf16_fp4 v56, v93, 1.0
	v_cvt_scalef32_pk_bf16_fp4 v58, v93, 1.0 op_sel:[1,0,0]
	v_cvt_scalef32_pk_bf16_fp4 v60, v93, 1.0 op_sel:[0,1,0]
	v_cvt_scalef32_pk_bf16_fp4 v92, v93, 1.0 op_sel:[1,1,0]
	v_readlane_b32 s12, v46, s12
	v_dot2c_f32_bf16_e32 v62, v56, v14
	v_dot2c_f32_bf16_e32 v54, v58, v12
	s_lshr_b32 s12, s12, 7
	v_dot2c_f32_bf16_e32 v62, v60, v18
	v_dot2c_f32_bf16_e32 v54, v92, v16
	v_cvt_scalef32_pk_bf16_fp4 v56, v94, 1.0
	v_cvt_scalef32_pk_bf16_fp4 v58, v94, 1.0 op_sel:[1,0,0]
	v_cvt_scalef32_pk_bf16_fp4 v60, v94, 1.0 op_sel:[0,1,0]
	v_cvt_scalef32_pk_bf16_fp4 v92, v94, 1.0 op_sel:[1,1,0]
	s_mov_b32 s13, s86
	v_dot2c_f32_bf16_e32 v62, v56, v22
	v_dot2c_f32_bf16_e32 v54, v58, v20
	s_lshl_b64 s[12:13], s[12:13], 10
	v_dot2c_f32_bf16_e32 v62, v60, v26
	v_dot2c_f32_bf16_e32 v54, v92, v24
	v_cvt_scalef32_pk_bf16_fp4 v56, v95, 1.0
	v_cvt_scalef32_pk_bf16_fp4 v58, v95, 1.0 op_sel:[1,0,0]
	v_cvt_scalef32_pk_bf16_fp4 v60, v95, 1.0 op_sel:[0,1,0]
	v_cvt_scalef32_pk_bf16_fp4 v92, v95, 1.0 op_sel:[1,1,0]
	s_nop 0
	v_dot2c_f32_bf16_e32 v62, v56, v30
	v_dot2c_f32_bf16_e32 v54, v58, v28
	s_nop 0
	v_dot2c_f32_bf16_e32 v62, v60, v36
	v_dot2c_f32_bf16_e32 v54, v92, v34
	s_nop 0
	s_nop 2
	v_add_f32_e32 v54, v62, v54
	v_lshl_add_u64 v[56:57], v[40:41], 0, s[12:13]
	global_load_dwordx4 v[92:95], v[56:57], off
	s_waitcnt vmcnt(15)
	v_cvt_scalef32_pk_bf16_fp4 v56, v96, 1.0
	v_cvt_scalef32_pk_bf16_fp4 v58, v96, 1.0 op_sel:[1,0,0]
	v_cvt_scalef32_pk_bf16_fp4 v60, v96, 1.0 op_sel:[0,1,0]
	v_cvt_scalef32_pk_bf16_fp4 v62, v96, 1.0 op_sel:[1,1,0]
	s_add_i32 s12, s28, -7
	v_dot2c_f32_bf16_e32 v100, v56, v6
	v_mov_b32_e32 v56, 0
	v_dot2c_f32_bf16_e32 v56, v58, v4
	v_dot2c_f32_bf16_e32 v100, v60, v10
	v_readlane_b32 s12, v46, s12
	v_dot2c_f32_bf16_e32 v56, v62, v8
	v_cvt_scalef32_pk_bf16_fp4 v58, v97, 1.0
	v_cvt_scalef32_pk_bf16_fp4 v60, v97, 1.0 op_sel:[1,0,0]
	v_cvt_scalef32_pk_bf16_fp4 v62, v97, 1.0 op_sel:[0,1,0]
	v_cvt_scalef32_pk_bf16_fp4 v96, v97, 1.0 op_sel:[1,1,0]
	s_lshr_b32 s12, s12, 7
	v_dot2c_f32_bf16_e32 v100, v58, v14
	v_dot2c_f32_bf16_e32 v56, v60, v12
	s_mov_b32 s13, s86
	v_dot2c_f32_bf16_e32 v100, v62, v18
	v_dot2c_f32_bf16_e32 v56, v96, v16
	v_cvt_scalef32_pk_bf16_fp4 v58, v98, 1.0
	v_cvt_scalef32_pk_bf16_fp4 v60, v98, 1.0 op_sel:[1,0,0]
	v_cvt_scalef32_pk_bf16_fp4 v62, v98, 1.0 op_sel:[0,1,0]
	v_cvt_scalef32_pk_bf16_fp4 v96, v98, 1.0 op_sel:[1,1,0]
	s_lshl_b64 s[12:13], s[12:13], 10
	v_dot2c_f32_bf16_e32 v100, v58, v22
	v_dot2c_f32_bf16_e32 v56, v60, v20
	s_nop 0
	v_dot2c_f32_bf16_e32 v100, v62, v26
	v_dot2c_f32_bf16_e32 v56, v96, v24
	v_cvt_scalef32_pk_bf16_fp4 v58, v99, 1.0
	v_cvt_scalef32_pk_bf16_fp4 v60, v99, 1.0 op_sel:[1,0,0]
	v_cvt_scalef32_pk_bf16_fp4 v62, v99, 1.0 op_sel:[0,1,0]
	v_cvt_scalef32_pk_bf16_fp4 v96, v99, 1.0 op_sel:[1,1,0]
	s_nop 0
	v_dot2c_f32_bf16_e32 v100, v58, v30
	v_dot2c_f32_bf16_e32 v56, v60, v28
	s_nop 0
	v_dot2c_f32_bf16_e32 v100, v62, v36
	v_dot2c_f32_bf16_e32 v56, v96, v34
	s_nop 0
	s_nop 2
	v_add_f32_e32 v55, v100, v56
	v_lshl_add_u64 v[56:57], v[40:41], 0, s[12:13]
	global_load_dwordx4 v[96:99], v[56:57], off
	s_waitcnt vmcnt(15)
; #define P4_FOR16(M) M(0) M(1) M(2) M(3) M(4) M(5) M(6) M(7) M(8) M(9) M(10) M(11) M(12) M(13) M(14) M(15)
; #define P4_U(i) { P4_DOT(b##i, part[i]); const int nk_ = __builtin_amdgcn_readlane(ksel, nb + i); P4_LOAD(b##i, Ug, nk_); }
; #define P4_U(i) { P4_DOT(b##i, part[i]); const int nk_ = __builtin_amdgcn_readlane(kn, i); P4_LOAD(b##i, nbase, nk_); }
; __device__ __forceinline__ void peer_gather_f4p(const float* X, const int* __restrict__ IDX, const float* __restrict__ G, ...
;     ...
; #pragma unroll 1
;         for (int bt = 0; bt < 7; ++bt) {
;             const int ksel = (bt + 1 < 4) ? k0 : k1;
;             const int nb = (16 * (bt + 1)) & 63;
;     ...
;             P4_FOR16(P4_U)
;     ...
;             P4_RED(bt);
;         }
	v_cvt_scalef32_pk_bf16_fp4 v56, v104, 1.0
	v_mov_b32_e32 v100, 0
	v_cvt_scalef32_pk_bf16_fp4 v58, v104, 1.0 op_sel:[1,0,0]
	v_cvt_scalef32_pk_bf16_fp4 v60, v104, 1.0 op_sel:[0,1,0]
	v_cvt_scalef32_pk_bf16_fp4 v62, v104, 1.0 op_sel:[1,1,0]
	v_dot2c_f32_bf16_e32 v100, v56, v6
	v_mov_b32_e32 v56, 0
	v_dot2c_f32_bf16_e32 v56, v58, v4
	v_dot2c_f32_bf16_e32 v100, v60, v10
	s_add_i32 s12, s28, -6
	v_dot2c_f32_bf16_e32 v56, v62, v8
	v_cvt_scalef32_pk_bf16_fp4 v58, v105, 1.0
	v_cvt_scalef32_pk_bf16_fp4 v60, v105, 1.0 op_sel:[1,0,0]
	v_cvt_scalef32_pk_bf16_fp4 v62, v105, 1.0 op_sel:[0,1,0]
	v_cvt_scalef32_pk_bf16_fp4 v102, v105, 1.0 op_sel:[1,1,0]
	v_readlane_b32 s12, v46, s12
	v_dot2c_f32_bf16_e32 v100, v58, v14
	v_dot2c_f32_bf16_e32 v56, v60, v12
	s_lshr_b32 s12, s12, 7
	v_dot2c_f32_bf16_e32 v100, v62, v18
	v_dot2c_f32_bf16_e32 v56, v102, v16
	v_cvt_scalef32_pk_bf16_fp4 v58, v106, 1.0
	v_cvt_scalef32_pk_bf16_fp4 v60, v106, 1.0 op_sel:[1,0,0]
	v_cvt_scalef32_pk_bf16_fp4 v62, v106, 1.0 op_sel:[0,1,0]
	v_cvt_scalef32_pk_bf16_fp4 v102, v106, 1.0 op_sel:[1,1,0]
	s_mov_b32 s13, s86
	v_dot2c_f32_bf16_e32 v100, v58, v22
	v_dot2c_f32_bf16_e32 v56, v60, v20
	s_lshl_b64 s[12:13], s[12:13], 10
	v_dot2c_f32_bf16_e32 v100, v62, v26
	v_dot2c_f32_bf16_e32 v56, v102, v24
	v_cvt_scalef32_pk_bf16_fp4 v58, v107, 1.0
	v_cvt_scalef32_pk_bf16_fp4 v60, v107, 1.0 op_sel:[1,0,0]
	v_cvt_scalef32_pk_bf16_fp4 v62, v107, 1.0 op_sel:[0,1,0]
	v_cvt_scalef32_pk_bf16_fp4 v102, v107, 1.0 op_sel:[1,1,0]
	s_nop 0
	v_dot2c_f32_bf16_e32 v100, v58, v30
	v_dot2c_f32_bf16_e32 v56, v60, v28
	s_nop 0
	v_dot2c_f32_bf16_e32 v100, v62, v36
	v_dot2c_f32_bf16_e32 v56, v102, v34
	v_mov_b32_e32 v102, 0
	s_nop 2
	v_add_f32_e32 v56, v100, v56
	v_lshl_add_u64 v[58:59], v[40:41], 0, s[12:13]
	global_load_dwordx4 v[104:107], v[58:59], off
	s_waitcnt vmcnt(15)
	v_cvt_scalef32_pk_bf16_fp4 v58, v108, 1.0
	v_cvt_scalef32_pk_bf16_fp4 v60, v108, 1.0 op_sel:[1,0,0]
	v_cvt_scalef32_pk_bf16_fp4 v62, v108, 1.0 op_sel:[0,1,0]
	v_cvt_scalef32_pk_bf16_fp4 v100, v108, 1.0 op_sel:[1,1,0]
	s_add_i32 s12, s28, -5
	v_dot2c_f32_bf16_e32 v102, v58, v6
	v_mov_b32_e32 v58, 0
	v_dot2c_f32_bf16_e32 v58, v60, v4
	v_dot2c_f32_bf16_e32 v102, v62, v10
	v_readlane_b32 s12, v46, s12
	v_dot2c_f32_bf16_e32 v58, v100, v8
	v_cvt_scalef32_pk_bf16_fp4 v60, v109, 1.0
	v_cvt_scalef32_pk_bf16_fp4 v62, v109, 1.0 op_sel:[1,0,0]
	v_cvt_scalef32_pk_bf16_fp4 v100, v109, 1.0 op_sel:[0,1,0]
	v_cvt_scalef32_pk_bf16_fp4 v108, v109, 1.0 op_sel:[1,1,0]
	s_lshr_b32 s12, s12, 7
	v_dot2c_f32_bf16_e32 v102, v60, v14
	v_dot2c_f32_bf16_e32 v58, v62, v12
	s_mov_b32 s13, s86
	v_dot2c_f32_bf16_e32 v102, v100, v18
	v_dot2c_f32_bf16_e32 v58, v108, v16
	v_cvt_scalef32_pk_bf16_fp4 v60, v110, 1.0
	v_cvt_scalef32_pk_bf16_fp4 v62, v110, 1.0 op_sel:[1,0,0]
	v_cvt_scalef32_pk_bf16_fp4 v100, v110, 1.0 op_sel:[0,1,0]
	v_cvt_scalef32_pk_bf16_fp4 v108, v110, 1.0 op_sel:[1,1,0]
	s_lshl_b64 s[12:13], s[12:13], 10
	v_dot2c_f32_bf16_e32 v102, v60, v22
	v_dot2c_f32_bf16_e32 v58, v62, v20
	s_nop 0
	v_dot2c_f32_bf16_e32 v102, v100, v26
	v_dot2c_f32_bf16_e32 v58, v108, v24
	v_cvt_scalef32_pk_bf16_fp4 v60, v111, 1.0
	v_cvt_scalef32_pk_bf16_fp4 v62, v111, 1.0 op_sel:[1,0,0]
	v_cvt_scalef32_pk_bf16_fp4 v100, v111, 1.0 op_sel:[0,1,0]
	v_cvt_scalef32_pk_bf16_fp4 v108, v111, 1.0 op_sel:[1,1,0]
	s_nop 0
	v_dot2c_f32_bf16_e32 v102, v60, v30
	v_dot2c_f32_bf16_e32 v58, v62, v28
	s_nop 0
	v_dot2c_f32_bf16_e32 v102, v100, v36
	v_dot2c_f32_bf16_e32 v58, v108, v34
	s_nop 0
	s_nop 2
	v_add_f32_e32 v57, v102, v58
	v_lshl_add_u64 v[58:59], v[40:41], 0, s[12:13]
	global_load_dwordx4 v[108:111], v[58:59], off
	s_waitcnt vmcnt(15)
	v_cvt_scalef32_pk_bf16_fp4 v58, v112, 1.0
	v_mov_b32_e32 v102, 0
	v_cvt_scalef32_pk_bf16_fp4 v60, v112, 1.0 op_sel:[1,0,0]
	v_cvt_scalef32_pk_bf16_fp4 v62, v112, 1.0 op_sel:[0,1,0]
	v_cvt_scalef32_pk_bf16_fp4 v100, v112, 1.0 op_sel:[1,1,0]
	v_dot2c_f32_bf16_e32 v102, v58, v6
	v_mov_b32_e32 v58, 0
	v_dot2c_f32_bf16_e32 v58, v60, v4
	v_dot2c_f32_bf16_e32 v102, v62, v10
	s_add_i32 s12, s28, -4
	v_dot2c_f32_bf16_e32 v58, v100, v8
	v_cvt_scalef32_pk_bf16_fp4 v60, v113, 1.0
	v_cvt_scalef32_pk_bf16_fp4 v62, v113, 1.0 op_sel:[1,0,0]
	v_cvt_scalef32_pk_bf16_fp4 v100, v113, 1.0 op_sel:[0,1,0]
	v_cvt_scalef32_pk_bf16_fp4 v112, v113, 1.0 op_sel:[1,1,0]
	v_readlane_b32 s12, v46, s12
	v_dot2c_f32_bf16_e32 v102, v60, v14
	v_dot2c_f32_bf16_e32 v58, v62, v12
	s_lshr_b32 s12, s12, 7
	v_dot2c_f32_bf16_e32 v102, v100, v18
	v_dot2c_f32_bf16_e32 v58, v112, v16
	v_cvt_scalef32_pk_bf16_fp4 v60, v114, 1.0
	v_cvt_scalef32_pk_bf16_fp4 v62, v114, 1.0 op_sel:[1,0,0]
	v_cvt_scalef32_pk_bf16_fp4 v100, v114, 1.0 op_sel:[0,1,0]
	v_cvt_scalef32_pk_bf16_fp4 v112, v114, 1.0 op_sel:[1,1,0]
	s_mov_b32 s13, s86
	v_dot2c_f32_bf16_e32 v102, v60, v22
	v_dot2c_f32_bf16_e32 v58, v62, v20
	s_lshl_b64 s[12:13], s[12:13], 10
	v_dot2c_f32_bf16_e32 v102, v100, v26
	v_dot2c_f32_bf16_e32 v58, v112, v24
	v_cvt_scalef32_pk_bf16_fp4 v60, v115, 1.0
	v_cvt_scalef32_pk_bf16_fp4 v62, v115, 1.0 op_sel:[1,0,0]
	v_cvt_scalef32_pk_bf16_fp4 v100, v115, 1.0 op_sel:[0,1,0]
	v_cvt_scalef32_pk_bf16_fp4 v112, v115, 1.0 op_sel:[1,1,0]
	s_nop 0
	v_dot2c_f32_bf16_e32 v102, v60, v30
	v_dot2c_f32_bf16_e32 v58, v62, v28
	s_nop 0
	v_dot2c_f32_bf16_e32 v102, v100, v36
	v_dot2c_f32_bf16_e32 v58, v112, v34
	s_nop 0
	s_nop 2
	v_add_f32_e32 v132, v102, v58
	v_lshl_add_u64 v[58:59], v[40:41], 0, s[12:13]
	global_load_dwordx4 v[112:115], v[58:59], off
	s_waitcnt vmcnt(15)
; #define P4_FOR16(M) M(0) M(1) M(2) M(3) M(4) M(5) M(6) M(7) M(8) M(9) M(10) M(11) M(12) M(13) M(14) M(15)
; #define P4_U(i) { P4_DOT(b##i, part[i]); const int nk_ = __builtin_amdgcn_readlane(ksel, nb + i); P4_LOAD(b##i, Ug, nk_); }
; #define P4_U(i) { P4_DOT(b##i, part[i]); const int nk_ = __builtin_amdgcn_readlane(kn, i); P4_LOAD(b##i, nbase, nk_); }
; __device__ __forceinline__ void peer_gather_f4p(const float* X, const int* __restrict__ IDX, const float* __restrict__ G, ...
;     ...
; #pragma unroll 1
;         for (int bt = 0; bt < 7; ++bt) {
;             const int ksel = (bt + 1 < 4) ? k0 : k1;
;             const int nb = (16 * (bt + 1)) & 63;
;     ...
;             P4_FOR16(P4_U)
;     ...
;             P4_RED(bt);
;         }
	v_cvt_scalef32_pk_bf16_fp4 v58, v116, 1.0
	v_mov_b32_e32 v102, 0
	v_cvt_scalef32_pk_bf16_fp4 v60, v116, 1.0 op_sel:[1,0,0]
	v_cvt_scalef32_pk_bf16_fp4 v62, v116, 1.0 op_sel:[0,1,0]
	v_cvt_scalef32_pk_bf16_fp4 v100, v116, 1.0 op_sel:[1,1,0]
	v_dot2c_f32_bf16_e32 v102, v58, v6
	v_mov_b32_e32 v58, 0
	v_dot2c_f32_bf16_e32 v58, v60, v4
	v_dot2c_f32_bf16_e32 v102, v62, v10
	s_add_i32 s12, s28, -3
	v_dot2c_f32_bf16_e32 v58, v100, v8
	v_cvt_scalef32_pk_bf16_fp4 v60, v117, 1.0
	v_cvt_scalef32_pk_bf16_fp4 v62, v117, 1.0 op_sel:[1,0,0]
	v_cvt_scalef32_pk_bf16_fp4 v100, v117, 1.0 op_sel:[0,1,0]
	v_cvt_scalef32_pk_bf16_fp4 v116, v117, 1.0 op_sel:[1,1,0]
	v_readlane_b32 s12, v46, s12
	v_dot2c_f32_bf16_e32 v102, v60, v14
	v_dot2c_f32_bf16_e32 v58, v62, v12
	s_lshr_b32 s12, s12, 7
	v_dot2c_f32_bf16_e32 v102, v100, v18
	v_dot2c_f32_bf16_e32 v58, v116, v16
	v_cvt_scalef32_pk_bf16_fp4 v60, v118, 1.0
	v_cvt_scalef32_pk_bf16_fp4 v62, v118, 1.0 op_sel:[1,0,0]
	v_cvt_scalef32_pk_bf16_fp4 v100, v118, 1.0 op_sel:[0,1,0]
	v_cvt_scalef32_pk_bf16_fp4 v116, v118, 1.0 op_sel:[1,1,0]
	s_mov_b32 s13, s86
	v_dot2c_f32_bf16_e32 v102, v60, v22
	v_dot2c_f32_bf16_e32 v58, v62, v20
	s_lshl_b64 s[12:13], s[12:13], 10
	v_dot2c_f32_bf16_e32 v102, v100, v26
	v_dot2c_f32_bf16_e32 v58, v116, v24
	v_cvt_scalef32_pk_bf16_fp4 v60, v119, 1.0
	v_cvt_scalef32_pk_bf16_fp4 v62, v119, 1.0 op_sel:[1,0,0]
	v_cvt_scalef32_pk_bf16_fp4 v100, v119, 1.0 op_sel:[0,1,0]
	v_cvt_scalef32_pk_bf16_fp4 v116, v119, 1.0 op_sel:[1,1,0]
	s_nop 0
	v_dot2c_f32_bf16_e32 v102, v60, v30
	v_dot2c_f32_bf16_e32 v58, v62, v28
	s_nop 0
	v_dot2c_f32_bf16_e32 v102, v100, v36
	v_dot2c_f32_bf16_e32 v58, v116, v34
	s_nop 0
	s_nop 2
	v_add_f32_e32 v133, v102, v58
	v_lshl_add_u64 v[58:59], v[40:41], 0, s[12:13]
	global_load_dwordx4 v[116:119], v[58:59], off
	s_waitcnt vmcnt(15)
	v_cvt_scalef32_pk_bf16_fp4 v58, v120, 1.0
	v_mov_b32_e32 v102, 0
	v_cvt_scalef32_pk_bf16_fp4 v60, v120, 1.0 op_sel:[1,0,0]
	v_cvt_scalef32_pk_bf16_fp4 v62, v120, 1.0 op_sel:[0,1,0]
	v_cvt_scalef32_pk_bf16_fp4 v100, v120, 1.0 op_sel:[1,1,0]
	v_dot2c_f32_bf16_e32 v102, v58, v6
	v_mov_b32_e32 v58, 0
	v_dot2c_f32_bf16_e32 v58, v60, v4
	v_dot2c_f32_bf16_e32 v102, v62, v10
	s_add_i32 s12, s28, -2
	v_dot2c_f32_bf16_e32 v58, v100, v8
	v_cvt_scalef32_pk_bf16_fp4 v60, v121, 1.0
	v_cvt_scalef32_pk_bf16_fp4 v62, v121, 1.0 op_sel:[1,0,0]
	v_cvt_scalef32_pk_bf16_fp4 v100, v121, 1.0 op_sel:[0,1,0]
	v_cvt_scalef32_pk_bf16_fp4 v120, v121, 1.0 op_sel:[1,1,0]
	v_readlane_b32 s12, v46, s12
	v_dot2c_f32_bf16_e32 v102, v60, v14
	v_dot2c_f32_bf16_e32 v58, v62, v12
	s_lshr_b32 s12, s12, 7
	v_dot2c_f32_bf16_e32 v102, v100, v18
	v_dot2c_f32_bf16_e32 v58, v120, v16
	v_cvt_scalef32_pk_bf16_fp4 v60, v122, 1.0
	v_cvt_scalef32_pk_bf16_fp4 v62, v122, 1.0 op_sel:[1,0,0]
	v_cvt_scalef32_pk_bf16_fp4 v100, v122, 1.0 op_sel:[0,1,0]
	v_cvt_scalef32_pk_bf16_fp4 v120, v122, 1.0 op_sel:[1,1,0]
	s_mov_b32 s13, s86
	v_dot2c_f32_bf16_e32 v102, v60, v22
	v_dot2c_f32_bf16_e32 v58, v62, v20
	s_lshl_b64 s[12:13], s[12:13], 10
	v_dot2c_f32_bf16_e32 v102, v100, v26
	v_dot2c_f32_bf16_e32 v58, v120, v24
	v_cvt_scalef32_pk_bf16_fp4 v60, v123, 1.0
	v_cvt_scalef32_pk_bf16_fp4 v62, v123, 1.0 op_sel:[1,0,0]
	v_cvt_scalef32_pk_bf16_fp4 v100, v123, 1.0 op_sel:[0,1,0]
	v_cvt_scalef32_pk_bf16_fp4 v120, v123, 1.0 op_sel:[1,1,0]
	s_nop 0
	v_dot2c_f32_bf16_e32 v102, v60, v30
	v_dot2c_f32_bf16_e32 v58, v62, v28
	s_nop 0
	v_dot2c_f32_bf16_e32 v102, v100, v36
	v_dot2c_f32_bf16_e32 v58, v120, v34
	s_nop 0
	s_nop 2
	v_add_f32_e32 v134, v102, v58
	v_lshl_add_u64 v[58:59], v[40:41], 0, s[12:13]
	global_load_dwordx4 v[120:123], v[58:59], off
	s_waitcnt vmcnt(15)
	v_cvt_scalef32_pk_bf16_fp4 v58, v124, 1.0
	v_mov_b32_e32 v102, 0
	v_cvt_scalef32_pk_bf16_fp4 v60, v124, 1.0 op_sel:[1,0,0]
	v_cvt_scalef32_pk_bf16_fp4 v62, v124, 1.0 op_sel:[0,1,0]
	v_cvt_scalef32_pk_bf16_fp4 v100, v124, 1.0 op_sel:[1,1,0]
	v_dot2c_f32_bf16_e32 v102, v58, v6
	v_mov_b32_e32 v58, 0
	v_dot2c_f32_bf16_e32 v58, v60, v4
	v_dot2c_f32_bf16_e32 v102, v62, v10
	s_add_i32 s12, s28, -1
	v_dot2c_f32_bf16_e32 v58, v100, v8
	v_cvt_scalef32_pk_bf16_fp4 v60, v125, 1.0
	v_cvt_scalef32_pk_bf16_fp4 v62, v125, 1.0 op_sel:[1,0,0]
	v_cvt_scalef32_pk_bf16_fp4 v100, v125, 1.0 op_sel:[0,1,0]
	v_cvt_scalef32_pk_bf16_fp4 v124, v125, 1.0 op_sel:[1,1,0]
	v_readlane_b32 s12, v46, s12
	v_dot2c_f32_bf16_e32 v102, v60, v14
	v_dot2c_f32_bf16_e32 v58, v62, v12
	s_lshr_b32 s12, s12, 7
	v_dot2c_f32_bf16_e32 v102, v100, v18
	v_dot2c_f32_bf16_e32 v58, v124, v16
	v_cvt_scalef32_pk_bf16_fp4 v60, v126, 1.0
	v_cvt_scalef32_pk_bf16_fp4 v62, v126, 1.0 op_sel:[1,0,0]
	v_cvt_scalef32_pk_bf16_fp4 v100, v126, 1.0 op_sel:[0,1,0]
	v_cvt_scalef32_pk_bf16_fp4 v124, v126, 1.0 op_sel:[1,1,0]
	s_mov_b32 s13, s86
	v_dot2c_f32_bf16_e32 v102, v60, v22
	v_dot2c_f32_bf16_e32 v58, v62, v20
	s_lshl_b64 s[12:13], s[12:13], 10
	v_dot2c_f32_bf16_e32 v102, v100, v26
	v_dot2c_f32_bf16_e32 v58, v124, v24
	v_cvt_scalef32_pk_bf16_fp4 v60, v127, 1.0
	v_cvt_scalef32_pk_bf16_fp4 v62, v127, 1.0 op_sel:[1,0,0]
	v_cvt_scalef32_pk_bf16_fp4 v100, v127, 1.0 op_sel:[0,1,0]
	v_cvt_scalef32_pk_bf16_fp4 v124, v127, 1.0 op_sel:[1,1,0]
	s_nop 0
	v_dot2c_f32_bf16_e32 v102, v60, v30
	v_dot2c_f32_bf16_e32 v58, v62, v28
	s_nop 0
	v_dot2c_f32_bf16_e32 v102, v100, v36
	v_dot2c_f32_bf16_e32 v58, v124, v34
	s_nop 0
	s_nop 2
	v_add_f32_e32 v135, v102, v58
	v_lshl_add_u64 v[58:59], v[40:41], 0, s[12:13]
	v_mov_b32_e32 v102, 0
	global_load_dwordx4 v[124:127], v[58:59], off
	s_waitcnt vmcnt(15)
	v_cvt_scalef32_pk_bf16_fp4 v58, v128, 1.0
	v_cvt_scalef32_pk_bf16_fp4 v60, v128, 1.0 op_sel:[1,0,0]
	v_cvt_scalef32_pk_bf16_fp4 v62, v128, 1.0 op_sel:[0,1,0]
	v_cvt_scalef32_pk_bf16_fp4 v100, v128, 1.0 op_sel:[1,1,0]
	v_readlane_b32 s12, v46, s28
	v_dot2c_f32_bf16_e32 v102, v58, v6
	v_dot2c_f32_bf16_e32 v42, v60, v4
	s_lshr_b32 s12, s12, 7
	v_dot2c_f32_bf16_e32 v102, v62, v10
	v_dot2c_f32_bf16_e32 v42, v100, v8
	v_cvt_scalef32_pk_bf16_fp4 v58, v129, 1.0
	v_cvt_scalef32_pk_bf16_fp4 v60, v129, 1.0 op_sel:[1,0,0]
	v_cvt_scalef32_pk_bf16_fp4 v62, v129, 1.0 op_sel:[0,1,0]
	v_cvt_scalef32_pk_bf16_fp4 v100, v129, 1.0 op_sel:[1,1,0]
	s_mov_b32 s13, s86
	v_dot2c_f32_bf16_e32 v102, v58, v14
	v_dot2c_f32_bf16_e32 v42, v60, v12
	s_lshl_b64 s[12:13], s[12:13], 10
	v_dot2c_f32_bf16_e32 v102, v62, v18
	v_dot2c_f32_bf16_e32 v42, v100, v16
	v_cvt_scalef32_pk_bf16_fp4 v58, v130, 1.0
	v_cvt_scalef32_pk_bf16_fp4 v60, v130, 1.0 op_sel:[1,0,0]
	v_cvt_scalef32_pk_bf16_fp4 v62, v130, 1.0 op_sel:[0,1,0]
	v_cvt_scalef32_pk_bf16_fp4 v100, v130, 1.0 op_sel:[1,1,0]
	v_cndmask_b32_e64 v46, v48, v56, s[48:49]
	v_dot2c_f32_bf16_e32 v102, v58, v22
	v_dot2c_f32_bf16_e32 v42, v60, v20
	ds_swizzle_b32 v46, v46 offset:swizzle(SWAP,8)
	v_dot2c_f32_bf16_e32 v102, v62, v26
	v_dot2c_f32_bf16_e32 v42, v100, v24
	v_cvt_scalef32_pk_bf16_fp4 v58, v131, 1.0
	v_cvt_scalef32_pk_bf16_fp4 v60, v131, 1.0 op_sel:[1,0,0]
	v_cvt_scalef32_pk_bf16_fp4 v62, v131, 1.0 op_sel:[0,1,0]
	v_cvt_scalef32_pk_bf16_fp4 v100, v131, 1.0 op_sel:[1,1,0]
	s_nop 0
	v_dot2c_f32_bf16_e32 v102, v58, v30
	v_dot2c_f32_bf16_e32 v42, v60, v28
	s_nop 0
	v_dot2c_f32_bf16_e32 v102, v62, v36
	v_dot2c_f32_bf16_e32 v42, v100, v34
	s_nop 0
	s_nop 2
	v_add_f32_e32 v58, v102, v42
	v_lshl_add_u64 v[42:43], v[40:41], 0, s[12:13]
	global_load_dwordx4 v[128:131], v[42:43], off
	v_cndmask_b32_e64 v43, v47, v55, s[48:49]
	ds_swizzle_b32 v43, v43 offset:swizzle(SWAP,8)
	v_cndmask_b32_e64 v42, v55, v47, s[48:49]
	v_cndmask_b32_e64 v47, v49, v57, s[48:49]
	ds_swizzle_b32 v47, v47 offset:swizzle(SWAP,8)
	s_waitcnt lgkmcnt(1)
	v_add_f32_e32 v42, v42, v43
	v_cndmask_b32_e64 v43, v56, v48, s[48:49]
	v_cndmask_b32_e64 v48, v50, v132, s[48:49]
	v_add_f32_e32 v43, v43, v46
	v_cndmask_b32_e64 v46, v57, v49, s[48:49]
	ds_swizzle_b32 v48, v48 offset:swizzle(SWAP,8)
	v_cndmask_b32_e64 v49, v51, v133, s[48:49]
	ds_swizzle_b32 v49, v49 offset:swizzle(SWAP,8)
	s_waitcnt lgkmcnt(2)
	v_add_f32_e32 v46, v46, v47
	v_cndmask_b32_e64 v47, v132, v50, s[48:49]
	v_cndmask_b32_e64 v50, v52, v134, s[48:49]
	ds_swizzle_b32 v50, v50 offset:swizzle(SWAP,8)
	s_waitcnt lgkmcnt(2)
	v_add_f32_e32 v47, v47, v48
	v_cndmask_b32_e64 v48, v133, v51, s[48:49]
	v_cndmask_b32_e64 v51, v53, v135, s[48:49]
	s_waitcnt lgkmcnt(1)
	v_add_f32_e32 v48, v48, v49
	v_cndmask_b32_e64 v49, v134, v52, s[48:49]
	ds_swizzle_b32 v51, v51 offset:swizzle(SWAP,8)
	v_cndmask_b32_e64 v52, v54, v58, s[48:49]
	ds_swizzle_b32 v52, v52 offset:swizzle(SWAP,8)
	s_waitcnt lgkmcnt(2)
	v_add_f32_e32 v49, v49, v50
	v_cndmask_b32_e64 v50, v135, v53, s[48:49]
	s_waitcnt lgkmcnt(1)
	v_add_f32_e32 v50, v50, v51
	v_cndmask_b32_e64 v51, v58, v54, s[48:49]
	s_waitcnt lgkmcnt(0)
	v_add_f32_e32 v51, v51, v52
	v_cndmask_b32_e64 v53, v42, v48, s[46:47]
	v_cndmask_b32_e64 v42, v48, v42, s[46:47]
	v_cndmask_b32_e64 v48, v49, v43, s[46:47]
	v_cndmask_b32_e64 v43, v43, v49, s[46:47]
	v_cndmask_b32_e64 v49, v46, v50, s[46:47]
	v_cndmask_b32_e64 v52, v47, v51, s[46:47]
	ds_swizzle_b32 v53, v53 offset:swizzle(SWAP,4)
	ds_swizzle_b32 v43, v43 offset:swizzle(SWAP,4)
	ds_swizzle_b32 v49, v49 offset:swizzle(SWAP,4)
	ds_swizzle_b32 v52, v52 offset:swizzle(SWAP,4)
	v_cndmask_b32_e64 v46, v50, v46, s[46:47]
	v_cndmask_b32_e64 v47, v51, v47, s[46:47]
	s_waitcnt lgkmcnt(3)
	v_add_f32_e32 v42, v42, v53
	s_waitcnt lgkmcnt(2)
	v_add_f32_e32 v43, v48, v43
	s_waitcnt lgkmcnt(1)
	v_add_f32_e32 v46, v46, v49
	s_waitcnt lgkmcnt(0)
	v_add_f32_e32 v47, v47, v52
	v_cndmask_b32_e64 v48, v42, v46, s[44:45]
	v_cndmask_b32_e64 v49, v43, v47, s[44:45]
	ds_swizzle_b32 v48, v48 offset:swizzle(SWAP,2)
	ds_swizzle_b32 v49, v49 offset:swizzle(SWAP,2)
	v_cndmask_b32_e64 v42, v46, v42, s[44:45]
	v_cndmask_b32_e64 v43, v47, v43, s[44:45]
	s_waitcnt lgkmcnt(1)
	v_add_f32_e32 v42, v42, v48
	s_waitcnt lgkmcnt(0)
	v_add_f32_e32 v43, v43, v49
	v_cndmask_b32_e64 v46, v42, v43, s[42:43]
	ds_swizzle_b32 v46, v46 offset:swizzle(SWAP,1)
	v_cndmask_b32_e64 v42, v43, v42, s[42:43]
	s_waitcnt lgkmcnt(0)
	v_add_f32_e32 v42, v42, v46
	ds_swizzle_b32 v43, v42 offset:swizzle(SWAP,16)
	s_waitcnt lgkmcnt(0)
	v_add_f32_e32 v46, v42, v43
	ds_read2st64_b32 v[42:43], v45 offset1:8
	v_mov_b32_e32 v47, v46
	s_nop 1
	v_permlane32_swap_b32_e32 v46, v47
	v_add_f32_e32 v46, v46, v47
	s_waitcnt lgkmcnt(0)
	v_mul_f32_e32 v42, v42, v46
	v_mul_f32_e32 v46, 0x3d372713, v42
	v_mul_f32_e32 v46, v42, v46
	v_fma_f32 v46, v42, v46, v42
	v_mul_f32_e32 v46, 0x3f4c422a, v46
	v_cmp_nlt_f32_e64 s[12:13], |v46|, s25
	s_and_saveexec_b64 s[40:41], s[12:13]
	s_xor_b64 s[12:13], exec, s[40:41]
	s_cbranch_execz .LBB0_536
	v_add_f32_e64 v47, |v46|, |v46|
	v_mul_f32_e32 v48, 0x3fb8aa3b, v47
	v_rndne_f32_e32 v49, v48
	v_sub_f32_e32 v50, v48, v49
	v_fma_f32 v48, v47, s70, -v48
	v_fmac_f32_e32 v48, 0x32a5705f, v47
	v_add_f32_e32 v48, v50, v48
	v_cvt_i32_f32_e32 v49, v49
	v_exp_f32_e32 v48, v48
	v_cmp_ngt_f32_e64 s[50:51], s67, v47
	v_ldexp_f32 v48, v48, v49
	s_nop 0
	v_cndmask_b32_e64 v48, 0, v48, s[50:51]
	v_cmp_nlt_f32_e64 s[50:51], s68, v47
	s_nop 1
	v_cndmask_b32_e64 v47, v205, v48, s[50:51]
	v_add_f32_e32 v47, 1.0, v47
	v_rcp_f32_e32 v47, v47
	s_nop 0
	v_fma_f32 v47, v47, -2.0, 1.0
	s_andn2_saveexec_b64 s[12:13], s[12:13]
	s_cbranch_execnz .LBB0_537

; #define P4_FOR16(M) M(0) M(1) M(2) M(3) M(4) M(5) M(6) M(7) M(8) M(9) M(10) M(11) M(12) M(13) M(14) M(15)
; #define P4_U(i) { P4_DOT(b##i, part[i]); const int nk_ = __builtin_amdgcn_readlane(ksel, nb + i); P4_LOAD(b##i, Ug, nk_); }
; #define P4_U(i) { P4_DOT(b##i, part[i]); const int nk_ = __builtin_amdgcn_readlane(kn, i); P4_LOAD(b##i, nbase, nk_); }
; __device__ __forceinline__ void peer_gather_f4p(const float* X, const int* __restrict__ IDX, const float* __restrict__ G, ...
;     ...
;         {
;     ...
;             P4_FOR16(P4_U)
;     ...
;             P4_RED(7);
;         }
.LBB0_539:
	s_mov_b32 s87, s86
	s_waitcnt vmcnt(15)
	v_cvt_scalef32_pk_bf16_fp4 v42, v64, 1.0
	v_mov_b32_e32 v50, 0
	v_or_b32_e32 v40, s27, v44
	v_cvt_scalef32_pk_bf16_fp4 v44, v64, 1.0 op_sel:[1,0,0]
	v_cvt_scalef32_pk_bf16_fp4 v46, v64, 1.0 op_sel:[0,1,0]
	v_cvt_scalef32_pk_bf16_fp4 v48, v64, 1.0 op_sel:[1,1,0]
	v_dot2c_f32_bf16_e32 v50, v42, v6
	v_mov_b32_e32 v42, 0
	v_dot2c_f32_bf16_e32 v42, v44, v4
	v_dot2c_f32_bf16_e32 v50, v46, v10
	s_cmp_eq_u32 s26, 3
	v_dot2c_f32_bf16_e32 v42, v48, v8
	v_cvt_scalef32_pk_bf16_fp4 v44, v65, 1.0
	v_cvt_scalef32_pk_bf16_fp4 v46, v65, 1.0 op_sel:[1,0,0]
	v_cvt_scalef32_pk_bf16_fp4 v48, v65, 1.0 op_sel:[0,1,0]
	v_cvt_scalef32_pk_bf16_fp4 v52, v65, 1.0 op_sel:[1,1,0]
	v_readlane_b32 s26, v2, 0
	v_dot2c_f32_bf16_e32 v50, v44, v14
	v_dot2c_f32_bf16_e32 v42, v46, v12
	s_cselect_b32 s12, s53, s55
	v_dot2c_f32_bf16_e32 v50, v48, v18
	v_dot2c_f32_bf16_e32 v42, v52, v16
	v_cvt_scalef32_pk_bf16_fp4 v44, v66, 1.0
	v_cvt_scalef32_pk_bf16_fp4 v46, v66, 1.0 op_sel:[1,0,0]
	v_cvt_scalef32_pk_bf16_fp4 v48, v66, 1.0 op_sel:[0,1,0]
	v_cvt_scalef32_pk_bf16_fp4 v52, v66, 1.0 op_sel:[1,1,0]
	s_cselect_b32 s13, s52, s54
	v_dot2c_f32_bf16_e32 v50, v44, v22
	v_dot2c_f32_bf16_e32 v42, v46, v20
	s_lshr_b32 s26, s26, 7
	v_dot2c_f32_bf16_e32 v50, v48, v26
	v_dot2c_f32_bf16_e32 v42, v52, v24
	s_mov_b32 s27, s86
	v_cvt_scalef32_pk_bf16_fp4 v44, v67, 1.0
	v_cvt_scalef32_pk_bf16_fp4 v46, v67, 1.0 op_sel:[1,0,0]
	v_cvt_scalef32_pk_bf16_fp4 v48, v67, 1.0 op_sel:[0,1,0]
	v_cvt_scalef32_pk_bf16_fp4 v52, v67, 1.0 op_sel:[1,1,0]
	s_lshl_b64 s[26:27], s[26:27], 10
	v_dot2c_f32_bf16_e32 v50, v44, v30
	v_dot2c_f32_bf16_e32 v42, v46, v28
	s_add_u32 s26, s13, s26
	v_dot2c_f32_bf16_e32 v50, v48, v36
	v_dot2c_f32_bf16_e32 v42, v52, v34
	s_addc_u32 s27, s12, s27
	s_nop 2
	v_add_f32_e32 v41, v50, v42
	v_lshl_add_u64 v[42:43], s[26:27], 0, v[32:33]
	global_load_dwordx4 v[64:67], v[42:43], off
	s_waitcnt vmcnt(15)
	v_cvt_scalef32_pk_bf16_fp4 v42, v68, 1.0
	v_mov_b32_e32 v50, 0
	v_cvt_scalef32_pk_bf16_fp4 v44, v68, 1.0 op_sel:[1,0,0]
	v_cvt_scalef32_pk_bf16_fp4 v46, v68, 1.0 op_sel:[0,1,0]
	v_cvt_scalef32_pk_bf16_fp4 v48, v68, 1.0 op_sel:[1,1,0]
	v_dot2c_f32_bf16_e32 v50, v42, v6
	v_mov_b32_e32 v42, 0
	v_dot2c_f32_bf16_e32 v42, v44, v4
	v_dot2c_f32_bf16_e32 v50, v46, v10
	v_readlane_b32 s26, v2, 1
	v_dot2c_f32_bf16_e32 v42, v48, v8
	v_cvt_scalef32_pk_bf16_fp4 v44, v69, 1.0
	v_cvt_scalef32_pk_bf16_fp4 v46, v69, 1.0 op_sel:[1,0,0]
	v_cvt_scalef32_pk_bf16_fp4 v48, v69, 1.0 op_sel:[0,1,0]
	v_cvt_scalef32_pk_bf16_fp4 v52, v69, 1.0 op_sel:[1,1,0]
	s_lshr_b32 s26, s26, 7
	v_dot2c_f32_bf16_e32 v50, v44, v14
	v_dot2c_f32_bf16_e32 v42, v46, v12
	s_mov_b32 s27, s86
	v_dot2c_f32_bf16_e32 v50, v48, v18
	v_dot2c_f32_bf16_e32 v42, v52, v16
	v_cvt_scalef32_pk_bf16_fp4 v44, v70, 1.0
	v_cvt_scalef32_pk_bf16_fp4 v46, v70, 1.0 op_sel:[1,0,0]
	v_cvt_scalef32_pk_bf16_fp4 v48, v70, 1.0 op_sel:[0,1,0]
	v_cvt_scalef32_pk_bf16_fp4 v52, v70, 1.0 op_sel:[1,1,0]
	s_lshl_b64 s[26:27], s[26:27], 10
	v_dot2c_f32_bf16_e32 v50, v44, v22
	v_dot2c_f32_bf16_e32 v42, v46, v20
	s_add_u32 s26, s13, s26
	v_dot2c_f32_bf16_e32 v50, v48, v26
	v_dot2c_f32_bf16_e32 v42, v52, v24
	v_cvt_scalef32_pk_bf16_fp4 v44, v71, 1.0
	v_cvt_scalef32_pk_bf16_fp4 v46, v71, 1.0 op_sel:[1,0,0]
	v_cvt_scalef32_pk_bf16_fp4 v48, v71, 1.0 op_sel:[0,1,0]
	v_cvt_scalef32_pk_bf16_fp4 v52, v71, 1.0 op_sel:[1,1,0]
	s_addc_u32 s27, s12, s27
	v_dot2c_f32_bf16_e32 v50, v44, v30
	v_dot2c_f32_bf16_e32 v42, v46, v28
	v_mov_b32_e32 v38, 0
	v_dot2c_f32_bf16_e32 v50, v48, v36
	v_dot2c_f32_bf16_e32 v42, v52, v34
	v_mov_b32_e32 v52, 0
	s_nop 2
	v_add_f32_e32 v42, v50, v42
	v_lshl_add_u64 v[44:45], s[26:27], 0, v[32:33]
	global_load_dwordx4 v[68:71], v[44:45], off
	s_waitcnt vmcnt(15)
	v_cvt_scalef32_pk_bf16_fp4 v44, v72, 1.0
	v_cvt_scalef32_pk_bf16_fp4 v46, v72, 1.0 op_sel:[1,0,0]
	v_cvt_scalef32_pk_bf16_fp4 v48, v72, 1.0 op_sel:[0,1,0]
	v_cvt_scalef32_pk_bf16_fp4 v50, v72, 1.0 op_sel:[1,1,0]
	v_readlane_b32 s26, v2, 2
	v_dot2c_f32_bf16_e32 v52, v44, v6
	v_mov_b32_e32 v44, 0
	v_dot2c_f32_bf16_e32 v44, v46, v4
	v_dot2c_f32_bf16_e32 v52, v48, v10
	s_lshr_b32 s26, s26, 7
	v_dot2c_f32_bf16_e32 v44, v50, v8
	v_cvt_scalef32_pk_bf16_fp4 v46, v73, 1.0
	v_cvt_scalef32_pk_bf16_fp4 v48, v73, 1.0 op_sel:[1,0,0]
	v_cvt_scalef32_pk_bf16_fp4 v50, v73, 1.0 op_sel:[0,1,0]
	v_cvt_scalef32_pk_bf16_fp4 v54, v73, 1.0 op_sel:[1,1,0]
	s_mov_b32 s27, s86
	v_dot2c_f32_bf16_e32 v52, v46, v14
	v_dot2c_f32_bf16_e32 v44, v48, v12
	s_lshl_b64 s[26:27], s[26:27], 10
	v_dot2c_f32_bf16_e32 v52, v50, v18
	v_dot2c_f32_bf16_e32 v44, v54, v16
	v_cvt_scalef32_pk_bf16_fp4 v46, v74, 1.0
	v_cvt_scalef32_pk_bf16_fp4 v48, v74, 1.0 op_sel:[1,0,0]
	v_cvt_scalef32_pk_bf16_fp4 v50, v74, 1.0 op_sel:[0,1,0]
	v_cvt_scalef32_pk_bf16_fp4 v54, v74, 1.0 op_sel:[1,1,0]
	s_add_u32 s26, s13, s26
	v_dot2c_f32_bf16_e32 v52, v46, v22
	v_dot2c_f32_bf16_e32 v44, v48, v20
	s_addc_u32 s27, s12, s27
	v_dot2c_f32_bf16_e32 v52, v50, v26
	v_dot2c_f32_bf16_e32 v44, v54, v24
	v_cvt_scalef32_pk_bf16_fp4 v46, v75, 1.0
	v_cvt_scalef32_pk_bf16_fp4 v48, v75, 1.0 op_sel:[1,0,0]
	v_cvt_scalef32_pk_bf16_fp4 v50, v75, 1.0 op_sel:[0,1,0]
	v_cvt_scalef32_pk_bf16_fp4 v54, v75, 1.0 op_sel:[1,1,0]
	s_nop 0
	v_dot2c_f32_bf16_e32 v52, v46, v30
	v_dot2c_f32_bf16_e32 v44, v48, v28
	s_nop 0
	v_dot2c_f32_bf16_e32 v52, v50, v36
	v_dot2c_f32_bf16_e32 v44, v54, v34
	s_nop 0
	s_nop 2
	v_add_f32_e32 v43, v52, v44
	v_lshl_add_u64 v[44:45], s[26:27], 0, v[32:33]
	global_load_dwordx4 v[72:75], v[44:45], off
	s_waitcnt vmcnt(15)
; #define P4_FOR16(M) M(0) M(1) M(2) M(3) M(4) M(5) M(6) M(7) M(8) M(9) M(10) M(11) M(12) M(13) M(14) M(15)
; #define P4_U(i) { P4_DOT(b##i, part[i]); const int nk_ = __builtin_amdgcn_readlane(ksel, nb + i); P4_LOAD(b##i, Ug, nk_); }
; #define P4_U(i) { P4_DOT(b##i, part[i]); const int nk_ = __builtin_amdgcn_readlane(kn, i); P4_LOAD(b##i, nbase, nk_); }
; __device__ __forceinline__ void peer_gather_f4p(const float* X, const int* __restrict__ IDX, const float* __restrict__ G, ...
;     ...
;         {
;     ...
;             P4_FOR16(P4_U)
;     ...
;             P4_RED(7);
;         }
	v_cvt_scalef32_pk_bf16_fp4 v44, v76, 1.0
	v_mov_b32_e32 v52, 0
	v_cvt_scalef32_pk_bf16_fp4 v46, v76, 1.0 op_sel:[1,0,0]
	v_cvt_scalef32_pk_bf16_fp4 v48, v76, 1.0 op_sel:[0,1,0]
	v_cvt_scalef32_pk_bf16_fp4 v50, v76, 1.0 op_sel:[1,1,0]
	v_dot2c_f32_bf16_e32 v52, v44, v6
	v_mov_b32_e32 v44, 0
	v_dot2c_f32_bf16_e32 v44, v46, v4
	v_dot2c_f32_bf16_e32 v52, v48, v10
	v_readlane_b32 s26, v2, 3
	v_dot2c_f32_bf16_e32 v44, v50, v8
	v_cvt_scalef32_pk_bf16_fp4 v46, v77, 1.0
	v_cvt_scalef32_pk_bf16_fp4 v48, v77, 1.0 op_sel:[1,0,0]
	v_cvt_scalef32_pk_bf16_fp4 v50, v77, 1.0 op_sel:[0,1,0]
	v_cvt_scalef32_pk_bf16_fp4 v54, v77, 1.0 op_sel:[1,1,0]
	s_lshr_b32 s26, s26, 7
	v_dot2c_f32_bf16_e32 v52, v46, v14
	v_dot2c_f32_bf16_e32 v44, v48, v12
	s_mov_b32 s27, s86
	v_dot2c_f32_bf16_e32 v52, v50, v18
	v_dot2c_f32_bf16_e32 v44, v54, v16
	v_cvt_scalef32_pk_bf16_fp4 v46, v78, 1.0
	v_cvt_scalef32_pk_bf16_fp4 v48, v78, 1.0 op_sel:[1,0,0]
	v_cvt_scalef32_pk_bf16_fp4 v50, v78, 1.0 op_sel:[0,1,0]
	v_cvt_scalef32_pk_bf16_fp4 v54, v78, 1.0 op_sel:[1,1,0]
	s_lshl_b64 s[26:27], s[26:27], 10
	v_dot2c_f32_bf16_e32 v52, v46, v22
	v_dot2c_f32_bf16_e32 v44, v48, v20
	s_add_u32 s26, s13, s26
	v_dot2c_f32_bf16_e32 v52, v50, v26
	v_dot2c_f32_bf16_e32 v44, v54, v24
	v_cvt_scalef32_pk_bf16_fp4 v46, v79, 1.0
	v_cvt_scalef32_pk_bf16_fp4 v48, v79, 1.0 op_sel:[1,0,0]
	v_cvt_scalef32_pk_bf16_fp4 v50, v79, 1.0 op_sel:[0,1,0]
	v_cvt_scalef32_pk_bf16_fp4 v54, v79, 1.0 op_sel:[1,1,0]
	s_addc_u32 s27, s12, s27
	v_dot2c_f32_bf16_e32 v52, v46, v30
	v_dot2c_f32_bf16_e32 v44, v48, v28
	s_nop 0
	v_dot2c_f32_bf16_e32 v52, v50, v36
	v_dot2c_f32_bf16_e32 v44, v54, v34
	v_mov_b32_e32 v54, 0
	s_nop 2
	v_add_f32_e32 v44, v52, v44
	v_lshl_add_u64 v[46:47], s[26:27], 0, v[32:33]
	global_load_dwordx4 v[76:79], v[46:47], off
	s_waitcnt vmcnt(15)
	v_cvt_scalef32_pk_bf16_fp4 v46, v80, 1.0
	v_cvt_scalef32_pk_bf16_fp4 v48, v80, 1.0 op_sel:[1,0,0]
	v_cvt_scalef32_pk_bf16_fp4 v50, v80, 1.0 op_sel:[0,1,0]
	v_cvt_scalef32_pk_bf16_fp4 v52, v80, 1.0 op_sel:[1,1,0]
	v_readlane_b32 s26, v2, 4
	v_dot2c_f32_bf16_e32 v54, v46, v6
	v_mov_b32_e32 v46, 0
	v_dot2c_f32_bf16_e32 v46, v48, v4
	v_dot2c_f32_bf16_e32 v54, v50, v10
	s_lshr_b32 s26, s26, 7
	v_dot2c_f32_bf16_e32 v46, v52, v8
	v_cvt_scalef32_pk_bf16_fp4 v48, v81, 1.0
	v_cvt_scalef32_pk_bf16_fp4 v50, v81, 1.0 op_sel:[1,0,0]
	v_cvt_scalef32_pk_bf16_fp4 v52, v81, 1.0 op_sel:[0,1,0]
	v_cvt_scalef32_pk_bf16_fp4 v56, v81, 1.0 op_sel:[1,1,0]
	s_mov_b32 s27, s86
	v_dot2c_f32_bf16_e32 v54, v48, v14
	v_dot2c_f32_bf16_e32 v46, v50, v12
	s_lshl_b64 s[26:27], s[26:27], 10
	v_dot2c_f32_bf16_e32 v54, v52, v18
	v_dot2c_f32_bf16_e32 v46, v56, v16
	v_cvt_scalef32_pk_bf16_fp4 v48, v82, 1.0
	v_cvt_scalef32_pk_bf16_fp4 v50, v82, 1.0 op_sel:[1,0,0]
	v_cvt_scalef32_pk_bf16_fp4 v52, v82, 1.0 op_sel:[0,1,0]
	v_cvt_scalef32_pk_bf16_fp4 v56, v82, 1.0 op_sel:[1,1,0]
	s_add_u32 s26, s13, s26
	v_dot2c_f32_bf16_e32 v54, v48, v22
	v_dot2c_f32_bf16_e32 v46, v50, v20
	s_addc_u32 s27, s12, s27
	v_dot2c_f32_bf16_e32 v54, v52, v26
	v_dot2c_f32_bf16_e32 v46, v56, v24
	v_cvt_scalef32_pk_bf16_fp4 v48, v83, 1.0
	v_cvt_scalef32_pk_bf16_fp4 v50, v83, 1.0 op_sel:[1,0,0]
	v_cvt_scalef32_pk_bf16_fp4 v52, v83, 1.0 op_sel:[0,1,0]
	v_cvt_scalef32_pk_bf16_fp4 v56, v83, 1.0 op_sel:[1,1,0]
	s_nop 0
	v_dot2c_f32_bf16_e32 v54, v48, v30
	v_dot2c_f32_bf16_e32 v46, v50, v28
	s_nop 0
	v_dot2c_f32_bf16_e32 v54, v52, v36
	v_dot2c_f32_bf16_e32 v46, v56, v34
	s_nop 0
	s_nop 2
	v_add_f32_e32 v45, v54, v46
	v_lshl_add_u64 v[46:47], s[26:27], 0, v[32:33]
	global_load_dwordx4 v[80:83], v[46:47], off
	s_waitcnt vmcnt(15)
	v_cvt_scalef32_pk_bf16_fp4 v46, v84, 1.0
	v_mov_b32_e32 v54, 0
	v_cvt_scalef32_pk_bf16_fp4 v48, v84, 1.0 op_sel:[1,0,0]
	v_cvt_scalef32_pk_bf16_fp4 v50, v84, 1.0 op_sel:[0,1,0]
	v_cvt_scalef32_pk_bf16_fp4 v52, v84, 1.0 op_sel:[1,1,0]
	v_dot2c_f32_bf16_e32 v54, v46, v6
	v_mov_b32_e32 v46, 0
	v_dot2c_f32_bf16_e32 v46, v48, v4
	v_dot2c_f32_bf16_e32 v54, v50, v10
	v_readlane_b32 s26, v2, 5
	v_dot2c_f32_bf16_e32 v46, v52, v8
	v_cvt_scalef32_pk_bf16_fp4 v48, v85, 1.0
	v_cvt_scalef32_pk_bf16_fp4 v50, v85, 1.0 op_sel:[1,0,0]
	v_cvt_scalef32_pk_bf16_fp4 v52, v85, 1.0 op_sel:[0,1,0]
	v_cvt_scalef32_pk_bf16_fp4 v56, v85, 1.0 op_sel:[1,1,0]
	s_lshr_b32 s26, s26, 7
	v_dot2c_f32_bf16_e32 v54, v48, v14
	v_dot2c_f32_bf16_e32 v46, v50, v12
	s_mov_b32 s27, s86
	v_dot2c_f32_bf16_e32 v54, v52, v18
	v_dot2c_f32_bf16_e32 v46, v56, v16
	v_cvt_scalef32_pk_bf16_fp4 v48, v86, 1.0
	v_cvt_scalef32_pk_bf16_fp4 v50, v86, 1.0 op_sel:[1,0,0]
	v_cvt_scalef32_pk_bf16_fp4 v52, v86, 1.0 op_sel:[0,1,0]
	v_cvt_scalef32_pk_bf16_fp4 v56, v86, 1.0 op_sel:[1,1,0]
	s_lshl_b64 s[26:27], s[26:27], 10
	v_dot2c_f32_bf16_e32 v54, v48, v22
	v_dot2c_f32_bf16_e32 v46, v50, v20
	s_add_u32 s26, s13, s26
	v_dot2c_f32_bf16_e32 v54, v52, v26
	v_dot2c_f32_bf16_e32 v46, v56, v24
	v_cvt_scalef32_pk_bf16_fp4 v48, v87, 1.0
	v_cvt_scalef32_pk_bf16_fp4 v50, v87, 1.0 op_sel:[1,0,0]
	v_cvt_scalef32_pk_bf16_fp4 v52, v87, 1.0 op_sel:[0,1,0]
	v_cvt_scalef32_pk_bf16_fp4 v56, v87, 1.0 op_sel:[1,1,0]
	s_addc_u32 s27, s12, s27
	v_dot2c_f32_bf16_e32 v54, v48, v30
	v_dot2c_f32_bf16_e32 v46, v50, v28
	s_nop 0
	v_dot2c_f32_bf16_e32 v54, v52, v36
	v_dot2c_f32_bf16_e32 v46, v56, v34
	v_mov_b32_e32 v56, 0
	s_nop 2
	v_add_f32_e32 v46, v54, v46
	v_lshl_add_u64 v[48:49], s[26:27], 0, v[32:33]
	global_load_dwordx4 v[84:87], v[48:49], off
	s_waitcnt vmcnt(15)
; #define P4_FOR16(M) M(0) M(1) M(2) M(3) M(4) M(5) M(6) M(7) M(8) M(9) M(10) M(11) M(12) M(13) M(14) M(15)
; #define P4_U(i) { P4_DOT(b##i, part[i]); const int nk_ = __builtin_amdgcn_readlane(ksel, nb + i); P4_LOAD(b##i, Ug, nk_); }
; #define P4_U(i) { P4_DOT(b##i, part[i]); const int nk_ = __builtin_amdgcn_readlane(kn, i); P4_LOAD(b##i, nbase, nk_); }
; __device__ __forceinline__ void peer_gather_f4p(const float* X, const int* __restrict__ IDX, const float* __restrict__ G, ...
;     ...
;         {
;     ...
;             P4_FOR16(P4_U)
;     ...
;             P4_RED(7);
;         }
	v_cvt_scalef32_pk_bf16_fp4 v48, v88, 1.0
	v_cvt_scalef32_pk_bf16_fp4 v50, v88, 1.0 op_sel:[1,0,0]
	v_cvt_scalef32_pk_bf16_fp4 v52, v88, 1.0 op_sel:[0,1,0]
	v_cvt_scalef32_pk_bf16_fp4 v54, v88, 1.0 op_sel:[1,1,0]
	v_readlane_b32 s26, v2, 6
	v_dot2c_f32_bf16_e32 v56, v48, v6
	v_mov_b32_e32 v48, 0
	v_dot2c_f32_bf16_e32 v48, v50, v4
	v_dot2c_f32_bf16_e32 v56, v52, v10
	s_lshr_b32 s26, s26, 7
	v_dot2c_f32_bf16_e32 v48, v54, v8
	v_cvt_scalef32_pk_bf16_fp4 v50, v89, 1.0
	v_cvt_scalef32_pk_bf16_fp4 v52, v89, 1.0 op_sel:[1,0,0]
	v_cvt_scalef32_pk_bf16_fp4 v54, v89, 1.0 op_sel:[0,1,0]
	v_cvt_scalef32_pk_bf16_fp4 v58, v89, 1.0 op_sel:[1,1,0]
	s_mov_b32 s27, s86
	v_dot2c_f32_bf16_e32 v56, v50, v14
	v_dot2c_f32_bf16_e32 v48, v52, v12
	s_lshl_b64 s[26:27], s[26:27], 10
	v_dot2c_f32_bf16_e32 v56, v54, v18
	v_dot2c_f32_bf16_e32 v48, v58, v16
	v_cvt_scalef32_pk_bf16_fp4 v50, v90, 1.0
	v_cvt_scalef32_pk_bf16_fp4 v52, v90, 1.0 op_sel:[1,0,0]
	v_cvt_scalef32_pk_bf16_fp4 v54, v90, 1.0 op_sel:[0,1,0]
	v_cvt_scalef32_pk_bf16_fp4 v58, v90, 1.0 op_sel:[1,1,0]
	s_add_u32 s26, s13, s26
	v_dot2c_f32_bf16_e32 v56, v50, v22
	v_dot2c_f32_bf16_e32 v48, v52, v20
	s_addc_u32 s27, s12, s27
	v_dot2c_f32_bf16_e32 v56, v54, v26
	v_dot2c_f32_bf16_e32 v48, v58, v24
	v_cvt_scalef32_pk_bf16_fp4 v50, v91, 1.0
	v_cvt_scalef32_pk_bf16_fp4 v52, v91, 1.0 op_sel:[1,0,0]
	v_cvt_scalef32_pk_bf16_fp4 v54, v91, 1.0 op_sel:[0,1,0]
	v_cvt_scalef32_pk_bf16_fp4 v58, v91, 1.0 op_sel:[1,1,0]
	s_nop 0
	v_dot2c_f32_bf16_e32 v56, v50, v30
	v_dot2c_f32_bf16_e32 v48, v52, v28
	s_nop 0
	v_dot2c_f32_bf16_e32 v56, v54, v36
	v_dot2c_f32_bf16_e32 v48, v58, v34
	s_nop 0
	s_nop 2
	v_add_f32_e32 v47, v56, v48
	v_lshl_add_u64 v[48:49], s[26:27], 0, v[32:33]
	global_load_dwordx4 v[88:91], v[48:49], off
	s_waitcnt vmcnt(15)
	v_cvt_scalef32_pk_bf16_fp4 v48, v92, 1.0
	v_mov_b32_e32 v56, 0
	v_cvt_scalef32_pk_bf16_fp4 v50, v92, 1.0 op_sel:[1,0,0]
	v_cvt_scalef32_pk_bf16_fp4 v52, v92, 1.0 op_sel:[0,1,0]
	v_cvt_scalef32_pk_bf16_fp4 v54, v92, 1.0 op_sel:[1,1,0]
	v_dot2c_f32_bf16_e32 v56, v48, v6
	v_mov_b32_e32 v48, 0
	v_dot2c_f32_bf16_e32 v48, v50, v4
	v_dot2c_f32_bf16_e32 v56, v52, v10
	v_readlane_b32 s26, v2, 7
	v_dot2c_f32_bf16_e32 v48, v54, v8
	v_cvt_scalef32_pk_bf16_fp4 v50, v93, 1.0
	v_cvt_scalef32_pk_bf16_fp4 v52, v93, 1.0 op_sel:[1,0,0]
	v_cvt_scalef32_pk_bf16_fp4 v54, v93, 1.0 op_sel:[0,1,0]
	v_cvt_scalef32_pk_bf16_fp4 v58, v93, 1.0 op_sel:[1,1,0]
	s_lshr_b32 s26, s26, 7
	v_dot2c_f32_bf16_e32 v56, v50, v14
	v_dot2c_f32_bf16_e32 v48, v52, v12
	s_mov_b32 s27, s86
	v_dot2c_f32_bf16_e32 v56, v54, v18
	v_dot2c_f32_bf16_e32 v48, v58, v16
	v_cvt_scalef32_pk_bf16_fp4 v50, v94, 1.0
	v_cvt_scalef32_pk_bf16_fp4 v52, v94, 1.0 op_sel:[1,0,0]
	v_cvt_scalef32_pk_bf16_fp4 v54, v94, 1.0 op_sel:[0,1,0]
	v_cvt_scalef32_pk_bf16_fp4 v58, v94, 1.0 op_sel:[1,1,0]
	s_lshl_b64 s[26:27], s[26:27], 10
	v_dot2c_f32_bf16_e32 v56, v50, v22
	v_dot2c_f32_bf16_e32 v48, v52, v20
	s_add_u32 s26, s13, s26
	v_dot2c_f32_bf16_e32 v56, v54, v26
	v_dot2c_f32_bf16_e32 v48, v58, v24
	v_cvt_scalef32_pk_bf16_fp4 v50, v95, 1.0
	v_cvt_scalef32_pk_bf16_fp4 v52, v95, 1.0 op_sel:[1,0,0]
	v_cvt_scalef32_pk_bf16_fp4 v54, v95, 1.0 op_sel:[0,1,0]
	v_cvt_scalef32_pk_bf16_fp4 v58, v95, 1.0 op_sel:[1,1,0]
	s_addc_u32 s27, s12, s27
	v_dot2c_f32_bf16_e32 v56, v50, v30
	v_dot2c_f32_bf16_e32 v48, v52, v28
	s_nop 0
	v_dot2c_f32_bf16_e32 v56, v54, v36
	v_dot2c_f32_bf16_e32 v48, v58, v34
	v_mov_b32_e32 v58, 0
	s_nop 2
	v_add_f32_e32 v48, v56, v48
	v_lshl_add_u64 v[50:51], s[26:27], 0, v[32:33]
	global_load_dwordx4 v[92:95], v[50:51], off
	s_waitcnt vmcnt(15)
	v_cvt_scalef32_pk_bf16_fp4 v50, v96, 1.0
	v_cvt_scalef32_pk_bf16_fp4 v52, v96, 1.0 op_sel:[1,0,0]
	v_cvt_scalef32_pk_bf16_fp4 v54, v96, 1.0 op_sel:[0,1,0]
	v_cvt_scalef32_pk_bf16_fp4 v56, v96, 1.0 op_sel:[1,1,0]
	v_readlane_b32 s26, v2, 8
	v_dot2c_f32_bf16_e32 v58, v50, v6
	v_mov_b32_e32 v50, 0
	v_dot2c_f32_bf16_e32 v50, v52, v4
	v_dot2c_f32_bf16_e32 v58, v54, v10
	s_lshr_b32 s26, s26, 7
	v_dot2c_f32_bf16_e32 v50, v56, v8
	v_cvt_scalef32_pk_bf16_fp4 v52, v97, 1.0
	v_cvt_scalef32_pk_bf16_fp4 v54, v97, 1.0 op_sel:[1,0,0]
	v_cvt_scalef32_pk_bf16_fp4 v56, v97, 1.0 op_sel:[0,1,0]
	v_cvt_scalef32_pk_bf16_fp4 v60, v97, 1.0 op_sel:[1,1,0]
	s_mov_b32 s27, s86
	v_dot2c_f32_bf16_e32 v58, v52, v14
	v_dot2c_f32_bf16_e32 v50, v54, v12
	s_lshl_b64 s[26:27], s[26:27], 10
	v_dot2c_f32_bf16_e32 v58, v56, v18
	v_dot2c_f32_bf16_e32 v50, v60, v16
	v_cvt_scalef32_pk_bf16_fp4 v52, v98, 1.0
	v_cvt_scalef32_pk_bf16_fp4 v54, v98, 1.0 op_sel:[1,0,0]
	v_cvt_scalef32_pk_bf16_fp4 v56, v98, 1.0 op_sel:[0,1,0]
	v_cvt_scalef32_pk_bf16_fp4 v60, v98, 1.0 op_sel:[1,1,0]
	s_add_u32 s26, s13, s26
	v_dot2c_f32_bf16_e32 v58, v52, v22
	v_dot2c_f32_bf16_e32 v50, v54, v20
	s_addc_u32 s27, s12, s27
	v_dot2c_f32_bf16_e32 v58, v56, v26
	v_dot2c_f32_bf16_e32 v50, v60, v24
	v_cvt_scalef32_pk_bf16_fp4 v52, v99, 1.0
	v_cvt_scalef32_pk_bf16_fp4 v54, v99, 1.0 op_sel:[1,0,0]
	v_cvt_scalef32_pk_bf16_fp4 v56, v99, 1.0 op_sel:[0,1,0]
	v_cvt_scalef32_pk_bf16_fp4 v60, v99, 1.0 op_sel:[1,1,0]
	s_nop 0
	v_dot2c_f32_bf16_e32 v58, v52, v30
	v_dot2c_f32_bf16_e32 v50, v54, v28
	s_nop 0
	v_dot2c_f32_bf16_e32 v58, v56, v36
	v_dot2c_f32_bf16_e32 v50, v60, v34
	s_nop 0
	s_nop 2
	v_add_f32_e32 v49, v58, v50
	v_lshl_add_u64 v[50:51], s[26:27], 0, v[32:33]
	global_load_dwordx4 v[96:99], v[50:51], off
	s_waitcnt vmcnt(15)
; #define P4_FOR16(M) M(0) M(1) M(2) M(3) M(4) M(5) M(6) M(7) M(8) M(9) M(10) M(11) M(12) M(13) M(14) M(15)
; #define P4_U(i) { P4_DOT(b##i, part[i]); const int nk_ = __builtin_amdgcn_readlane(ksel, nb + i); P4_LOAD(b##i, Ug, nk_); }
; #define P4_U(i) { P4_DOT(b##i, part[i]); const int nk_ = __builtin_amdgcn_readlane(kn, i); P4_LOAD(b##i, nbase, nk_); }
; __device__ __forceinline__ void peer_gather_f4p(const float* X, const int* __restrict__ IDX, const float* __restrict__ G, ...
;     ...
;         {
;     ...
;             P4_FOR16(P4_U)
;     ...
;             P4_RED(7);
;         }
	v_cvt_scalef32_pk_bf16_fp4 v50, v104, 1.0
	v_mov_b32_e32 v58, 0
	v_cvt_scalef32_pk_bf16_fp4 v52, v104, 1.0 op_sel:[1,0,0]
	v_cvt_scalef32_pk_bf16_fp4 v54, v104, 1.0 op_sel:[0,1,0]
	v_cvt_scalef32_pk_bf16_fp4 v56, v104, 1.0 op_sel:[1,1,0]
	v_dot2c_f32_bf16_e32 v58, v50, v6
	v_mov_b32_e32 v50, 0
	v_dot2c_f32_bf16_e32 v50, v52, v4
	v_dot2c_f32_bf16_e32 v58, v54, v10
	v_readlane_b32 s26, v2, 9
	v_dot2c_f32_bf16_e32 v50, v56, v8
	v_cvt_scalef32_pk_bf16_fp4 v52, v105, 1.0
	v_cvt_scalef32_pk_bf16_fp4 v54, v105, 1.0 op_sel:[1,0,0]
	v_cvt_scalef32_pk_bf16_fp4 v56, v105, 1.0 op_sel:[0,1,0]
	v_cvt_scalef32_pk_bf16_fp4 v60, v105, 1.0 op_sel:[1,1,0]
	s_lshr_b32 s26, s26, 7
	v_dot2c_f32_bf16_e32 v58, v52, v14
	v_dot2c_f32_bf16_e32 v50, v54, v12
	s_mov_b32 s27, s86
	v_dot2c_f32_bf16_e32 v58, v56, v18
	v_dot2c_f32_bf16_e32 v50, v60, v16
	v_cvt_scalef32_pk_bf16_fp4 v52, v106, 1.0
	v_cvt_scalef32_pk_bf16_fp4 v54, v106, 1.0 op_sel:[1,0,0]
	v_cvt_scalef32_pk_bf16_fp4 v56, v106, 1.0 op_sel:[0,1,0]
	v_cvt_scalef32_pk_bf16_fp4 v60, v106, 1.0 op_sel:[1,1,0]
	s_lshl_b64 s[26:27], s[26:27], 10
	v_dot2c_f32_bf16_e32 v58, v52, v22
	v_dot2c_f32_bf16_e32 v50, v54, v20
	s_add_u32 s26, s13, s26
	v_dot2c_f32_bf16_e32 v58, v56, v26
	v_dot2c_f32_bf16_e32 v50, v60, v24
	v_cvt_scalef32_pk_bf16_fp4 v52, v107, 1.0
	v_cvt_scalef32_pk_bf16_fp4 v54, v107, 1.0 op_sel:[1,0,0]
	v_cvt_scalef32_pk_bf16_fp4 v56, v107, 1.0 op_sel:[0,1,0]
	v_cvt_scalef32_pk_bf16_fp4 v60, v107, 1.0 op_sel:[1,1,0]
	s_addc_u32 s27, s12, s27
	v_dot2c_f32_bf16_e32 v58, v52, v30
	v_dot2c_f32_bf16_e32 v50, v54, v28
	s_nop 0
	v_dot2c_f32_bf16_e32 v58, v56, v36
	v_dot2c_f32_bf16_e32 v50, v60, v34
	v_mov_b32_e32 v60, 0
	s_nop 2
	v_add_f32_e32 v50, v58, v50
	v_lshl_add_u64 v[52:53], s[26:27], 0, v[32:33]
	global_load_dwordx4 v[104:107], v[52:53], off
	s_waitcnt vmcnt(15)
	v_cvt_scalef32_pk_bf16_fp4 v52, v108, 1.0
	v_cvt_scalef32_pk_bf16_fp4 v54, v108, 1.0 op_sel:[1,0,0]
	v_cvt_scalef32_pk_bf16_fp4 v56, v108, 1.0 op_sel:[0,1,0]
	v_cvt_scalef32_pk_bf16_fp4 v58, v108, 1.0 op_sel:[1,1,0]
	v_readlane_b32 s26, v2, 10
	v_dot2c_f32_bf16_e32 v60, v52, v6
	v_mov_b32_e32 v52, 0
	v_dot2c_f32_bf16_e32 v52, v54, v4
	v_dot2c_f32_bf16_e32 v60, v56, v10
	s_lshr_b32 s26, s26, 7
	v_dot2c_f32_bf16_e32 v52, v58, v8
	v_cvt_scalef32_pk_bf16_fp4 v54, v109, 1.0
	v_cvt_scalef32_pk_bf16_fp4 v56, v109, 1.0 op_sel:[1,0,0]
	v_cvt_scalef32_pk_bf16_fp4 v58, v109, 1.0 op_sel:[0,1,0]
	v_cvt_scalef32_pk_bf16_fp4 v62, v109, 1.0 op_sel:[1,1,0]
	s_mov_b32 s27, s86
	v_dot2c_f32_bf16_e32 v60, v54, v14
	v_dot2c_f32_bf16_e32 v52, v56, v12
	s_lshl_b64 s[26:27], s[26:27], 10
	v_dot2c_f32_bf16_e32 v60, v58, v18
	v_dot2c_f32_bf16_e32 v52, v62, v16
	v_cvt_scalef32_pk_bf16_fp4 v54, v110, 1.0
	v_cvt_scalef32_pk_bf16_fp4 v56, v110, 1.0 op_sel:[1,0,0]
	v_cvt_scalef32_pk_bf16_fp4 v58, v110, 1.0 op_sel:[0,1,0]
	v_cvt_scalef32_pk_bf16_fp4 v62, v110, 1.0 op_sel:[1,1,0]
	s_add_u32 s26, s13, s26
	v_dot2c_f32_bf16_e32 v60, v54, v22
	v_dot2c_f32_bf16_e32 v52, v56, v20
	s_addc_u32 s27, s12, s27
	v_dot2c_f32_bf16_e32 v60, v58, v26
	v_dot2c_f32_bf16_e32 v52, v62, v24
	v_cvt_scalef32_pk_bf16_fp4 v54, v111, 1.0
	v_cvt_scalef32_pk_bf16_fp4 v56, v111, 1.0 op_sel:[1,0,0]
	v_cvt_scalef32_pk_bf16_fp4 v58, v111, 1.0 op_sel:[0,1,0]
	v_cvt_scalef32_pk_bf16_fp4 v62, v111, 1.0 op_sel:[1,1,0]
	s_nop 0
	v_dot2c_f32_bf16_e32 v60, v54, v30
	v_dot2c_f32_bf16_e32 v52, v56, v28
	s_nop 0
	v_dot2c_f32_bf16_e32 v60, v58, v36
	v_dot2c_f32_bf16_e32 v52, v62, v34
	s_nop 0
	s_nop 2
	v_add_f32_e32 v51, v60, v52
	v_lshl_add_u64 v[52:53], s[26:27], 0, v[32:33]
	global_load_dwordx4 v[108:111], v[52:53], off
	s_waitcnt vmcnt(15)
	v_cvt_scalef32_pk_bf16_fp4 v52, v112, 1.0
	v_mov_b32_e32 v60, 0
	v_cvt_scalef32_pk_bf16_fp4 v54, v112, 1.0 op_sel:[1,0,0]
	v_cvt_scalef32_pk_bf16_fp4 v56, v112, 1.0 op_sel:[0,1,0]
	v_cvt_scalef32_pk_bf16_fp4 v58, v112, 1.0 op_sel:[1,1,0]
	v_dot2c_f32_bf16_e32 v60, v52, v6
	v_mov_b32_e32 v52, 0
	v_dot2c_f32_bf16_e32 v52, v54, v4
	v_dot2c_f32_bf16_e32 v60, v56, v10
	v_readlane_b32 s26, v2, 11
	v_dot2c_f32_bf16_e32 v52, v58, v8
	v_cvt_scalef32_pk_bf16_fp4 v54, v113, 1.0
	v_cvt_scalef32_pk_bf16_fp4 v56, v113, 1.0 op_sel:[1,0,0]
	v_cvt_scalef32_pk_bf16_fp4 v58, v113, 1.0 op_sel:[0,1,0]
	v_cvt_scalef32_pk_bf16_fp4 v62, v113, 1.0 op_sel:[1,1,0]
	s_lshr_b32 s26, s26, 7
	v_dot2c_f32_bf16_e32 v60, v54, v14
	v_dot2c_f32_bf16_e32 v52, v56, v12
	s_mov_b32 s27, s86
	v_dot2c_f32_bf16_e32 v60, v58, v18
	v_dot2c_f32_bf16_e32 v52, v62, v16
	v_cvt_scalef32_pk_bf16_fp4 v54, v114, 1.0
	v_cvt_scalef32_pk_bf16_fp4 v56, v114, 1.0 op_sel:[1,0,0]
	v_cvt_scalef32_pk_bf16_fp4 v58, v114, 1.0 op_sel:[0,1,0]
	v_cvt_scalef32_pk_bf16_fp4 v62, v114, 1.0 op_sel:[1,1,0]
	s_lshl_b64 s[26:27], s[26:27], 10
	v_dot2c_f32_bf16_e32 v60, v54, v22
	v_dot2c_f32_bf16_e32 v52, v56, v20
	s_add_u32 s26, s13, s26
	v_dot2c_f32_bf16_e32 v60, v58, v26
	v_dot2c_f32_bf16_e32 v52, v62, v24
	v_cvt_scalef32_pk_bf16_fp4 v54, v115, 1.0
	v_cvt_scalef32_pk_bf16_fp4 v56, v115, 1.0 op_sel:[1,0,0]
	v_cvt_scalef32_pk_bf16_fp4 v58, v115, 1.0 op_sel:[0,1,0]
	v_cvt_scalef32_pk_bf16_fp4 v62, v115, 1.0 op_sel:[1,1,0]
	s_addc_u32 s27, s12, s27
	v_dot2c_f32_bf16_e32 v60, v54, v30
	v_dot2c_f32_bf16_e32 v52, v56, v28
	s_nop 0
	v_dot2c_f32_bf16_e32 v60, v58, v36
	v_dot2c_f32_bf16_e32 v52, v62, v34
	s_nop 0
	s_nop 2
	v_add_f32_e32 v100, v60, v52
	v_lshl_add_u64 v[52:53], s[26:27], 0, v[32:33]
	global_load_dwordx4 v[112:115], v[52:53], off
	s_waitcnt vmcnt(15)
; #define P4_FOR16(M) M(0) M(1) M(2) M(3) M(4) M(5) M(6) M(7) M(8) M(9) M(10) M(11) M(12) M(13) M(14) M(15)
; #define P4_U(i) { P4_DOT(b##i, part[i]); const int nk_ = __builtin_amdgcn_readlane(ksel, nb + i); P4_LOAD(b##i, Ug, nk_); }
; #define P4_U(i) { P4_DOT(b##i, part[i]); const int nk_ = __builtin_amdgcn_readlane(kn, i); P4_LOAD(b##i, nbase, nk_); }
; __device__ __forceinline__ void peer_gather_f4p(const float* X, const int* __restrict__ IDX, const float* __restrict__ G, ...
;     ...
;         {
;     ...
;             P4_FOR16(P4_U)
;     ...
;             P4_RED(7);
;         }
	v_cvt_scalef32_pk_bf16_fp4 v52, v116, 1.0
	v_mov_b32_e32 v60, 0
	v_cvt_scalef32_pk_bf16_fp4 v54, v116, 1.0 op_sel:[1,0,0]
	v_cvt_scalef32_pk_bf16_fp4 v56, v116, 1.0 op_sel:[0,1,0]
	v_cvt_scalef32_pk_bf16_fp4 v58, v116, 1.0 op_sel:[1,1,0]
	v_dot2c_f32_bf16_e32 v60, v52, v6
	v_mov_b32_e32 v52, 0
	v_dot2c_f32_bf16_e32 v52, v54, v4
	v_dot2c_f32_bf16_e32 v60, v56, v10
	v_readlane_b32 s26, v2, 12
	v_dot2c_f32_bf16_e32 v52, v58, v8
	v_cvt_scalef32_pk_bf16_fp4 v54, v117, 1.0
	v_cvt_scalef32_pk_bf16_fp4 v56, v117, 1.0 op_sel:[1,0,0]
	v_cvt_scalef32_pk_bf16_fp4 v58, v117, 1.0 op_sel:[0,1,0]
	v_cvt_scalef32_pk_bf16_fp4 v62, v117, 1.0 op_sel:[1,1,0]
	s_lshr_b32 s26, s26, 7
	v_dot2c_f32_bf16_e32 v60, v54, v14
	v_dot2c_f32_bf16_e32 v52, v56, v12
	s_mov_b32 s27, s86
	v_dot2c_f32_bf16_e32 v60, v58, v18
	v_dot2c_f32_bf16_e32 v52, v62, v16
	v_cvt_scalef32_pk_bf16_fp4 v54, v118, 1.0
	v_cvt_scalef32_pk_bf16_fp4 v56, v118, 1.0 op_sel:[1,0,0]
	v_cvt_scalef32_pk_bf16_fp4 v58, v118, 1.0 op_sel:[0,1,0]
	v_cvt_scalef32_pk_bf16_fp4 v62, v118, 1.0 op_sel:[1,1,0]
	s_lshl_b64 s[26:27], s[26:27], 10
	v_dot2c_f32_bf16_e32 v60, v54, v22
	v_dot2c_f32_bf16_e32 v52, v56, v20
	s_add_u32 s26, s13, s26
	v_dot2c_f32_bf16_e32 v60, v58, v26
	v_dot2c_f32_bf16_e32 v52, v62, v24
	v_cvt_scalef32_pk_bf16_fp4 v54, v119, 1.0
	v_cvt_scalef32_pk_bf16_fp4 v56, v119, 1.0 op_sel:[1,0,0]
	v_cvt_scalef32_pk_bf16_fp4 v58, v119, 1.0 op_sel:[0,1,0]
	v_cvt_scalef32_pk_bf16_fp4 v62, v119, 1.0 op_sel:[1,1,0]
	s_addc_u32 s27, s12, s27
	v_dot2c_f32_bf16_e32 v60, v54, v30
	v_dot2c_f32_bf16_e32 v52, v56, v28
	s_nop 0
	v_dot2c_f32_bf16_e32 v60, v58, v36
	v_dot2c_f32_bf16_e32 v52, v62, v34
	s_nop 0
	s_nop 2
	v_add_f32_e32 v101, v60, v52
	v_lshl_add_u64 v[52:53], s[26:27], 0, v[32:33]
	global_load_dwordx4 v[116:119], v[52:53], off
	s_waitcnt vmcnt(15)
	v_cvt_scalef32_pk_bf16_fp4 v52, v120, 1.0
	v_mov_b32_e32 v60, 0
	v_cvt_scalef32_pk_bf16_fp4 v54, v120, 1.0 op_sel:[1,0,0]
	v_cvt_scalef32_pk_bf16_fp4 v56, v120, 1.0 op_sel:[0,1,0]
	v_cvt_scalef32_pk_bf16_fp4 v58, v120, 1.0 op_sel:[1,1,0]
	v_dot2c_f32_bf16_e32 v60, v52, v6
	v_mov_b32_e32 v52, 0
	v_dot2c_f32_bf16_e32 v52, v54, v4
	v_dot2c_f32_bf16_e32 v60, v56, v10
	v_readlane_b32 s26, v2, 13
	v_dot2c_f32_bf16_e32 v52, v58, v8
	v_cvt_scalef32_pk_bf16_fp4 v54, v121, 1.0
	v_cvt_scalef32_pk_bf16_fp4 v56, v121, 1.0 op_sel:[1,0,0]
	v_cvt_scalef32_pk_bf16_fp4 v58, v121, 1.0 op_sel:[0,1,0]
	v_cvt_scalef32_pk_bf16_fp4 v62, v121, 1.0 op_sel:[1,1,0]
	s_lshr_b32 s26, s26, 7
	v_dot2c_f32_bf16_e32 v60, v54, v14
	v_dot2c_f32_bf16_e32 v52, v56, v12
	s_mov_b32 s27, s86
	v_dot2c_f32_bf16_e32 v60, v58, v18
	v_dot2c_f32_bf16_e32 v52, v62, v16
	v_cvt_scalef32_pk_bf16_fp4 v54, v122, 1.0
	v_cvt_scalef32_pk_bf16_fp4 v56, v122, 1.0 op_sel:[1,0,0]
	v_cvt_scalef32_pk_bf16_fp4 v58, v122, 1.0 op_sel:[0,1,0]
	v_cvt_scalef32_pk_bf16_fp4 v62, v122, 1.0 op_sel:[1,1,0]
	s_lshl_b64 s[26:27], s[26:27], 10
	v_dot2c_f32_bf16_e32 v60, v54, v22
	v_dot2c_f32_bf16_e32 v52, v56, v20
	s_add_u32 s26, s13, s26
	v_dot2c_f32_bf16_e32 v60, v58, v26
	v_dot2c_f32_bf16_e32 v52, v62, v24
	v_cvt_scalef32_pk_bf16_fp4 v54, v123, 1.0
	v_cvt_scalef32_pk_bf16_fp4 v56, v123, 1.0 op_sel:[1,0,0]
	v_cvt_scalef32_pk_bf16_fp4 v58, v123, 1.0 op_sel:[0,1,0]
	v_cvt_scalef32_pk_bf16_fp4 v62, v123, 1.0 op_sel:[1,1,0]
	s_addc_u32 s27, s12, s27
	v_dot2c_f32_bf16_e32 v60, v54, v30
	v_dot2c_f32_bf16_e32 v52, v56, v28
	s_nop 0
	v_dot2c_f32_bf16_e32 v60, v58, v36
	v_dot2c_f32_bf16_e32 v52, v62, v34
	s_nop 0
	s_nop 2
	v_add_f32_e32 v102, v60, v52
	v_lshl_add_u64 v[52:53], s[26:27], 0, v[32:33]
	global_load_dwordx4 v[120:123], v[52:53], off
	s_waitcnt vmcnt(15)
	v_cvt_scalef32_pk_bf16_fp4 v52, v124, 1.0
	v_mov_b32_e32 v60, 0
	v_cvt_scalef32_pk_bf16_fp4 v54, v124, 1.0 op_sel:[1,0,0]
	v_cvt_scalef32_pk_bf16_fp4 v56, v124, 1.0 op_sel:[0,1,0]
	v_cvt_scalef32_pk_bf16_fp4 v58, v124, 1.0 op_sel:[1,1,0]
	v_dot2c_f32_bf16_e32 v60, v52, v6
	v_mov_b32_e32 v52, 0
	v_dot2c_f32_bf16_e32 v52, v54, v4
	v_dot2c_f32_bf16_e32 v60, v56, v10
	v_readlane_b32 s26, v2, 14
	v_dot2c_f32_bf16_e32 v52, v58, v8
	v_cvt_scalef32_pk_bf16_fp4 v54, v125, 1.0
	v_cvt_scalef32_pk_bf16_fp4 v56, v125, 1.0 op_sel:[1,0,0]
	v_cvt_scalef32_pk_bf16_fp4 v58, v125, 1.0 op_sel:[0,1,0]
	v_cvt_scalef32_pk_bf16_fp4 v62, v125, 1.0 op_sel:[1,1,0]
	s_lshr_b32 s26, s26, 7
	v_dot2c_f32_bf16_e32 v60, v54, v14
	v_dot2c_f32_bf16_e32 v52, v56, v12
	s_mov_b32 s27, s86
	v_dot2c_f32_bf16_e32 v60, v58, v18
	v_dot2c_f32_bf16_e32 v52, v62, v16
	v_cvt_scalef32_pk_bf16_fp4 v54, v126, 1.0
	v_cvt_scalef32_pk_bf16_fp4 v56, v126, 1.0 op_sel:[1,0,0]
	v_cvt_scalef32_pk_bf16_fp4 v58, v126, 1.0 op_sel:[0,1,0]
	v_cvt_scalef32_pk_bf16_fp4 v62, v126, 1.0 op_sel:[1,1,0]
	s_lshl_b64 s[26:27], s[26:27], 10
	v_dot2c_f32_bf16_e32 v60, v54, v22
	v_dot2c_f32_bf16_e32 v52, v56, v20
	s_add_u32 s26, s13, s26
	v_dot2c_f32_bf16_e32 v60, v58, v26
	v_dot2c_f32_bf16_e32 v52, v62, v24
	v_cvt_scalef32_pk_bf16_fp4 v54, v127, 1.0
	v_cvt_scalef32_pk_bf16_fp4 v56, v127, 1.0 op_sel:[1,0,0]
	v_cvt_scalef32_pk_bf16_fp4 v58, v127, 1.0 op_sel:[0,1,0]
	v_cvt_scalef32_pk_bf16_fp4 v62, v127, 1.0 op_sel:[1,1,0]
	s_addc_u32 s27, s12, s27
	v_dot2c_f32_bf16_e32 v60, v54, v30
	v_dot2c_f32_bf16_e32 v52, v56, v28
	s_nop 0
	v_dot2c_f32_bf16_e32 v60, v58, v36
	v_dot2c_f32_bf16_e32 v52, v62, v34
	s_nop 0
	s_nop 2
	v_add_f32_e32 v62, v60, v52
	v_lshl_add_u64 v[52:53], s[26:27], 0, v[32:33]
	v_mov_b32_e32 v60, 0
	global_load_dwordx4 v[124:127], v[52:53], off
	s_waitcnt vmcnt(15)
	v_cvt_scalef32_pk_bf16_fp4 v52, v128, 1.0
	v_cvt_scalef32_pk_bf16_fp4 v54, v128, 1.0 op_sel:[1,0,0]
	v_cvt_scalef32_pk_bf16_fp4 v56, v128, 1.0 op_sel:[0,1,0]
	v_cvt_scalef32_pk_bf16_fp4 v58, v128, 1.0 op_sel:[1,1,0]
	v_readlane_b32 s26, v2, 15
	v_dot2c_f32_bf16_e32 v60, v52, v6
	v_dot2c_f32_bf16_e32 v38, v54, v4
	s_lshr_b32 s26, s26, 7
	v_dot2c_f32_bf16_e32 v60, v56, v10
	v_dot2c_f32_bf16_e32 v38, v58, v8
	v_cvt_scalef32_pk_bf16_fp4 v4, v129, 1.0
	v_cvt_scalef32_pk_bf16_fp4 v6, v129, 1.0 op_sel:[1,0,0]
	v_cvt_scalef32_pk_bf16_fp4 v8, v129, 1.0 op_sel:[0,1,0]
	v_cvt_scalef32_pk_bf16_fp4 v10, v129, 1.0 op_sel:[1,1,0]
	s_mov_b32 s27, s86
	v_dot2c_f32_bf16_e32 v60, v4, v14
	v_dot2c_f32_bf16_e32 v38, v6, v12
	s_lshl_b64 s[26:27], s[26:27], 10
	v_dot2c_f32_bf16_e32 v60, v8, v18
	v_dot2c_f32_bf16_e32 v38, v10, v16
	v_cvt_scalef32_pk_bf16_fp4 v4, v130, 1.0
	v_cvt_scalef32_pk_bf16_fp4 v6, v130, 1.0 op_sel:[1,0,0]
	v_cvt_scalef32_pk_bf16_fp4 v8, v130, 1.0 op_sel:[0,1,0]
	v_cvt_scalef32_pk_bf16_fp4 v10, v130, 1.0 op_sel:[1,1,0]
	s_add_u32 s26, s13, s26
	v_dot2c_f32_bf16_e32 v60, v4, v22
	v_dot2c_f32_bf16_e32 v38, v6, v20
	s_addc_u32 s27, s12, s27
	v_dot2c_f32_bf16_e32 v60, v8, v26
	v_dot2c_f32_bf16_e32 v38, v10, v24
	v_cvt_scalef32_pk_bf16_fp4 v4, v131, 1.0
	v_cvt_scalef32_pk_bf16_fp4 v6, v131, 1.0 op_sel:[1,0,0]
	v_cvt_scalef32_pk_bf16_fp4 v8, v131, 1.0 op_sel:[0,1,0]
	v_cvt_scalef32_pk_bf16_fp4 v10, v131, 1.0 op_sel:[1,1,0]
	v_cndmask_b32_e64 v2, v49, v41, s[48:49]
	v_dot2c_f32_bf16_e32 v60, v4, v30
	v_dot2c_f32_bf16_e32 v38, v6, v28
	v_cndmask_b32_e64 v7, v43, v51, s[48:49]
	v_dot2c_f32_bf16_e32 v60, v8, v36
	v_dot2c_f32_bf16_e32 v38, v10, v34
	ds_swizzle_b32 v7, v7 offset:swizzle(SWAP,8)
	s_nop 2
	v_add_f32_e32 v6, v60, v38
	v_lshl_add_u64 v[4:5], s[26:27], 0, v[32:33]
	global_load_dwordx4 v[128:131], v[4:5], off
	v_cndmask_b32_e64 v4, v41, v49, s[48:49]
	ds_swizzle_b32 v4, v4 offset:swizzle(SWAP,8)
	v_cndmask_b32_e64 v5, v42, v50, s[48:49]
	ds_swizzle_b32 v5, v5 offset:swizzle(SWAP,8)
	v_cndmask_b32_e64 v8, v44, v100, s[48:49]
	ds_swizzle_b32 v8, v8 offset:swizzle(SWAP,8)
	v_cndmask_b32_e64 v9, v45, v101, s[48:49]
	ds_swizzle_b32 v9, v9 offset:swizzle(SWAP,8)
	v_cndmask_b32_e64 v10, v46, v102, s[48:49]
	s_waitcnt lgkmcnt(3)
	v_add_f32_e32 v2, v2, v4
	v_cndmask_b32_e64 v4, v50, v42, s[48:49]
	ds_swizzle_b32 v10, v10 offset:swizzle(SWAP,8)
	v_cndmask_b32_e64 v11, v47, v62, s[48:49]
	s_waitcnt lgkmcnt(3)
	v_add_f32_e32 v4, v4, v5
	v_cndmask_b32_e64 v5, v51, v43, s[48:49]
	ds_swizzle_b32 v11, v11 offset:swizzle(SWAP,8)
	v_add_f32_e32 v5, v5, v7
	v_cndmask_b32_e64 v7, v100, v44, s[48:49]
	s_waitcnt lgkmcnt(3)
	v_add_f32_e32 v7, v7, v8
	v_cndmask_b32_e64 v8, v101, v45, s[48:49]
	s_waitcnt lgkmcnt(2)
	v_add_f32_e32 v8, v8, v9
	v_cndmask_b32_e64 v9, v102, v46, s[48:49]
	s_waitcnt lgkmcnt(1)
	v_add_f32_e32 v9, v9, v10
	v_cndmask_b32_e64 v10, v62, v47, s[48:49]
	s_waitcnt lgkmcnt(0)
	v_add_f32_e32 v10, v10, v11
	v_cndmask_b32_e64 v11, v6, v48, s[48:49]
	v_cndmask_b32_e64 v6, v48, v6, s[48:49]
	ds_swizzle_b32 v6, v6 offset:swizzle(SWAP,8)
	s_waitcnt lgkmcnt(0)
	v_add_f32_e32 v6, v11, v6
	v_cndmask_b32_e64 v11, v8, v2, s[46:47]
	v_cndmask_b32_e64 v2, v2, v8, s[46:47]
	v_cndmask_b32_e64 v8, v9, v4, s[46:47]
	v_cndmask_b32_e64 v4, v4, v9, s[46:47]
	ds_swizzle_b32 v4, v4 offset:swizzle(SWAP,4)
	ds_swizzle_b32 v2, v2 offset:swizzle(SWAP,4)
	s_waitcnt lgkmcnt(1)
	v_add_f32_e32 v4, v8, v4
	v_cndmask_b32_e64 v8, v10, v5, s[46:47]
	v_cndmask_b32_e64 v5, v5, v10, s[46:47]
	ds_swizzle_b32 v5, v5 offset:swizzle(SWAP,4)
	s_waitcnt lgkmcnt(1)
	v_add_f32_e32 v2, v11, v2
	s_waitcnt lgkmcnt(0)
	v_add_f32_e32 v5, v8, v5
	v_cndmask_b32_e64 v8, v6, v7, s[46:47]
	v_cndmask_b32_e64 v6, v7, v6, s[46:47]
	ds_swizzle_b32 v6, v6 offset:swizzle(SWAP,4)
	v_cndmask_b32_e64 v7, v5, v2, s[44:45]
	v_cndmask_b32_e64 v2, v2, v5, s[44:45]
	ds_swizzle_b32 v2, v2 offset:swizzle(SWAP,2)
	s_waitcnt lgkmcnt(1)
	v_add_f32_e32 v6, v8, v6
	v_cndmask_b32_e64 v5, v6, v4, s[44:45]
	v_cndmask_b32_e64 v4, v4, v6, s[44:45]
	ds_swizzle_b32 v4, v4 offset:swizzle(SWAP,2)
	s_waitcnt lgkmcnt(1)
	v_add_f32_e32 v2, v7, v2
	s_waitcnt lgkmcnt(0)
	v_add_f32_e32 v4, v5, v4
	v_cndmask_b32_e64 v5, v4, v2, s[42:43]
	v_cndmask_b32_e64 v2, v2, v4, s[42:43]
	ds_swizzle_b32 v2, v2 offset:swizzle(SWAP,1)
	s_waitcnt lgkmcnt(0)
	v_add_f32_e32 v2, v5, v2
	ds_swizzle_b32 v4, v2 offset:swizzle(SWAP,16)
	s_waitcnt lgkmcnt(0)
	v_add_f32_e32 v2, v2, v4
	v_mov_b32_e32 v4, v2
	s_nop 1
	v_permlane32_swap_b32_e32 v2, v4
	v_add_f32_e32 v6, v2, v4
	v_lshl_add_u32 v2, v40, 2, s14
	v_add_u32_e32 v4, 0xc0, v2
	ds_read2st64_b32 v[4:5], v4 offset0:9 offset1:17
	s_waitcnt lgkmcnt(0)
	v_mul_f32_e32 v4, v4, v6
	v_mul_f32_e32 v6, 0x3d372713, v4
	v_mul_f32_e32 v6, v4, v6
	v_fma_f32 v6, v4, v6, v4
	v_mul_f32_e32 v6, 0x3f4c422a, v6
	v_cmp_nlt_f32_e64 s[12:13], |v6|, s25
	s_and_saveexec_b64 s[26:27], s[12:13]
	s_xor_b64 s[12:13], exec, s[26:27]
	s_cbranch_execz .LBB0_543
	v_add_f32_e64 v7, |v6|, |v6|
	v_mul_f32_e32 v8, 0x3fb8aa3b, v7
	v_rndne_f32_e32 v9, v8
	v_sub_f32_e32 v10, v8, v9
	v_fma_f32 v8, v7, s70, -v8
	v_fmac_f32_e32 v8, 0x32a5705f, v7
	v_add_f32_e32 v8, v10, v8
	v_cvt_i32_f32_e32 v9, v9
	v_exp_f32_e32 v8, v8
	v_cmp_ngt_f32_e64 s[42:43], s67, v7
	v_ldexp_f32 v8, v8, v9
	s_nop 0
	v_cndmask_b32_e64 v8, 0, v8, s[42:43]
	v_cmp_nlt_f32_e64 s[42:43], s68, v7
	s_nop 1
	v_cndmask_b32_e64 v7, v205, v8, s[42:43]
	v_add_f32_e32 v7, 1.0, v7
	v_rcp_f32_e32 v7, v7
	s_nop 0
	v_fma_f32 v7, v7, -2.0, 1.0
	s_andn2_saveexec_b64 s[12:13], s[12:13]
	s_cbranch_execnz .LBB0_544

; #define GAS __attribute__((address_space(1)))
; __device__ __forceinline__ void peer_gather_f4p(const float* X, const int* __restrict__ IDX, const float* __restrict__ G, ...
;     ...
;     for (int kt = 0; kt < 4; ++kt) {
;         const int row = blockIdx.x * 32 + wave * 4 + kt;
;         int lane = tid_ & 63; asm volatile("" : "+v"(lane));
;         f32x2 xr[16];
; #pragma unroll
;         for (int j = 0; j < 8; ++j) {
;             if (RES_BF16) {
;                 const u32x2 t2 = *(const GAS u32x2*)((const GAS bf16_t*)xbout + (size_t)row * D + 256 * j + lane * 4);
;                 xr[2 * j] = f32x2{__uint_as_float(t2[0] << 16), __uint_as_float(t2[0] & 0xffff0000u)}; xr[2 * j + 1] = f32x2{__uint_as_float(t2[1] << 16), __uint_as_float(t2[1] & 0xffff0000u)};
;             } else {
;                 const f32x4 t4 = *(const GAS f32x4*)((const GAS float*)X + (size_t)row * D + 256 * j + lane * 4);
;                 xr[2 * j] = f32x2{t4[0], t4[1]}; xr[2 * j + 1] = f32x2{t4[2], t4[3]};
;             }
;         }
;         const int k0 = keys[kt * 128 + lane], k1 = keys[kt * 128 + 64 + lane];
;         const int kn = keys[((kt + 1) & 3) * 128 + lane];
;         const GAS unsigned char* nbase = (kt < 3) ? Ug : Vg;
.LBB0_1228:
	s_add_i32 s12, s26, s56
	s_ashr_i32 s13, s12, 31
	v_mov_b32_e32 v42, v1
	s_lshl_b64 s[12:13], s[12:13], 12
	s_add_u32 s12, s15, s12
	v_lshlrev_b32_e32 v32, 2, v42
	s_addc_u32 s13, s18, s13
	v_ashrrev_i32_e32 v33, 31, v32
	v_lshl_add_u64 v[34:35], v[32:33], 1, s[12:13]
	global_load_dwordx2 v[4:5], v[34:35], off
	global_load_dwordx2 v[8:9], v[34:35], off offset:512
	global_load_dwordx2 v[12:13], v[34:35], off offset:1024
	global_load_dwordx2 v[16:17], v[34:35], off offset:1536
	global_load_dwordx2 v[20:21], v[34:35], off offset:2048
	global_load_dwordx2 v[24:25], v[34:35], off offset:2560
	global_load_dwordx2 v[28:29], v[34:35], off offset:3072
	s_lshl_b32 s12, s26, 9
	global_load_dwordx2 v[34:35], v[34:35], off offset:3584
	s_add_i32 s12, s14, s12
	s_add_i32 s19, s26, 1
	v_add_u32_e32 v2, s12, v32
	s_lshl_b32 s12, s19, 9
	s_and_b32 s12, s12, 0x600
	s_add_i32 s12, s14, s12
	ds_read2st64_b32 v[38:39], v2 offset1:1
	v_add_u32_e32 v2, s12, v32
	ds_read_b32 v2, v2
	v_and_b32_e32 v43, 8, v42
	v_cmp_eq_u32_e64 s[46:47], 0, v43
	v_and_b32_e32 v43, 4, v42
	v_lshlrev_b32_e32 v32, 4, v42
	v_cmp_eq_u32_e64 s[44:45], 0, v43
	v_and_b32_e32 v43, 2, v42
	v_and_b32_e32 v44, 15, v42
	v_ashrrev_i32_e32 v33, 31, v32
	v_cmp_eq_u32_e64 s[42:43], 0, v43
	v_and_b32_e32 v43, 1, v42
	v_cmp_gt_i32_e32 vcc, 16, v42
	v_add_u32_e32 v42, s17, v44
	s_lshl_b32 s27, s26, 7
	v_lshl_add_u64 v[40:41], s[50:51], 0, v[32:33]
	v_cmp_eq_u32_e64 s[40:41], 0, v43
	v_lshl_add_u32 v45, v42, 2, s16
	s_mov_b32 s28, 31
	s_mov_b32 s29, 0
	s_waitcnt vmcnt(7)
	v_mov_b32_e32 v6, v4
	v_mov_b32_e32 v4, v5
	s_waitcnt vmcnt(6)
	v_mov_b32_e32 v10, v8
	v_mov_b32_e32 v8, v9
	s_waitcnt vmcnt(5)
	v_mov_b32_e32 v14, v12
	v_mov_b32_e32 v12, v13
	s_waitcnt vmcnt(4)
	v_mov_b32_e32 v18, v16
	v_mov_b32_e32 v16, v17
	s_waitcnt vmcnt(3)
	v_mov_b32_e32 v22, v20
	v_mov_b32_e32 v20, v21
	s_waitcnt vmcnt(2)
	v_mov_b32_e32 v26, v24
	v_mov_b32_e32 v24, v25
	s_waitcnt vmcnt(1)
	v_mov_b32_e32 v30, v28
	v_mov_b32_e32 v28, v29
	s_waitcnt vmcnt(0)
	v_mov_b32_e32 v36, v34
	v_mov_b32_e32 v34, v35
	s_branch .LBB0_1230

; #define P4_FOR16(M) M(0) M(1) M(2) M(3) M(4) M(5) M(6) M(7) M(8) M(9) M(10) M(11) M(12) M(13) M(14) M(15)
; #define P4_U(i) { P4_DOT(b##i, part[i]); const int nk_ = __builtin_amdgcn_readlane(ksel, nb + i); P4_LOAD(b##i, Ug, nk_); }
; #define P4_U(i) { P4_DOT(b##i, part[i]); const int nk_ = __builtin_amdgcn_readlane(kn, i); P4_LOAD(b##i, nbase, nk_); }
; __device__ __forceinline__ void peer_gather_f4p(const float* X, const int* __restrict__ IDX, const float* __restrict__ G, ...
;     ...
;         for (int bt = 0; bt < 7; ++bt) {
;             const int ksel = (bt + 1 < 4) ? k0 : k1;
;             const int nb = (16 * (bt + 1)) & 63;
;     ...
;             P4_FOR16(P4_U)
.LBB0_1230:
	s_mov_b32 s87, s86
	s_waitcnt vmcnt(15)
	v_cvt_scalef32_pk_bf16_fp4 v48, v64, 1.0
	v_mov_b32_e32 v56, 0
	v_cvt_scalef32_pk_bf16_fp4 v50, v64, 1.0 op_sel:[1,0,0]
	v_cvt_scalef32_pk_bf16_fp4 v52, v64, 1.0 op_sel:[0,1,0]
	v_cvt_scalef32_pk_bf16_fp4 v54, v64, 1.0 op_sel:[1,1,0]
	v_dot2c_f32_bf16_e32 v56, v48, v6
	v_mov_b32_e32 v48, 0
	v_dot2c_f32_bf16_e32 v48, v50, v4
	v_dot2c_f32_bf16_e32 v56, v52, v10
	s_cmp_lt_u32 s29, 3
	v_dot2c_f32_bf16_e32 v48, v54, v8
	v_cvt_scalef32_pk_bf16_fp4 v50, v65, 1.0
	v_cvt_scalef32_pk_bf16_fp4 v52, v65, 1.0 op_sel:[1,0,0]
	v_cvt_scalef32_pk_bf16_fp4 v54, v65, 1.0 op_sel:[0,1,0]
	v_cvt_scalef32_pk_bf16_fp4 v58, v65, 1.0 op_sel:[1,1,0]
	s_cselect_b64 s[48:49], -1, 0
	v_dot2c_f32_bf16_e32 v56, v50, v14
	v_dot2c_f32_bf16_e32 v48, v52, v12
	s_waitcnt lgkmcnt(1)
	v_cndmask_b32_e64 v46, v39, v38, s[48:49]
	v_dot2c_f32_bf16_e32 v56, v54, v18
	v_dot2c_f32_bf16_e32 v48, v58, v16
	v_cvt_scalef32_pk_bf16_fp4 v50, v66, 1.0
	v_cvt_scalef32_pk_bf16_fp4 v52, v66, 1.0 op_sel:[1,0,0]
	v_cvt_scalef32_pk_bf16_fp4 v54, v66, 1.0 op_sel:[0,1,0]
	v_cvt_scalef32_pk_bf16_fp4 v58, v66, 1.0 op_sel:[1,1,0]
	s_add_i32 s12, s28, -15
	v_dot2c_f32_bf16_e32 v56, v50, v22
	v_dot2c_f32_bf16_e32 v48, v52, v20
	v_readlane_b32 s12, v46, s12
	v_dot2c_f32_bf16_e32 v56, v54, v26
	v_dot2c_f32_bf16_e32 v48, v58, v24
	v_cvt_scalef32_pk_bf16_fp4 v50, v67, 1.0
	v_cvt_scalef32_pk_bf16_fp4 v52, v67, 1.0 op_sel:[1,0,0]
	v_cvt_scalef32_pk_bf16_fp4 v54, v67, 1.0 op_sel:[0,1,0]
	v_cvt_scalef32_pk_bf16_fp4 v58, v67, 1.0 op_sel:[1,1,0]
	s_lshr_b32 s12, s12, 7
	v_dot2c_f32_bf16_e32 v56, v50, v30
	v_dot2c_f32_bf16_e32 v48, v52, v28
	s_mov_b32 s13, s86
	v_dot2c_f32_bf16_e32 v56, v54, v36
	v_dot2c_f32_bf16_e32 v48, v58, v34
	s_lshl_b64 s[12:13], s[12:13], 10
	s_nop 2
	v_add_f32_e32 v47, v56, v48
	v_lshl_add_u64 v[48:49], v[40:41], 0, s[12:13]
	global_load_dwordx4 v[64:67], v[48:49], off
	s_waitcnt vmcnt(15)
	v_cvt_scalef32_pk_bf16_fp4 v48, v68, 1.0
	v_mov_b32_e32 v56, 0
	v_cvt_scalef32_pk_bf16_fp4 v50, v68, 1.0 op_sel:[1,0,0]
	v_cvt_scalef32_pk_bf16_fp4 v52, v68, 1.0 op_sel:[0,1,0]
	v_cvt_scalef32_pk_bf16_fp4 v54, v68, 1.0 op_sel:[1,1,0]
	v_dot2c_f32_bf16_e32 v56, v48, v6
	v_mov_b32_e32 v48, 0
	v_dot2c_f32_bf16_e32 v48, v50, v4
	v_dot2c_f32_bf16_e32 v56, v52, v10
	s_add_i32 s12, s28, -14
	v_dot2c_f32_bf16_e32 v48, v54, v8
	v_cvt_scalef32_pk_bf16_fp4 v50, v69, 1.0
	v_cvt_scalef32_pk_bf16_fp4 v52, v69, 1.0 op_sel:[1,0,0]
	v_cvt_scalef32_pk_bf16_fp4 v54, v69, 1.0 op_sel:[0,1,0]
	v_cvt_scalef32_pk_bf16_fp4 v58, v69, 1.0 op_sel:[1,1,0]
	v_readlane_b32 s12, v46, s12
	v_dot2c_f32_bf16_e32 v56, v50, v14
	v_dot2c_f32_bf16_e32 v48, v52, v12
	s_lshr_b32 s12, s12, 7
	v_dot2c_f32_bf16_e32 v56, v54, v18
	v_dot2c_f32_bf16_e32 v48, v58, v16
	v_cvt_scalef32_pk_bf16_fp4 v50, v70, 1.0
	v_cvt_scalef32_pk_bf16_fp4 v52, v70, 1.0 op_sel:[1,0,0]
	v_cvt_scalef32_pk_bf16_fp4 v54, v70, 1.0 op_sel:[0,1,0]
	v_cvt_scalef32_pk_bf16_fp4 v58, v70, 1.0 op_sel:[1,1,0]
	s_mov_b32 s13, s86
	v_dot2c_f32_bf16_e32 v56, v50, v22
	v_dot2c_f32_bf16_e32 v48, v52, v20
	s_lshl_b64 s[12:13], s[12:13], 10
	v_dot2c_f32_bf16_e32 v56, v54, v26
	v_dot2c_f32_bf16_e32 v48, v58, v24
	v_cvt_scalef32_pk_bf16_fp4 v50, v71, 1.0
	v_cvt_scalef32_pk_bf16_fp4 v52, v71, 1.0 op_sel:[1,0,0]
	v_cvt_scalef32_pk_bf16_fp4 v54, v71, 1.0 op_sel:[0,1,0]
	v_cvt_scalef32_pk_bf16_fp4 v58, v71, 1.0 op_sel:[1,1,0]
	v_mov_b32_e32 v42, 0
	v_dot2c_f32_bf16_e32 v56, v50, v30
	v_dot2c_f32_bf16_e32 v48, v52, v28
	s_nop 0
	v_dot2c_f32_bf16_e32 v56, v54, v36
	v_dot2c_f32_bf16_e32 v48, v58, v34
	v_mov_b32_e32 v58, 0
	s_nop 2
	v_add_f32_e32 v48, v56, v48
	v_lshl_add_u64 v[50:51], v[40:41], 0, s[12:13]
	global_load_dwordx4 v[68:71], v[50:51], off
	s_waitcnt vmcnt(15)
	v_cvt_scalef32_pk_bf16_fp4 v50, v72, 1.0
	v_cvt_scalef32_pk_bf16_fp4 v52, v72, 1.0 op_sel:[1,0,0]
	v_cvt_scalef32_pk_bf16_fp4 v54, v72, 1.0 op_sel:[0,1,0]
	v_cvt_scalef32_pk_bf16_fp4 v56, v72, 1.0 op_sel:[1,1,0]
	s_add_i32 s12, s28, -13
	v_dot2c_f32_bf16_e32 v58, v50, v6
	v_mov_b32_e32 v50, 0
	v_dot2c_f32_bf16_e32 v50, v52, v4
	v_dot2c_f32_bf16_e32 v58, v54, v10
	v_readlane_b32 s12, v46, s12
	v_dot2c_f32_bf16_e32 v50, v56, v8
	v_cvt_scalef32_pk_bf16_fp4 v52, v73, 1.0
	v_cvt_scalef32_pk_bf16_fp4 v54, v73, 1.0 op_sel:[1,0,0]
	v_cvt_scalef32_pk_bf16_fp4 v56, v73, 1.0 op_sel:[0,1,0]
	v_cvt_scalef32_pk_bf16_fp4 v60, v73, 1.0 op_sel:[1,1,0]
	s_lshr_b32 s12, s12, 7
	v_dot2c_f32_bf16_e32 v58, v52, v14
	v_dot2c_f32_bf16_e32 v50, v54, v12
	s_mov_b32 s13, s86
	v_dot2c_f32_bf16_e32 v58, v56, v18
	v_dot2c_f32_bf16_e32 v50, v60, v16
	v_cvt_scalef32_pk_bf16_fp4 v52, v74, 1.0
	v_cvt_scalef32_pk_bf16_fp4 v54, v74, 1.0 op_sel:[1,0,0]
	v_cvt_scalef32_pk_bf16_fp4 v56, v74, 1.0 op_sel:[0,1,0]
	v_cvt_scalef32_pk_bf16_fp4 v60, v74, 1.0 op_sel:[1,1,0]
	s_lshl_b64 s[12:13], s[12:13], 10
	v_dot2c_f32_bf16_e32 v58, v52, v22
	v_dot2c_f32_bf16_e32 v50, v54, v20
	s_nop 0
	v_dot2c_f32_bf16_e32 v58, v56, v26
	v_dot2c_f32_bf16_e32 v50, v60, v24
	v_cvt_scalef32_pk_bf16_fp4 v52, v75, 1.0
	v_cvt_scalef32_pk_bf16_fp4 v54, v75, 1.0 op_sel:[1,0,0]
	v_cvt_scalef32_pk_bf16_fp4 v56, v75, 1.0 op_sel:[0,1,0]
	v_cvt_scalef32_pk_bf16_fp4 v60, v75, 1.0 op_sel:[1,1,0]
	s_nop 0
	v_dot2c_f32_bf16_e32 v58, v52, v30
	v_dot2c_f32_bf16_e32 v50, v54, v28
	s_nop 0
	v_dot2c_f32_bf16_e32 v58, v56, v36
	v_dot2c_f32_bf16_e32 v50, v60, v34
	s_nop 0
	s_nop 2
	v_add_f32_e32 v49, v58, v50
	v_lshl_add_u64 v[50:51], v[40:41], 0, s[12:13]
	global_load_dwordx4 v[72:75], v[50:51], off
	s_waitcnt vmcnt(15)
; #define P4_FOR16(M) M(0) M(1) M(2) M(3) M(4) M(5) M(6) M(7) M(8) M(9) M(10) M(11) M(12) M(13) M(14) M(15)
; #define P4_U(i) { P4_DOT(b##i, part[i]); const int nk_ = __builtin_amdgcn_readlane(ksel, nb + i); P4_LOAD(b##i, Ug, nk_); }
; #define P4_U(i) { P4_DOT(b##i, part[i]); const int nk_ = __builtin_amdgcn_readlane(kn, i); P4_LOAD(b##i, nbase, nk_); }
; __device__ __forceinline__ void peer_gather_f4p(const float* X, const int* __restrict__ IDX, const float* __restrict__ G, ...
;     ...
;         for (int bt = 0; bt < 7; ++bt) {
;             const int ksel = (bt + 1 < 4) ? k0 : k1;
;             const int nb = (16 * (bt + 1)) & 63;
;     ...
;             P4_FOR16(P4_U)
	v_cvt_scalef32_pk_bf16_fp4 v50, v76, 1.0
	v_mov_b32_e32 v58, 0
	v_cvt_scalef32_pk_bf16_fp4 v52, v76, 1.0 op_sel:[1,0,0]
	v_cvt_scalef32_pk_bf16_fp4 v54, v76, 1.0 op_sel:[0,1,0]
	v_cvt_scalef32_pk_bf16_fp4 v56, v76, 1.0 op_sel:[1,1,0]
	v_dot2c_f32_bf16_e32 v58, v50, v6
	v_mov_b32_e32 v50, 0
	v_dot2c_f32_bf16_e32 v50, v52, v4
	v_dot2c_f32_bf16_e32 v58, v54, v10
	s_add_i32 s12, s28, -12
	v_dot2c_f32_bf16_e32 v50, v56, v8
	v_cvt_scalef32_pk_bf16_fp4 v52, v77, 1.0
	v_cvt_scalef32_pk_bf16_fp4 v54, v77, 1.0 op_sel:[1,0,0]
	v_cvt_scalef32_pk_bf16_fp4 v56, v77, 1.0 op_sel:[0,1,0]
	v_cvt_scalef32_pk_bf16_fp4 v60, v77, 1.0 op_sel:[1,1,0]
	v_readlane_b32 s12, v46, s12
	v_dot2c_f32_bf16_e32 v58, v52, v14
	v_dot2c_f32_bf16_e32 v50, v54, v12
	s_lshr_b32 s12, s12, 7
	v_dot2c_f32_bf16_e32 v58, v56, v18
	v_dot2c_f32_bf16_e32 v50, v60, v16
	v_cvt_scalef32_pk_bf16_fp4 v52, v78, 1.0
	v_cvt_scalef32_pk_bf16_fp4 v54, v78, 1.0 op_sel:[1,0,0]
	v_cvt_scalef32_pk_bf16_fp4 v56, v78, 1.0 op_sel:[0,1,0]
	v_cvt_scalef32_pk_bf16_fp4 v60, v78, 1.0 op_sel:[1,1,0]
	s_mov_b32 s13, s86
	v_dot2c_f32_bf16_e32 v58, v52, v22
	v_dot2c_f32_bf16_e32 v50, v54, v20
	s_lshl_b64 s[12:13], s[12:13], 10
	v_dot2c_f32_bf16_e32 v58, v56, v26
	v_dot2c_f32_bf16_e32 v50, v60, v24
	v_cvt_scalef32_pk_bf16_fp4 v52, v79, 1.0
	v_cvt_scalef32_pk_bf16_fp4 v54, v79, 1.0 op_sel:[1,0,0]
	v_cvt_scalef32_pk_bf16_fp4 v56, v79, 1.0 op_sel:[0,1,0]
	v_cvt_scalef32_pk_bf16_fp4 v60, v79, 1.0 op_sel:[1,1,0]
	s_nop 0
	v_dot2c_f32_bf16_e32 v58, v52, v30
	v_dot2c_f32_bf16_e32 v50, v54, v28
	s_nop 0
	v_dot2c_f32_bf16_e32 v58, v56, v36
	v_dot2c_f32_bf16_e32 v50, v60, v34
	v_mov_b32_e32 v60, 0
	s_nop 2
	v_add_f32_e32 v50, v58, v50
	v_lshl_add_u64 v[52:53], v[40:41], 0, s[12:13]
	global_load_dwordx4 v[76:79], v[52:53], off
	s_waitcnt vmcnt(15)
	v_cvt_scalef32_pk_bf16_fp4 v52, v84, 1.0
	v_cvt_scalef32_pk_bf16_fp4 v54, v84, 1.0 op_sel:[1,0,0]
	v_cvt_scalef32_pk_bf16_fp4 v56, v84, 1.0 op_sel:[0,1,0]
	v_cvt_scalef32_pk_bf16_fp4 v58, v84, 1.0 op_sel:[1,1,0]
	s_add_i32 s12, s28, -11
	v_dot2c_f32_bf16_e32 v60, v52, v6
	v_mov_b32_e32 v52, 0
	v_dot2c_f32_bf16_e32 v52, v54, v4
	v_dot2c_f32_bf16_e32 v60, v56, v10
	v_readlane_b32 s12, v46, s12
	v_dot2c_f32_bf16_e32 v52, v58, v8
	v_cvt_scalef32_pk_bf16_fp4 v54, v85, 1.0
	v_cvt_scalef32_pk_bf16_fp4 v56, v85, 1.0 op_sel:[1,0,0]
	v_cvt_scalef32_pk_bf16_fp4 v58, v85, 1.0 op_sel:[0,1,0]
	v_cvt_scalef32_pk_bf16_fp4 v62, v85, 1.0 op_sel:[1,1,0]
	s_lshr_b32 s12, s12, 7
	v_dot2c_f32_bf16_e32 v60, v54, v14
	v_dot2c_f32_bf16_e32 v52, v56, v12
	s_mov_b32 s13, s86
	v_dot2c_f32_bf16_e32 v60, v58, v18
	v_dot2c_f32_bf16_e32 v52, v62, v16
	v_cvt_scalef32_pk_bf16_fp4 v54, v86, 1.0
	v_cvt_scalef32_pk_bf16_fp4 v56, v86, 1.0 op_sel:[1,0,0]
	v_cvt_scalef32_pk_bf16_fp4 v58, v86, 1.0 op_sel:[0,1,0]
	v_cvt_scalef32_pk_bf16_fp4 v62, v86, 1.0 op_sel:[1,1,0]
	s_lshl_b64 s[12:13], s[12:13], 10
	v_dot2c_f32_bf16_e32 v60, v54, v22
	v_dot2c_f32_bf16_e32 v52, v56, v20
	s_nop 0
	v_dot2c_f32_bf16_e32 v60, v58, v26
	v_dot2c_f32_bf16_e32 v52, v62, v24
	v_cvt_scalef32_pk_bf16_fp4 v54, v87, 1.0
	v_cvt_scalef32_pk_bf16_fp4 v56, v87, 1.0 op_sel:[1,0,0]
	v_cvt_scalef32_pk_bf16_fp4 v58, v87, 1.0 op_sel:[0,1,0]
	v_cvt_scalef32_pk_bf16_fp4 v62, v87, 1.0 op_sel:[1,1,0]
	s_nop 0
	v_dot2c_f32_bf16_e32 v60, v54, v30
	v_dot2c_f32_bf16_e32 v52, v56, v28
	s_nop 0
	v_dot2c_f32_bf16_e32 v60, v58, v36
	v_dot2c_f32_bf16_e32 v52, v62, v34
	s_nop 0
	s_nop 2
	v_add_f32_e32 v51, v60, v52
	v_lshl_add_u64 v[52:53], v[40:41], 0, s[12:13]
	global_load_dwordx4 v[84:87], v[52:53], off
	s_waitcnt vmcnt(15)
	v_cvt_scalef32_pk_bf16_fp4 v52, v88, 1.0
	v_mov_b32_e32 v60, 0
	v_cvt_scalef32_pk_bf16_fp4 v54, v88, 1.0 op_sel:[1,0,0]
	v_cvt_scalef32_pk_bf16_fp4 v56, v88, 1.0 op_sel:[0,1,0]
	v_cvt_scalef32_pk_bf16_fp4 v58, v88, 1.0 op_sel:[1,1,0]
	v_dot2c_f32_bf16_e32 v60, v52, v6
	v_mov_b32_e32 v52, 0
	v_dot2c_f32_bf16_e32 v52, v54, v4
	v_dot2c_f32_bf16_e32 v60, v56, v10
	s_add_i32 s12, s28, -10
	v_dot2c_f32_bf16_e32 v52, v58, v8
	v_cvt_scalef32_pk_bf16_fp4 v54, v89, 1.0
	v_cvt_scalef32_pk_bf16_fp4 v56, v89, 1.0 op_sel:[1,0,0]
	v_cvt_scalef32_pk_bf16_fp4 v58, v89, 1.0 op_sel:[0,1,0]
	v_cvt_scalef32_pk_bf16_fp4 v62, v89, 1.0 op_sel:[1,1,0]
	v_readlane_b32 s12, v46, s12
	v_dot2c_f32_bf16_e32 v60, v54, v14
	v_dot2c_f32_bf16_e32 v52, v56, v12
	s_lshr_b32 s12, s12, 7
	v_dot2c_f32_bf16_e32 v60, v58, v18
	v_dot2c_f32_bf16_e32 v52, v62, v16
	v_cvt_scalef32_pk_bf16_fp4 v54, v90, 1.0
	v_cvt_scalef32_pk_bf16_fp4 v56, v90, 1.0 op_sel:[1,0,0]
	v_cvt_scalef32_pk_bf16_fp4 v58, v90, 1.0 op_sel:[0,1,0]
	v_cvt_scalef32_pk_bf16_fp4 v62, v90, 1.0 op_sel:[1,1,0]
	s_mov_b32 s13, s86
	v_dot2c_f32_bf16_e32 v60, v54, v22
	v_dot2c_f32_bf16_e32 v52, v56, v20
	s_lshl_b64 s[12:13], s[12:13], 10
	v_dot2c_f32_bf16_e32 v60, v58, v26
	v_dot2c_f32_bf16_e32 v52, v62, v24
	v_cvt_scalef32_pk_bf16_fp4 v54, v91, 1.0
	v_cvt_scalef32_pk_bf16_fp4 v56, v91, 1.0 op_sel:[1,0,0]
	v_cvt_scalef32_pk_bf16_fp4 v58, v91, 1.0 op_sel:[0,1,0]
	v_cvt_scalef32_pk_bf16_fp4 v62, v91, 1.0 op_sel:[1,1,0]
	s_nop 0
	v_dot2c_f32_bf16_e32 v60, v54, v30
	v_dot2c_f32_bf16_e32 v52, v56, v28
	s_nop 0
	v_dot2c_f32_bf16_e32 v60, v58, v36
	v_dot2c_f32_bf16_e32 v52, v62, v34
	v_mov_b32_e32 v62, 0
	s_nop 2
	v_add_f32_e32 v52, v60, v52
	v_lshl_add_u64 v[54:55], v[40:41], 0, s[12:13]
	global_load_dwordx4 v[88:91], v[54:55], off
	s_waitcnt vmcnt(15)
; #define P4_FOR16(M) M(0) M(1) M(2) M(3) M(4) M(5) M(6) M(7) M(8) M(9) M(10) M(11) M(12) M(13) M(14) M(15)
; #define P4_U(i) { P4_DOT(b##i, part[i]); const int nk_ = __builtin_amdgcn_readlane(ksel, nb + i); P4_LOAD(b##i, Ug, nk_); }
; #define P4_U(i) { P4_DOT(b##i, part[i]); const int nk_ = __builtin_amdgcn_readlane(kn, i); P4_LOAD(b##i, nbase, nk_); }
; __device__ __forceinline__ void peer_gather_f4p(const float* X, const int* __restrict__ IDX, const float* __restrict__ G, ...
;     ...
;         for (int bt = 0; bt < 7; ++bt) {
;             const int ksel = (bt + 1 < 4) ? k0 : k1;
;             const int nb = (16 * (bt + 1)) & 63;
;     ...
;             P4_FOR16(P4_U)
	v_cvt_scalef32_pk_bf16_fp4 v54, v92, 1.0
	v_cvt_scalef32_pk_bf16_fp4 v56, v92, 1.0 op_sel:[1,0,0]
	v_cvt_scalef32_pk_bf16_fp4 v58, v92, 1.0 op_sel:[0,1,0]
	v_cvt_scalef32_pk_bf16_fp4 v60, v92, 1.0 op_sel:[1,1,0]
	s_add_i32 s12, s28, -9
	v_dot2c_f32_bf16_e32 v62, v54, v6
	v_mov_b32_e32 v54, 0
	v_dot2c_f32_bf16_e32 v54, v56, v4
	v_dot2c_f32_bf16_e32 v62, v58, v10
	v_readlane_b32 s12, v46, s12
	v_dot2c_f32_bf16_e32 v54, v60, v8
	v_cvt_scalef32_pk_bf16_fp4 v56, v93, 1.0
	v_cvt_scalef32_pk_bf16_fp4 v58, v93, 1.0 op_sel:[1,0,0]
	v_cvt_scalef32_pk_bf16_fp4 v60, v93, 1.0 op_sel:[0,1,0]
	v_cvt_scalef32_pk_bf16_fp4 v80, v93, 1.0 op_sel:[1,1,0]
	s_lshr_b32 s12, s12, 7
	v_dot2c_f32_bf16_e32 v62, v56, v14
	v_dot2c_f32_bf16_e32 v54, v58, v12
	s_mov_b32 s13, s86
	v_dot2c_f32_bf16_e32 v62, v60, v18
	v_dot2c_f32_bf16_e32 v54, v80, v16
	v_cvt_scalef32_pk_bf16_fp4 v56, v94, 1.0
	v_cvt_scalef32_pk_bf16_fp4 v58, v94, 1.0 op_sel:[1,0,0]
	v_cvt_scalef32_pk_bf16_fp4 v60, v94, 1.0 op_sel:[0,1,0]
	v_cvt_scalef32_pk_bf16_fp4 v80, v94, 1.0 op_sel:[1,1,0]
	s_lshl_b64 s[12:13], s[12:13], 10
	v_dot2c_f32_bf16_e32 v62, v56, v22
	v_dot2c_f32_bf16_e32 v54, v58, v20
	s_nop 0
	v_dot2c_f32_bf16_e32 v62, v60, v26
	v_dot2c_f32_bf16_e32 v54, v80, v24
	v_cvt_scalef32_pk_bf16_fp4 v56, v95, 1.0
	v_cvt_scalef32_pk_bf16_fp4 v58, v95, 1.0 op_sel:[1,0,0]
	v_cvt_scalef32_pk_bf16_fp4 v60, v95, 1.0 op_sel:[0,1,0]
	v_cvt_scalef32_pk_bf16_fp4 v80, v95, 1.0 op_sel:[1,1,0]
	s_nop 0
	v_dot2c_f32_bf16_e32 v62, v56, v30
	v_dot2c_f32_bf16_e32 v54, v58, v28
	s_nop 0
	v_dot2c_f32_bf16_e32 v62, v60, v36
	v_dot2c_f32_bf16_e32 v54, v80, v34
	s_nop 0
	s_nop 2
	v_add_f32_e32 v53, v62, v54
	v_lshl_add_u64 v[54:55], v[40:41], 0, s[12:13]
	global_load_dwordx4 v[92:95], v[54:55], off
	s_waitcnt vmcnt(15)
	v_cvt_scalef32_pk_bf16_fp4 v54, v96, 1.0
	v_mov_b32_e32 v62, 0
	v_cvt_scalef32_pk_bf16_fp4 v56, v96, 1.0 op_sel:[1,0,0]
	v_cvt_scalef32_pk_bf16_fp4 v58, v96, 1.0 op_sel:[0,1,0]
	v_cvt_scalef32_pk_bf16_fp4 v60, v96, 1.0 op_sel:[1,1,0]
	v_dot2c_f32_bf16_e32 v62, v54, v6
	v_mov_b32_e32 v54, 0
	v_dot2c_f32_bf16_e32 v54, v56, v4
	v_dot2c_f32_bf16_e32 v62, v58, v10
	s_add_i32 s12, s28, -8
	v_dot2c_f32_bf16_e32 v54, v60, v8
	v_cvt_scalef32_pk_bf16_fp4 v56, v97, 1.0
	v_cvt_scalef32_pk_bf16_fp4 v58, v97, 1.0 op_sel:[1,0,0]
	v_cvt_scalef32_pk_bf16_fp4 v60, v97, 1.0 op_sel:[0,1,0]
	v_cvt_scalef32_pk_bf16_fp4 v80, v97, 1.0 op_sel:[1,1,0]
	v_readlane_b32 s12, v46, s12
	v_dot2c_f32_bf16_e32 v62, v56, v14
	v_dot2c_f32_bf16_e32 v54, v58, v12
	s_lshr_b32 s12, s12, 7
	v_dot2c_f32_bf16_e32 v62, v60, v18
	v_dot2c_f32_bf16_e32 v54, v80, v16
	v_cvt_scalef32_pk_bf16_fp4 v56, v98, 1.0
	v_cvt_scalef32_pk_bf16_fp4 v58, v98, 1.0 op_sel:[1,0,0]
	v_cvt_scalef32_pk_bf16_fp4 v60, v98, 1.0 op_sel:[0,1,0]
	v_cvt_scalef32_pk_bf16_fp4 v80, v98, 1.0 op_sel:[1,1,0]
	s_mov_b32 s13, s86
	v_dot2c_f32_bf16_e32 v62, v56, v22
	v_dot2c_f32_bf16_e32 v54, v58, v20
	s_lshl_b64 s[12:13], s[12:13], 10
	v_dot2c_f32_bf16_e32 v62, v60, v26
	v_dot2c_f32_bf16_e32 v54, v80, v24
	v_cvt_scalef32_pk_bf16_fp4 v56, v99, 1.0
	v_cvt_scalef32_pk_bf16_fp4 v58, v99, 1.0 op_sel:[1,0,0]
	v_cvt_scalef32_pk_bf16_fp4 v60, v99, 1.0 op_sel:[0,1,0]
	v_cvt_scalef32_pk_bf16_fp4 v80, v99, 1.0 op_sel:[1,1,0]
	s_nop 0
	v_dot2c_f32_bf16_e32 v62, v56, v30
	v_dot2c_f32_bf16_e32 v54, v58, v28
	s_nop 0
	v_dot2c_f32_bf16_e32 v62, v60, v36
	v_dot2c_f32_bf16_e32 v54, v80, v34
	v_mov_b32_e32 v80, 0
	s_nop 2
	v_add_f32_e32 v54, v62, v54
	v_lshl_add_u64 v[56:57], v[40:41], 0, s[12:13]
	global_load_dwordx4 v[96:99], v[56:57], off
	s_waitcnt vmcnt(15)
	v_cvt_scalef32_pk_bf16_fp4 v56, v100, 1.0
	v_cvt_scalef32_pk_bf16_fp4 v58, v100, 1.0 op_sel:[1,0,0]
	v_cvt_scalef32_pk_bf16_fp4 v60, v100, 1.0 op_sel:[0,1,0]
	v_cvt_scalef32_pk_bf16_fp4 v62, v100, 1.0 op_sel:[1,1,0]
	s_add_i32 s12, s28, -7
	v_dot2c_f32_bf16_e32 v80, v56, v6
	v_mov_b32_e32 v56, 0
	v_dot2c_f32_bf16_e32 v56, v58, v4
	v_dot2c_f32_bf16_e32 v80, v60, v10
	v_readlane_b32 s12, v46, s12
	v_dot2c_f32_bf16_e32 v56, v62, v8
	v_cvt_scalef32_pk_bf16_fp4 v58, v101, 1.0
	v_cvt_scalef32_pk_bf16_fp4 v60, v101, 1.0 op_sel:[1,0,0]
	v_cvt_scalef32_pk_bf16_fp4 v62, v101, 1.0 op_sel:[0,1,0]
	v_cvt_scalef32_pk_bf16_fp4 v82, v101, 1.0 op_sel:[1,1,0]
	s_lshr_b32 s12, s12, 7
	v_dot2c_f32_bf16_e32 v80, v58, v14
	v_dot2c_f32_bf16_e32 v56, v60, v12
	s_mov_b32 s13, s86
	v_dot2c_f32_bf16_e32 v80, v62, v18
	v_dot2c_f32_bf16_e32 v56, v82, v16
	v_cvt_scalef32_pk_bf16_fp4 v58, v102, 1.0
	v_cvt_scalef32_pk_bf16_fp4 v60, v102, 1.0 op_sel:[1,0,0]
	v_cvt_scalef32_pk_bf16_fp4 v62, v102, 1.0 op_sel:[0,1,0]
	v_cvt_scalef32_pk_bf16_fp4 v82, v102, 1.0 op_sel:[1,1,0]
	s_lshl_b64 s[12:13], s[12:13], 10
	v_dot2c_f32_bf16_e32 v80, v58, v22
	v_dot2c_f32_bf16_e32 v56, v60, v20
	s_nop 0
	v_dot2c_f32_bf16_e32 v80, v62, v26
	v_dot2c_f32_bf16_e32 v56, v82, v24
	v_cvt_scalef32_pk_bf16_fp4 v58, v103, 1.0
	v_cvt_scalef32_pk_bf16_fp4 v60, v103, 1.0 op_sel:[1,0,0]
	v_cvt_scalef32_pk_bf16_fp4 v62, v103, 1.0 op_sel:[0,1,0]
	v_cvt_scalef32_pk_bf16_fp4 v82, v103, 1.0 op_sel:[1,1,0]
	s_nop 0
	v_dot2c_f32_bf16_e32 v80, v58, v30
	v_dot2c_f32_bf16_e32 v56, v60, v28
	s_nop 0
	v_dot2c_f32_bf16_e32 v80, v62, v36
	v_dot2c_f32_bf16_e32 v56, v82, v34
	s_nop 0
	s_nop 2
	v_add_f32_e32 v55, v80, v56
	v_lshl_add_u64 v[56:57], v[40:41], 0, s[12:13]
	global_load_dwordx4 v[100:103], v[56:57], off
	s_waitcnt vmcnt(15)
; #define P4_FOR16(M) M(0) M(1) M(2) M(3) M(4) M(5) M(6) M(7) M(8) M(9) M(10) M(11) M(12) M(13) M(14) M(15)
; #define P4_U(i) { P4_DOT(b##i, part[i]); const int nk_ = __builtin_amdgcn_readlane(ksel, nb + i); P4_LOAD(b##i, Ug, nk_); }
; #define P4_U(i) { P4_DOT(b##i, part[i]); const int nk_ = __builtin_amdgcn_readlane(kn, i); P4_LOAD(b##i, nbase, nk_); }
; __device__ __forceinline__ void peer_gather_f4p(const float* X, const int* __restrict__ IDX, const float* __restrict__ G, ...
;     ...
;         for (int bt = 0; bt < 7; ++bt) {
;             const int ksel = (bt + 1 < 4) ? k0 : k1;
;             const int nb = (16 * (bt + 1)) & 63;
;     ...
;             P4_FOR16(P4_U)
	v_cvt_scalef32_pk_bf16_fp4 v56, v104, 1.0
	v_mov_b32_e32 v80, 0
	v_cvt_scalef32_pk_bf16_fp4 v58, v104, 1.0 op_sel:[1,0,0]
	v_cvt_scalef32_pk_bf16_fp4 v60, v104, 1.0 op_sel:[0,1,0]
	v_cvt_scalef32_pk_bf16_fp4 v62, v104, 1.0 op_sel:[1,1,0]
	v_dot2c_f32_bf16_e32 v80, v56, v6
	v_mov_b32_e32 v56, 0
	v_dot2c_f32_bf16_e32 v56, v58, v4
	v_dot2c_f32_bf16_e32 v80, v60, v10
	s_add_i32 s12, s28, -6
	v_dot2c_f32_bf16_e32 v56, v62, v8
	v_cvt_scalef32_pk_bf16_fp4 v58, v105, 1.0
	v_cvt_scalef32_pk_bf16_fp4 v60, v105, 1.0 op_sel:[1,0,0]
	v_cvt_scalef32_pk_bf16_fp4 v62, v105, 1.0 op_sel:[0,1,0]
	v_cvt_scalef32_pk_bf16_fp4 v82, v105, 1.0 op_sel:[1,1,0]
	v_readlane_b32 s12, v46, s12
	v_dot2c_f32_bf16_e32 v80, v58, v14
	v_dot2c_f32_bf16_e32 v56, v60, v12
	s_lshr_b32 s12, s12, 7
	v_dot2c_f32_bf16_e32 v80, v62, v18
	v_dot2c_f32_bf16_e32 v56, v82, v16
	v_cvt_scalef32_pk_bf16_fp4 v58, v106, 1.0
	v_cvt_scalef32_pk_bf16_fp4 v60, v106, 1.0 op_sel:[1,0,0]
	v_cvt_scalef32_pk_bf16_fp4 v62, v106, 1.0 op_sel:[0,1,0]
	v_cvt_scalef32_pk_bf16_fp4 v82, v106, 1.0 op_sel:[1,1,0]
	s_mov_b32 s13, s86
	v_dot2c_f32_bf16_e32 v80, v58, v22
	v_dot2c_f32_bf16_e32 v56, v60, v20
	s_lshl_b64 s[12:13], s[12:13], 10
	v_dot2c_f32_bf16_e32 v80, v62, v26
	v_dot2c_f32_bf16_e32 v56, v82, v24
	v_cvt_scalef32_pk_bf16_fp4 v58, v107, 1.0
	v_cvt_scalef32_pk_bf16_fp4 v60, v107, 1.0 op_sel:[1,0,0]
	v_cvt_scalef32_pk_bf16_fp4 v62, v107, 1.0 op_sel:[0,1,0]
	v_cvt_scalef32_pk_bf16_fp4 v82, v107, 1.0 op_sel:[1,1,0]
	s_nop 0
	v_dot2c_f32_bf16_e32 v80, v58, v30
	v_dot2c_f32_bf16_e32 v56, v60, v28
	s_nop 0
	v_dot2c_f32_bf16_e32 v80, v62, v36
	v_dot2c_f32_bf16_e32 v56, v82, v34
	v_mov_b32_e32 v82, 0
	s_nop 2
	v_add_f32_e32 v56, v80, v56
	v_lshl_add_u64 v[58:59], v[40:41], 0, s[12:13]
	global_load_dwordx4 v[104:107], v[58:59], off
	s_waitcnt vmcnt(15)
	v_cvt_scalef32_pk_bf16_fp4 v58, v108, 1.0
	v_cvt_scalef32_pk_bf16_fp4 v60, v108, 1.0 op_sel:[1,0,0]
	v_cvt_scalef32_pk_bf16_fp4 v62, v108, 1.0 op_sel:[0,1,0]
	v_cvt_scalef32_pk_bf16_fp4 v80, v108, 1.0 op_sel:[1,1,0]
	s_add_i32 s12, s28, -5
	v_dot2c_f32_bf16_e32 v82, v58, v6
	v_mov_b32_e32 v58, 0
	v_dot2c_f32_bf16_e32 v58, v60, v4
	v_dot2c_f32_bf16_e32 v82, v62, v10
	v_readlane_b32 s12, v46, s12
	v_dot2c_f32_bf16_e32 v58, v80, v8
	v_cvt_scalef32_pk_bf16_fp4 v60, v109, 1.0
	v_cvt_scalef32_pk_bf16_fp4 v62, v109, 1.0 op_sel:[1,0,0]
	v_cvt_scalef32_pk_bf16_fp4 v80, v109, 1.0 op_sel:[0,1,0]
	v_cvt_scalef32_pk_bf16_fp4 v108, v109, 1.0 op_sel:[1,1,0]
	s_lshr_b32 s12, s12, 7
	v_dot2c_f32_bf16_e32 v82, v60, v14
	v_dot2c_f32_bf16_e32 v58, v62, v12
	s_mov_b32 s13, s86
	v_dot2c_f32_bf16_e32 v82, v80, v18
	v_dot2c_f32_bf16_e32 v58, v108, v16
	v_cvt_scalef32_pk_bf16_fp4 v60, v110, 1.0
	v_cvt_scalef32_pk_bf16_fp4 v62, v110, 1.0 op_sel:[1,0,0]
	v_cvt_scalef32_pk_bf16_fp4 v80, v110, 1.0 op_sel:[0,1,0]
	v_cvt_scalef32_pk_bf16_fp4 v108, v110, 1.0 op_sel:[1,1,0]
	s_lshl_b64 s[12:13], s[12:13], 10
	v_dot2c_f32_bf16_e32 v82, v60, v22
	v_dot2c_f32_bf16_e32 v58, v62, v20
	s_nop 0
	v_dot2c_f32_bf16_e32 v82, v80, v26
	v_dot2c_f32_bf16_e32 v58, v108, v24
	v_cvt_scalef32_pk_bf16_fp4 v60, v111, 1.0
	v_cvt_scalef32_pk_bf16_fp4 v62, v111, 1.0 op_sel:[1,0,0]
	v_cvt_scalef32_pk_bf16_fp4 v80, v111, 1.0 op_sel:[0,1,0]
	v_cvt_scalef32_pk_bf16_fp4 v108, v111, 1.0 op_sel:[1,1,0]
	s_nop 0
	v_dot2c_f32_bf16_e32 v82, v60, v30
	v_dot2c_f32_bf16_e32 v58, v62, v28
	s_nop 0
	v_dot2c_f32_bf16_e32 v82, v80, v36
	v_dot2c_f32_bf16_e32 v58, v108, v34
	s_nop 0
	s_nop 2
	v_add_f32_e32 v57, v82, v58
	v_lshl_add_u64 v[58:59], v[40:41], 0, s[12:13]
	global_load_dwordx4 v[108:111], v[58:59], off
	s_waitcnt vmcnt(15)
	v_cvt_scalef32_pk_bf16_fp4 v58, v112, 1.0
	v_mov_b32_e32 v82, 0
	v_cvt_scalef32_pk_bf16_fp4 v60, v112, 1.0 op_sel:[1,0,0]
	v_cvt_scalef32_pk_bf16_fp4 v62, v112, 1.0 op_sel:[0,1,0]
	v_cvt_scalef32_pk_bf16_fp4 v80, v112, 1.0 op_sel:[1,1,0]
	v_dot2c_f32_bf16_e32 v82, v58, v6
	v_mov_b32_e32 v58, 0
	v_dot2c_f32_bf16_e32 v58, v60, v4
	v_dot2c_f32_bf16_e32 v82, v62, v10
	s_add_i32 s12, s28, -4
	v_dot2c_f32_bf16_e32 v58, v80, v8
	v_cvt_scalef32_pk_bf16_fp4 v60, v113, 1.0
	v_cvt_scalef32_pk_bf16_fp4 v62, v113, 1.0 op_sel:[1,0,0]
	v_cvt_scalef32_pk_bf16_fp4 v80, v113, 1.0 op_sel:[0,1,0]
	v_cvt_scalef32_pk_bf16_fp4 v112, v113, 1.0 op_sel:[1,1,0]
	v_readlane_b32 s12, v46, s12
	v_dot2c_f32_bf16_e32 v82, v60, v14
	v_dot2c_f32_bf16_e32 v58, v62, v12
	s_lshr_b32 s12, s12, 7
	v_dot2c_f32_bf16_e32 v82, v80, v18
	v_dot2c_f32_bf16_e32 v58, v112, v16
	v_cvt_scalef32_pk_bf16_fp4 v60, v114, 1.0
	v_cvt_scalef32_pk_bf16_fp4 v62, v114, 1.0 op_sel:[1,0,0]
	v_cvt_scalef32_pk_bf16_fp4 v80, v114, 1.0 op_sel:[0,1,0]
	v_cvt_scalef32_pk_bf16_fp4 v112, v114, 1.0 op_sel:[1,1,0]
	s_mov_b32 s13, s86
	v_dot2c_f32_bf16_e32 v82, v60, v22
	v_dot2c_f32_bf16_e32 v58, v62, v20
	s_lshl_b64 s[12:13], s[12:13], 10
	v_dot2c_f32_bf16_e32 v82, v80, v26
	v_dot2c_f32_bf16_e32 v58, v112, v24
	v_cvt_scalef32_pk_bf16_fp4 v60, v115, 1.0
	v_cvt_scalef32_pk_bf16_fp4 v62, v115, 1.0 op_sel:[1,0,0]
	v_cvt_scalef32_pk_bf16_fp4 v80, v115, 1.0 op_sel:[0,1,0]
	v_cvt_scalef32_pk_bf16_fp4 v112, v115, 1.0 op_sel:[1,1,0]
	s_nop 0
	v_dot2c_f32_bf16_e32 v82, v60, v30
	v_dot2c_f32_bf16_e32 v58, v62, v28
	s_nop 0
	v_dot2c_f32_bf16_e32 v82, v80, v36
	v_dot2c_f32_bf16_e32 v58, v112, v34
	s_nop 0
	s_nop 2
	v_add_f32_e32 v132, v82, v58
	v_lshl_add_u64 v[58:59], v[40:41], 0, s[12:13]
	global_load_dwordx4 v[112:115], v[58:59], off
	s_waitcnt vmcnt(15)
; #define P4_FOR16(M) M(0) M(1) M(2) M(3) M(4) M(5) M(6) M(7) M(8) M(9) M(10) M(11) M(12) M(13) M(14) M(15)
; #define P4_U(i) { P4_DOT(b##i, part[i]); const int nk_ = __builtin_amdgcn_readlane(ksel, nb + i); P4_LOAD(b##i, Ug, nk_); }
; #define P4_U(i) { P4_DOT(b##i, part[i]); const int nk_ = __builtin_amdgcn_readlane(kn, i); P4_LOAD(b##i, nbase, nk_); }
; __device__ __forceinline__ void peer_gather_f4p(const float* X, const int* __restrict__ IDX, const float* __restrict__ G, ...
;     ...
;         for (int bt = 0; bt < 7; ++bt) {
;             const int ksel = (bt + 1 < 4) ? k0 : k1;
;             const int nb = (16 * (bt + 1)) & 63;
;     ...
;             P4_FOR16(P4_U)
	v_cvt_scalef32_pk_bf16_fp4 v58, v116, 1.0
	v_mov_b32_e32 v82, 0
	v_cvt_scalef32_pk_bf16_fp4 v60, v116, 1.0 op_sel:[1,0,0]
	v_cvt_scalef32_pk_bf16_fp4 v62, v116, 1.0 op_sel:[0,1,0]
	v_cvt_scalef32_pk_bf16_fp4 v80, v116, 1.0 op_sel:[1,1,0]
	v_dot2c_f32_bf16_e32 v82, v58, v6
	v_mov_b32_e32 v58, 0
	v_dot2c_f32_bf16_e32 v58, v60, v4
	v_dot2c_f32_bf16_e32 v82, v62, v10
	s_add_i32 s12, s28, -3
	v_dot2c_f32_bf16_e32 v58, v80, v8
	v_cvt_scalef32_pk_bf16_fp4 v60, v117, 1.0
	v_cvt_scalef32_pk_bf16_fp4 v62, v117, 1.0 op_sel:[1,0,0]
	v_cvt_scalef32_pk_bf16_fp4 v80, v117, 1.0 op_sel:[0,1,0]
	v_cvt_scalef32_pk_bf16_fp4 v116, v117, 1.0 op_sel:[1,1,0]
	v_readlane_b32 s12, v46, s12
	v_dot2c_f32_bf16_e32 v82, v60, v14
	v_dot2c_f32_bf16_e32 v58, v62, v12
	s_lshr_b32 s12, s12, 7
	v_dot2c_f32_bf16_e32 v82, v80, v18
	v_dot2c_f32_bf16_e32 v58, v116, v16
	v_cvt_scalef32_pk_bf16_fp4 v60, v118, 1.0
	v_cvt_scalef32_pk_bf16_fp4 v62, v118, 1.0 op_sel:[1,0,0]
	v_cvt_scalef32_pk_bf16_fp4 v80, v118, 1.0 op_sel:[0,1,0]
	v_cvt_scalef32_pk_bf16_fp4 v116, v118, 1.0 op_sel:[1,1,0]
	s_mov_b32 s13, s86
	v_dot2c_f32_bf16_e32 v82, v60, v22
	v_dot2c_f32_bf16_e32 v58, v62, v20
	s_lshl_b64 s[12:13], s[12:13], 10
	v_dot2c_f32_bf16_e32 v82, v80, v26
	v_dot2c_f32_bf16_e32 v58, v116, v24
	v_cvt_scalef32_pk_bf16_fp4 v60, v119, 1.0
	v_cvt_scalef32_pk_bf16_fp4 v62, v119, 1.0 op_sel:[1,0,0]
	v_cvt_scalef32_pk_bf16_fp4 v80, v119, 1.0 op_sel:[0,1,0]
	v_cvt_scalef32_pk_bf16_fp4 v116, v119, 1.0 op_sel:[1,1,0]
	s_nop 0
	v_dot2c_f32_bf16_e32 v82, v60, v30
	v_dot2c_f32_bf16_e32 v58, v62, v28
	s_nop 0
	v_dot2c_f32_bf16_e32 v82, v80, v36
	v_dot2c_f32_bf16_e32 v58, v116, v34
	s_nop 0
	s_nop 2
	v_add_f32_e32 v133, v82, v58
	v_lshl_add_u64 v[58:59], v[40:41], 0, s[12:13]
	global_load_dwordx4 v[116:119], v[58:59], off
	s_waitcnt vmcnt(15)
	v_cvt_scalef32_pk_bf16_fp4 v58, v120, 1.0
	v_mov_b32_e32 v82, 0
	v_cvt_scalef32_pk_bf16_fp4 v60, v120, 1.0 op_sel:[1,0,0]
	v_cvt_scalef32_pk_bf16_fp4 v62, v120, 1.0 op_sel:[0,1,0]
	v_cvt_scalef32_pk_bf16_fp4 v80, v120, 1.0 op_sel:[1,1,0]
	v_dot2c_f32_bf16_e32 v82, v58, v6
	v_mov_b32_e32 v58, 0
	v_dot2c_f32_bf16_e32 v58, v60, v4
	v_dot2c_f32_bf16_e32 v82, v62, v10
	s_add_i32 s12, s28, -2
	v_dot2c_f32_bf16_e32 v58, v80, v8
	v_cvt_scalef32_pk_bf16_fp4 v60, v121, 1.0
	v_cvt_scalef32_pk_bf16_fp4 v62, v121, 1.0 op_sel:[1,0,0]
	v_cvt_scalef32_pk_bf16_fp4 v80, v121, 1.0 op_sel:[0,1,0]
	v_cvt_scalef32_pk_bf16_fp4 v120, v121, 1.0 op_sel:[1,1,0]
	v_readlane_b32 s12, v46, s12
	v_dot2c_f32_bf16_e32 v82, v60, v14
	v_dot2c_f32_bf16_e32 v58, v62, v12
	s_lshr_b32 s12, s12, 7
	v_dot2c_f32_bf16_e32 v82, v80, v18
	v_dot2c_f32_bf16_e32 v58, v120, v16
	v_cvt_scalef32_pk_bf16_fp4 v60, v122, 1.0
	v_cvt_scalef32_pk_bf16_fp4 v62, v122, 1.0 op_sel:[1,0,0]
	v_cvt_scalef32_pk_bf16_fp4 v80, v122, 1.0 op_sel:[0,1,0]
	v_cvt_scalef32_pk_bf16_fp4 v120, v122, 1.0 op_sel:[1,1,0]
	s_mov_b32 s13, s86
	v_dot2c_f32_bf16_e32 v82, v60, v22
	v_dot2c_f32_bf16_e32 v58, v62, v20
	s_lshl_b64 s[12:13], s[12:13], 10
	v_dot2c_f32_bf16_e32 v82, v80, v26
	v_dot2c_f32_bf16_e32 v58, v120, v24
	v_cvt_scalef32_pk_bf16_fp4 v60, v123, 1.0
	v_cvt_scalef32_pk_bf16_fp4 v62, v123, 1.0 op_sel:[1,0,0]
	v_cvt_scalef32_pk_bf16_fp4 v80, v123, 1.0 op_sel:[0,1,0]
	v_cvt_scalef32_pk_bf16_fp4 v120, v123, 1.0 op_sel:[1,1,0]
	s_nop 0
	v_dot2c_f32_bf16_e32 v82, v60, v30
	v_dot2c_f32_bf16_e32 v58, v62, v28
	s_nop 0
	v_dot2c_f32_bf16_e32 v82, v80, v36
	v_dot2c_f32_bf16_e32 v58, v120, v34
	s_nop 0
	s_nop 2
	v_add_f32_e32 v134, v82, v58
	v_lshl_add_u64 v[58:59], v[40:41], 0, s[12:13]
	global_load_dwordx4 v[120:123], v[58:59], off
	s_waitcnt vmcnt(15)
	v_cvt_scalef32_pk_bf16_fp4 v58, v124, 1.0
	v_mov_b32_e32 v82, 0
	v_cvt_scalef32_pk_bf16_fp4 v60, v124, 1.0 op_sel:[1,0,0]
	v_cvt_scalef32_pk_bf16_fp4 v62, v124, 1.0 op_sel:[0,1,0]
	v_cvt_scalef32_pk_bf16_fp4 v80, v124, 1.0 op_sel:[1,1,0]
	v_dot2c_f32_bf16_e32 v82, v58, v6
	v_mov_b32_e32 v58, 0
	v_dot2c_f32_bf16_e32 v58, v60, v4
	v_dot2c_f32_bf16_e32 v82, v62, v10
	s_add_i32 s12, s28, -1
	v_dot2c_f32_bf16_e32 v58, v80, v8
	v_cvt_scalef32_pk_bf16_fp4 v60, v125, 1.0
	v_cvt_scalef32_pk_bf16_fp4 v62, v125, 1.0 op_sel:[1,0,0]
	v_cvt_scalef32_pk_bf16_fp4 v80, v125, 1.0 op_sel:[0,1,0]
	v_cvt_scalef32_pk_bf16_fp4 v124, v125, 1.0 op_sel:[1,1,0]
	v_readlane_b32 s12, v46, s12
	v_dot2c_f32_bf16_e32 v82, v60, v14
	v_dot2c_f32_bf16_e32 v58, v62, v12
	s_lshr_b32 s12, s12, 7
	v_dot2c_f32_bf16_e32 v82, v80, v18
	v_dot2c_f32_bf16_e32 v58, v124, v16
	v_cvt_scalef32_pk_bf16_fp4 v60, v126, 1.0
	v_cvt_scalef32_pk_bf16_fp4 v62, v126, 1.0 op_sel:[1,0,0]
	v_cvt_scalef32_pk_bf16_fp4 v80, v126, 1.0 op_sel:[0,1,0]
	v_cvt_scalef32_pk_bf16_fp4 v124, v126, 1.0 op_sel:[1,1,0]
	s_mov_b32 s13, s86
	v_dot2c_f32_bf16_e32 v82, v60, v22
	v_dot2c_f32_bf16_e32 v58, v62, v20
	s_lshl_b64 s[12:13], s[12:13], 10
	v_dot2c_f32_bf16_e32 v82, v80, v26
	v_dot2c_f32_bf16_e32 v58, v124, v24
	v_cvt_scalef32_pk_bf16_fp4 v60, v127, 1.0
	v_cvt_scalef32_pk_bf16_fp4 v62, v127, 1.0 op_sel:[1,0,0]
	v_cvt_scalef32_pk_bf16_fp4 v80, v127, 1.0 op_sel:[0,1,0]
	v_cvt_scalef32_pk_bf16_fp4 v124, v127, 1.0 op_sel:[1,1,0]
	s_nop 0
	v_dot2c_f32_bf16_e32 v82, v60, v30
	v_dot2c_f32_bf16_e32 v58, v62, v28
	s_nop 0
	v_dot2c_f32_bf16_e32 v82, v80, v36
	v_dot2c_f32_bf16_e32 v58, v124, v34
	s_nop 0
	s_nop 2
	v_add_f32_e32 v135, v82, v58
	v_lshl_add_u64 v[58:59], v[40:41], 0, s[12:13]
	v_mov_b32_e32 v82, 0
	global_load_dwordx4 v[124:127], v[58:59], off
	s_waitcnt vmcnt(15)
	v_cvt_scalef32_pk_bf16_fp4 v58, v128, 1.0
	v_cvt_scalef32_pk_bf16_fp4 v60, v128, 1.0 op_sel:[1,0,0]
	v_cvt_scalef32_pk_bf16_fp4 v62, v128, 1.0 op_sel:[0,1,0]
	v_cvt_scalef32_pk_bf16_fp4 v80, v128, 1.0 op_sel:[1,1,0]
	v_readlane_b32 s12, v46, s28
	v_dot2c_f32_bf16_e32 v82, v58, v6
	v_dot2c_f32_bf16_e32 v42, v60, v4
	s_lshr_b32 s12, s12, 7
	v_dot2c_f32_bf16_e32 v82, v62, v10
	v_dot2c_f32_bf16_e32 v42, v80, v8
	v_cvt_scalef32_pk_bf16_fp4 v58, v129, 1.0
	v_cvt_scalef32_pk_bf16_fp4 v60, v129, 1.0 op_sel:[1,0,0]
	v_cvt_scalef32_pk_bf16_fp4 v62, v129, 1.0 op_sel:[0,1,0]
	v_cvt_scalef32_pk_bf16_fp4 v80, v129, 1.0 op_sel:[1,1,0]
	s_mov_b32 s13, s86
	v_dot2c_f32_bf16_e32 v82, v58, v14
	v_dot2c_f32_bf16_e32 v42, v60, v12
	s_lshl_b64 s[12:13], s[12:13], 10
	v_dot2c_f32_bf16_e32 v82, v62, v18
	v_dot2c_f32_bf16_e32 v42, v80, v16
	v_cvt_scalef32_pk_bf16_fp4 v58, v130, 1.0
	v_cvt_scalef32_pk_bf16_fp4 v60, v130, 1.0 op_sel:[1,0,0]
	v_cvt_scalef32_pk_bf16_fp4 v62, v130, 1.0 op_sel:[0,1,0]
	v_cvt_scalef32_pk_bf16_fp4 v80, v130, 1.0 op_sel:[1,1,0]
	v_cndmask_b32_e64 v46, v48, v56, s[46:47]
	v_dot2c_f32_bf16_e32 v82, v58, v22
	v_dot2c_f32_bf16_e32 v42, v60, v20
	ds_swizzle_b32 v46, v46 offset:swizzle(SWAP,8)
	v_dot2c_f32_bf16_e32 v82, v62, v26
	v_dot2c_f32_bf16_e32 v42, v80, v24
	v_cvt_scalef32_pk_bf16_fp4 v58, v131, 1.0
	v_cvt_scalef32_pk_bf16_fp4 v60, v131, 1.0 op_sel:[1,0,0]
	v_cvt_scalef32_pk_bf16_fp4 v62, v131, 1.0 op_sel:[0,1,0]
	v_cvt_scalef32_pk_bf16_fp4 v80, v131, 1.0 op_sel:[1,1,0]
	s_nop 0
	v_dot2c_f32_bf16_e32 v82, v58, v30
	v_dot2c_f32_bf16_e32 v42, v60, v28
	s_nop 0
	v_dot2c_f32_bf16_e32 v82, v62, v36
	v_dot2c_f32_bf16_e32 v42, v80, v34
	s_nop 0
	s_nop 2
	v_add_f32_e32 v58, v82, v42
	v_lshl_add_u64 v[42:43], v[40:41], 0, s[12:13]
	global_load_dwordx4 v[128:131], v[42:43], off
	v_cndmask_b32_e64 v43, v47, v55, s[46:47]
	ds_swizzle_b32 v43, v43 offset:swizzle(SWAP,8)
	v_cndmask_b32_e64 v42, v55, v47, s[46:47]
	v_cndmask_b32_e64 v47, v49, v57, s[46:47]
	ds_swizzle_b32 v47, v47 offset:swizzle(SWAP,8)
	s_waitcnt lgkmcnt(1)
	v_add_f32_e32 v42, v42, v43
	v_cndmask_b32_e64 v43, v56, v48, s[46:47]
	v_cndmask_b32_e64 v48, v50, v132, s[46:47]
	v_add_f32_e32 v43, v43, v46
	v_cndmask_b32_e64 v46, v57, v49, s[46:47]
	ds_swizzle_b32 v48, v48 offset:swizzle(SWAP,8)
	v_cndmask_b32_e64 v49, v51, v133, s[46:47]
	ds_swizzle_b32 v49, v49 offset:swizzle(SWAP,8)
	s_waitcnt lgkmcnt(2)
	v_add_f32_e32 v46, v46, v47
	v_cndmask_b32_e64 v47, v132, v50, s[46:47]
	v_cndmask_b32_e64 v50, v52, v134, s[46:47]
	ds_swizzle_b32 v50, v50 offset:swizzle(SWAP,8)
	s_waitcnt lgkmcnt(2)
	v_add_f32_e32 v47, v47, v48
	v_cndmask_b32_e64 v48, v133, v51, s[46:47]
	v_cndmask_b32_e64 v51, v53, v135, s[46:47]
	s_waitcnt lgkmcnt(1)
	v_add_f32_e32 v48, v48, v49
	v_cndmask_b32_e64 v49, v134, v52, s[46:47]
	ds_swizzle_b32 v51, v51 offset:swizzle(SWAP,8)
	v_cndmask_b32_e64 v52, v54, v58, s[46:47]
	ds_swizzle_b32 v52, v52 offset:swizzle(SWAP,8)
	s_waitcnt lgkmcnt(2)
	v_add_f32_e32 v49, v49, v50
	v_cndmask_b32_e64 v50, v135, v53, s[46:47]
	s_waitcnt lgkmcnt(1)
	v_add_f32_e32 v50, v50, v51
	v_cndmask_b32_e64 v51, v58, v54, s[46:47]
	s_waitcnt lgkmcnt(0)
	v_add_f32_e32 v51, v51, v52
	v_cndmask_b32_e64 v53, v42, v48, s[44:45]
	v_cndmask_b32_e64 v42, v48, v42, s[44:45]
	v_cndmask_b32_e64 v48, v49, v43, s[44:45]
	v_cndmask_b32_e64 v43, v43, v49, s[44:45]
	v_cndmask_b32_e64 v49, v46, v50, s[44:45]
	v_cndmask_b32_e64 v52, v47, v51, s[44:45]
	ds_swizzle_b32 v53, v53 offset:swizzle(SWAP,4)
	ds_swizzle_b32 v43, v43 offset:swizzle(SWAP,4)
	ds_swizzle_b32 v49, v49 offset:swizzle(SWAP,4)
	ds_swizzle_b32 v52, v52 offset:swizzle(SWAP,4)
	v_cndmask_b32_e64 v46, v50, v46, s[44:45]
	v_cndmask_b32_e64 v47, v51, v47, s[44:45]
	s_waitcnt lgkmcnt(3)
	v_add_f32_e32 v42, v42, v53
	s_waitcnt lgkmcnt(2)
	v_add_f32_e32 v43, v48, v43
	s_waitcnt lgkmcnt(1)
	v_add_f32_e32 v46, v46, v49
	s_waitcnt lgkmcnt(0)
	v_add_f32_e32 v47, v47, v52
	v_cndmask_b32_e64 v48, v42, v46, s[42:43]
	v_cndmask_b32_e64 v49, v43, v47, s[42:43]
	ds_swizzle_b32 v48, v48 offset:swizzle(SWAP,2)
	ds_swizzle_b32 v49, v49 offset:swizzle(SWAP,2)
	v_cndmask_b32_e64 v42, v46, v42, s[42:43]
	v_cndmask_b32_e64 v43, v47, v43, s[42:43]
	s_waitcnt lgkmcnt(1)
	v_add_f32_e32 v42, v42, v48
	s_waitcnt lgkmcnt(0)
	v_add_f32_e32 v43, v43, v49
	v_cndmask_b32_e64 v46, v42, v43, s[40:41]
	ds_swizzle_b32 v46, v46 offset:swizzle(SWAP,1)
	v_cndmask_b32_e64 v42, v43, v42, s[40:41]
	s_waitcnt lgkmcnt(0)
	v_add_f32_e32 v42, v42, v46
	ds_swizzle_b32 v43, v42 offset:swizzle(SWAP,16)
	s_waitcnt lgkmcnt(0)
	v_add_f32_e32 v46, v42, v43
	ds_read2st64_b32 v[42:43], v45 offset1:8
	v_mov_b32_e32 v47, v46
	s_nop 1
	v_permlane32_swap_b32_e32 v46, v47
	v_add_f32_e32 v46, v46, v47
	s_waitcnt lgkmcnt(0)
	v_mul_f32_e32 v42, v42, v46
	v_mul_f32_e32 v46, 0x3d372713, v42
	v_mul_f32_e32 v46, v42, v46
	v_fma_f32 v46, v42, v46, v42
	v_mul_f32_e32 v46, 0x3f4c422a, v46
	v_cmp_nlt_f32_e64 s[12:13], |v46|, s25
	s_and_saveexec_b64 s[48:49], s[12:13]
	s_xor_b64 s[12:13], exec, s[48:49]
	s_cbranch_execz .LBB0_1233
	v_add_f32_e64 v47, |v46|, |v46|
	v_mul_f32_e32 v48, 0x3fb8aa3b, v47
	v_rndne_f32_e32 v49, v48
	v_sub_f32_e32 v50, v48, v49
	v_fma_f32 v48, v47, s70, -v48
	v_fmac_f32_e32 v48, 0x32a5705f, v47
	v_add_f32_e32 v48, v50, v48
	v_cvt_i32_f32_e32 v49, v49
	v_exp_f32_e32 v48, v48
	v_cmp_ngt_f32_e64 s[48:49], s67, v47
	v_ldexp_f32 v48, v48, v49
	s_nop 0
	v_cndmask_b32_e64 v48, 0, v48, s[48:49]
	v_cmp_nlt_f32_e64 s[48:49], s68, v47
	s_nop 1
	v_cndmask_b32_e64 v47, v205, v48, s[48:49]
	v_add_f32_e32 v47, 1.0, v47
	v_rcp_f32_e32 v47, v47
	s_nop 0
	v_fma_f32 v47, v47, -2.0, 1.0
	s_andn2_saveexec_b64 s[12:13], s[12:13]
	s_cbranch_execnz .LBB0_1234

; #define P4_FOR16(M) M(0) M(1) M(2) M(3) M(4) M(5) M(6) M(7) M(8) M(9) M(10) M(11) M(12) M(13) M(14) M(15)
; #define P4_U(i) { P4_DOT(b##i, part[i]); const int nk_ = __builtin_amdgcn_readlane(ksel, nb + i); P4_LOAD(b##i, Ug, nk_); }
; #define P4_U(i) { P4_DOT(b##i, part[i]); const int nk_ = __builtin_amdgcn_readlane(kn, i); P4_LOAD(b##i, nbase, nk_); }
; __device__ __forceinline__ void peer_gather_f4p(const float* X, const int* __restrict__ IDX, const float* __restrict__ G, ...
;     ...
;         {
;     ...
;             P4_FOR16(P4_U)
.LBB0_1236:
	s_mov_b32 s87, s86
	s_waitcnt vmcnt(15)
	v_cvt_scalef32_pk_bf16_fp4 v42, v64, 1.0
	v_mov_b32_e32 v50, 0
	v_or_b32_e32 v40, s27, v44
	v_cvt_scalef32_pk_bf16_fp4 v44, v64, 1.0 op_sel:[1,0,0]
	v_cvt_scalef32_pk_bf16_fp4 v46, v64, 1.0 op_sel:[0,1,0]
	v_cvt_scalef32_pk_bf16_fp4 v48, v64, 1.0 op_sel:[1,1,0]
	v_dot2c_f32_bf16_e32 v50, v42, v6
	v_mov_b32_e32 v42, 0
	v_dot2c_f32_bf16_e32 v42, v44, v4
	v_dot2c_f32_bf16_e32 v50, v46, v10
	s_cmp_eq_u32 s26, 3
	v_dot2c_f32_bf16_e32 v42, v48, v8
	v_cvt_scalef32_pk_bf16_fp4 v44, v65, 1.0
	v_cvt_scalef32_pk_bf16_fp4 v46, v65, 1.0 op_sel:[1,0,0]
	v_cvt_scalef32_pk_bf16_fp4 v48, v65, 1.0 op_sel:[0,1,0]
	v_cvt_scalef32_pk_bf16_fp4 v52, v65, 1.0 op_sel:[1,1,0]
	v_readlane_b32 s26, v2, 0
	v_dot2c_f32_bf16_e32 v50, v44, v14
	v_dot2c_f32_bf16_e32 v42, v46, v12
	s_cselect_b32 s12, s53, s51
	v_dot2c_f32_bf16_e32 v50, v48, v18
	v_dot2c_f32_bf16_e32 v42, v52, v16
	v_cvt_scalef32_pk_bf16_fp4 v44, v66, 1.0
	v_cvt_scalef32_pk_bf16_fp4 v46, v66, 1.0 op_sel:[1,0,0]
	v_cvt_scalef32_pk_bf16_fp4 v48, v66, 1.0 op_sel:[0,1,0]
	v_cvt_scalef32_pk_bf16_fp4 v52, v66, 1.0 op_sel:[1,1,0]
	s_cselect_b32 s13, s52, s50
	v_dot2c_f32_bf16_e32 v50, v44, v22
	v_dot2c_f32_bf16_e32 v42, v46, v20
	s_lshr_b32 s26, s26, 7
	v_dot2c_f32_bf16_e32 v50, v48, v26
	v_dot2c_f32_bf16_e32 v42, v52, v24
	s_mov_b32 s27, s86
	v_cvt_scalef32_pk_bf16_fp4 v44, v67, 1.0
	v_cvt_scalef32_pk_bf16_fp4 v46, v67, 1.0 op_sel:[1,0,0]
	v_cvt_scalef32_pk_bf16_fp4 v48, v67, 1.0 op_sel:[0,1,0]
	v_cvt_scalef32_pk_bf16_fp4 v52, v67, 1.0 op_sel:[1,1,0]
	s_lshl_b64 s[26:27], s[26:27], 10
	v_dot2c_f32_bf16_e32 v50, v44, v30
	v_dot2c_f32_bf16_e32 v42, v46, v28
	s_add_u32 s26, s13, s26
	v_dot2c_f32_bf16_e32 v50, v48, v36
	v_dot2c_f32_bf16_e32 v42, v52, v34
	s_addc_u32 s27, s12, s27
	s_nop 2
	v_add_f32_e32 v41, v50, v42
	v_lshl_add_u64 v[42:43], s[26:27], 0, v[32:33]
	global_load_dwordx4 v[64:67], v[42:43], off
	s_waitcnt vmcnt(15)
	v_cvt_scalef32_pk_bf16_fp4 v42, v68, 1.0
	v_mov_b32_e32 v50, 0
	v_cvt_scalef32_pk_bf16_fp4 v44, v68, 1.0 op_sel:[1,0,0]
	v_cvt_scalef32_pk_bf16_fp4 v46, v68, 1.0 op_sel:[0,1,0]
	v_cvt_scalef32_pk_bf16_fp4 v48, v68, 1.0 op_sel:[1,1,0]
	v_dot2c_f32_bf16_e32 v50, v42, v6
	v_mov_b32_e32 v42, 0
	v_dot2c_f32_bf16_e32 v42, v44, v4
	v_dot2c_f32_bf16_e32 v50, v46, v10
	v_readlane_b32 s26, v2, 1
	v_dot2c_f32_bf16_e32 v42, v48, v8
	v_cvt_scalef32_pk_bf16_fp4 v44, v69, 1.0
	v_cvt_scalef32_pk_bf16_fp4 v46, v69, 1.0 op_sel:[1,0,0]
	v_cvt_scalef32_pk_bf16_fp4 v48, v69, 1.0 op_sel:[0,1,0]
	v_cvt_scalef32_pk_bf16_fp4 v52, v69, 1.0 op_sel:[1,1,0]
	s_lshr_b32 s26, s26, 7
	v_dot2c_f32_bf16_e32 v50, v44, v14
	v_dot2c_f32_bf16_e32 v42, v46, v12
	s_mov_b32 s27, s86
	v_dot2c_f32_bf16_e32 v50, v48, v18
	v_dot2c_f32_bf16_e32 v42, v52, v16
	v_cvt_scalef32_pk_bf16_fp4 v44, v70, 1.0
	v_cvt_scalef32_pk_bf16_fp4 v46, v70, 1.0 op_sel:[1,0,0]
	v_cvt_scalef32_pk_bf16_fp4 v48, v70, 1.0 op_sel:[0,1,0]
	v_cvt_scalef32_pk_bf16_fp4 v52, v70, 1.0 op_sel:[1,1,0]
	s_lshl_b64 s[26:27], s[26:27], 10
	v_dot2c_f32_bf16_e32 v50, v44, v22
	v_dot2c_f32_bf16_e32 v42, v46, v20
	s_add_u32 s26, s13, s26
	v_dot2c_f32_bf16_e32 v50, v48, v26
	v_dot2c_f32_bf16_e32 v42, v52, v24
	v_cvt_scalef32_pk_bf16_fp4 v44, v71, 1.0
	v_cvt_scalef32_pk_bf16_fp4 v46, v71, 1.0 op_sel:[1,0,0]
	v_cvt_scalef32_pk_bf16_fp4 v48, v71, 1.0 op_sel:[0,1,0]
	v_cvt_scalef32_pk_bf16_fp4 v52, v71, 1.0 op_sel:[1,1,0]
	s_addc_u32 s27, s12, s27
	v_dot2c_f32_bf16_e32 v50, v44, v30
	v_dot2c_f32_bf16_e32 v42, v46, v28
	v_mov_b32_e32 v38, 0
	v_dot2c_f32_bf16_e32 v50, v48, v36
	v_dot2c_f32_bf16_e32 v42, v52, v34
	v_mov_b32_e32 v52, 0
	s_nop 2
	v_add_f32_e32 v42, v50, v42
	v_lshl_add_u64 v[44:45], s[26:27], 0, v[32:33]
	global_load_dwordx4 v[68:71], v[44:45], off
	s_waitcnt vmcnt(15)
	v_cvt_scalef32_pk_bf16_fp4 v44, v72, 1.0
	v_cvt_scalef32_pk_bf16_fp4 v46, v72, 1.0 op_sel:[1,0,0]
	v_cvt_scalef32_pk_bf16_fp4 v48, v72, 1.0 op_sel:[0,1,0]
	v_cvt_scalef32_pk_bf16_fp4 v50, v72, 1.0 op_sel:[1,1,0]
	v_readlane_b32 s26, v2, 2
	v_dot2c_f32_bf16_e32 v52, v44, v6
	v_mov_b32_e32 v44, 0
	v_dot2c_f32_bf16_e32 v44, v46, v4
	v_dot2c_f32_bf16_e32 v52, v48, v10
	s_lshr_b32 s26, s26, 7
	v_dot2c_f32_bf16_e32 v44, v50, v8
	v_cvt_scalef32_pk_bf16_fp4 v46, v73, 1.0
	v_cvt_scalef32_pk_bf16_fp4 v48, v73, 1.0 op_sel:[1,0,0]
	v_cvt_scalef32_pk_bf16_fp4 v50, v73, 1.0 op_sel:[0,1,0]
	v_cvt_scalef32_pk_bf16_fp4 v54, v73, 1.0 op_sel:[1,1,0]
	s_mov_b32 s27, s86
	v_dot2c_f32_bf16_e32 v52, v46, v14
	v_dot2c_f32_bf16_e32 v44, v48, v12
	s_lshl_b64 s[26:27], s[26:27], 10
	v_dot2c_f32_bf16_e32 v52, v50, v18
	v_dot2c_f32_bf16_e32 v44, v54, v16
	v_cvt_scalef32_pk_bf16_fp4 v46, v74, 1.0
	v_cvt_scalef32_pk_bf16_fp4 v48, v74, 1.0 op_sel:[1,0,0]
	v_cvt_scalef32_pk_bf16_fp4 v50, v74, 1.0 op_sel:[0,1,0]
	v_cvt_scalef32_pk_bf16_fp4 v54, v74, 1.0 op_sel:[1,1,0]
	s_add_u32 s26, s13, s26
	v_dot2c_f32_bf16_e32 v52, v46, v22
	v_dot2c_f32_bf16_e32 v44, v48, v20
	s_addc_u32 s27, s12, s27
	v_dot2c_f32_bf16_e32 v52, v50, v26
	v_dot2c_f32_bf16_e32 v44, v54, v24
	v_cvt_scalef32_pk_bf16_fp4 v46, v75, 1.0
	v_cvt_scalef32_pk_bf16_fp4 v48, v75, 1.0 op_sel:[1,0,0]
	v_cvt_scalef32_pk_bf16_fp4 v50, v75, 1.0 op_sel:[0,1,0]
	v_cvt_scalef32_pk_bf16_fp4 v54, v75, 1.0 op_sel:[1,1,0]
	s_nop 0
	v_dot2c_f32_bf16_e32 v52, v46, v30
	v_dot2c_f32_bf16_e32 v44, v48, v28
	s_nop 0
	v_dot2c_f32_bf16_e32 v52, v50, v36
	v_dot2c_f32_bf16_e32 v44, v54, v34
	s_nop 0
	s_nop 2
	v_add_f32_e32 v43, v52, v44
	v_lshl_add_u64 v[44:45], s[26:27], 0, v[32:33]
	global_load_dwordx4 v[72:75], v[44:45], off
	s_waitcnt vmcnt(15)
; #define P4_FOR16(M) M(0) M(1) M(2) M(3) M(4) M(5) M(6) M(7) M(8) M(9) M(10) M(11) M(12) M(13) M(14) M(15)
; #define P4_U(i) { P4_DOT(b##i, part[i]); const int nk_ = __builtin_amdgcn_readlane(ksel, nb + i); P4_LOAD(b##i, Ug, nk_); }
; #define P4_U(i) { P4_DOT(b##i, part[i]); const int nk_ = __builtin_amdgcn_readlane(kn, i); P4_LOAD(b##i, nbase, nk_); }
; __device__ __forceinline__ void peer_gather_f4p(const float* X, const int* __restrict__ IDX, const float* __restrict__ G, ...
;     ...
;         {
;     ...
;             P4_FOR16(P4_U)
	v_cvt_scalef32_pk_bf16_fp4 v44, v76, 1.0
	v_mov_b32_e32 v52, 0
	v_cvt_scalef32_pk_bf16_fp4 v46, v76, 1.0 op_sel:[1,0,0]
	v_cvt_scalef32_pk_bf16_fp4 v48, v76, 1.0 op_sel:[0,1,0]
	v_cvt_scalef32_pk_bf16_fp4 v50, v76, 1.0 op_sel:[1,1,0]
	v_dot2c_f32_bf16_e32 v52, v44, v6
	v_mov_b32_e32 v44, 0
	v_dot2c_f32_bf16_e32 v44, v46, v4
	v_dot2c_f32_bf16_e32 v52, v48, v10
	v_readlane_b32 s26, v2, 3
	v_dot2c_f32_bf16_e32 v44, v50, v8
	v_cvt_scalef32_pk_bf16_fp4 v46, v77, 1.0
	v_cvt_scalef32_pk_bf16_fp4 v48, v77, 1.0 op_sel:[1,0,0]
	v_cvt_scalef32_pk_bf16_fp4 v50, v77, 1.0 op_sel:[0,1,0]
	v_cvt_scalef32_pk_bf16_fp4 v54, v77, 1.0 op_sel:[1,1,0]
	s_lshr_b32 s26, s26, 7
	v_dot2c_f32_bf16_e32 v52, v46, v14
	v_dot2c_f32_bf16_e32 v44, v48, v12
	s_mov_b32 s27, s86
	v_dot2c_f32_bf16_e32 v52, v50, v18
	v_dot2c_f32_bf16_e32 v44, v54, v16
	v_cvt_scalef32_pk_bf16_fp4 v46, v78, 1.0
	v_cvt_scalef32_pk_bf16_fp4 v48, v78, 1.0 op_sel:[1,0,0]
	v_cvt_scalef32_pk_bf16_fp4 v50, v78, 1.0 op_sel:[0,1,0]
	v_cvt_scalef32_pk_bf16_fp4 v54, v78, 1.0 op_sel:[1,1,0]
	s_lshl_b64 s[26:27], s[26:27], 10
	v_dot2c_f32_bf16_e32 v52, v46, v22
	v_dot2c_f32_bf16_e32 v44, v48, v20
	s_add_u32 s26, s13, s26
	v_dot2c_f32_bf16_e32 v52, v50, v26
	v_dot2c_f32_bf16_e32 v44, v54, v24
	v_cvt_scalef32_pk_bf16_fp4 v46, v79, 1.0
	v_cvt_scalef32_pk_bf16_fp4 v48, v79, 1.0 op_sel:[1,0,0]
	v_cvt_scalef32_pk_bf16_fp4 v50, v79, 1.0 op_sel:[0,1,0]
	v_cvt_scalef32_pk_bf16_fp4 v54, v79, 1.0 op_sel:[1,1,0]
	s_addc_u32 s27, s12, s27
	v_dot2c_f32_bf16_e32 v52, v46, v30
	v_dot2c_f32_bf16_e32 v44, v48, v28
	s_nop 0
	v_dot2c_f32_bf16_e32 v52, v50, v36
	v_dot2c_f32_bf16_e32 v44, v54, v34
	v_mov_b32_e32 v54, 0
	s_nop 2
	v_add_f32_e32 v44, v52, v44
	v_lshl_add_u64 v[46:47], s[26:27], 0, v[32:33]
	global_load_dwordx4 v[76:79], v[46:47], off
	s_waitcnt vmcnt(15)
	v_cvt_scalef32_pk_bf16_fp4 v46, v84, 1.0
	v_cvt_scalef32_pk_bf16_fp4 v48, v84, 1.0 op_sel:[1,0,0]
	v_cvt_scalef32_pk_bf16_fp4 v50, v84, 1.0 op_sel:[0,1,0]
	v_cvt_scalef32_pk_bf16_fp4 v52, v84, 1.0 op_sel:[1,1,0]
	v_readlane_b32 s26, v2, 4
	v_dot2c_f32_bf16_e32 v54, v46, v6
	v_mov_b32_e32 v46, 0
	v_dot2c_f32_bf16_e32 v46, v48, v4
	v_dot2c_f32_bf16_e32 v54, v50, v10
	s_lshr_b32 s26, s26, 7
	v_dot2c_f32_bf16_e32 v46, v52, v8
	v_cvt_scalef32_pk_bf16_fp4 v48, v85, 1.0
	v_cvt_scalef32_pk_bf16_fp4 v50, v85, 1.0 op_sel:[1,0,0]
	v_cvt_scalef32_pk_bf16_fp4 v52, v85, 1.0 op_sel:[0,1,0]
	v_cvt_scalef32_pk_bf16_fp4 v56, v85, 1.0 op_sel:[1,1,0]
	s_mov_b32 s27, s86
	v_dot2c_f32_bf16_e32 v54, v48, v14
	v_dot2c_f32_bf16_e32 v46, v50, v12
	s_lshl_b64 s[26:27], s[26:27], 10
	v_dot2c_f32_bf16_e32 v54, v52, v18
	v_dot2c_f32_bf16_e32 v46, v56, v16
	v_cvt_scalef32_pk_bf16_fp4 v48, v86, 1.0
	v_cvt_scalef32_pk_bf16_fp4 v50, v86, 1.0 op_sel:[1,0,0]
	v_cvt_scalef32_pk_bf16_fp4 v52, v86, 1.0 op_sel:[0,1,0]
	v_cvt_scalef32_pk_bf16_fp4 v56, v86, 1.0 op_sel:[1,1,0]
	s_add_u32 s26, s13, s26
	v_dot2c_f32_bf16_e32 v54, v48, v22
	v_dot2c_f32_bf16_e32 v46, v50, v20
	s_addc_u32 s27, s12, s27
	v_dot2c_f32_bf16_e32 v54, v52, v26
	v_dot2c_f32_bf16_e32 v46, v56, v24
	v_cvt_scalef32_pk_bf16_fp4 v48, v87, 1.0
	v_cvt_scalef32_pk_bf16_fp4 v50, v87, 1.0 op_sel:[1,0,0]
	v_cvt_scalef32_pk_bf16_fp4 v52, v87, 1.0 op_sel:[0,1,0]
	v_cvt_scalef32_pk_bf16_fp4 v56, v87, 1.0 op_sel:[1,1,0]
	s_nop 0
	v_dot2c_f32_bf16_e32 v54, v48, v30
	v_dot2c_f32_bf16_e32 v46, v50, v28
	s_nop 0
	v_dot2c_f32_bf16_e32 v54, v52, v36
	v_dot2c_f32_bf16_e32 v46, v56, v34
	s_nop 0
	s_nop 2
	v_add_f32_e32 v45, v54, v46
	v_lshl_add_u64 v[46:47], s[26:27], 0, v[32:33]
	global_load_dwordx4 v[84:87], v[46:47], off
	s_waitcnt vmcnt(15)
	v_cvt_scalef32_pk_bf16_fp4 v46, v88, 1.0
	v_mov_b32_e32 v54, 0
	v_cvt_scalef32_pk_bf16_fp4 v48, v88, 1.0 op_sel:[1,0,0]
	v_cvt_scalef32_pk_bf16_fp4 v50, v88, 1.0 op_sel:[0,1,0]
	v_cvt_scalef32_pk_bf16_fp4 v52, v88, 1.0 op_sel:[1,1,0]
	v_dot2c_f32_bf16_e32 v54, v46, v6
	v_mov_b32_e32 v46, 0
	v_dot2c_f32_bf16_e32 v46, v48, v4
	v_dot2c_f32_bf16_e32 v54, v50, v10
	v_readlane_b32 s26, v2, 5
	v_dot2c_f32_bf16_e32 v46, v52, v8
	v_cvt_scalef32_pk_bf16_fp4 v48, v89, 1.0
	v_cvt_scalef32_pk_bf16_fp4 v50, v89, 1.0 op_sel:[1,0,0]
	v_cvt_scalef32_pk_bf16_fp4 v52, v89, 1.0 op_sel:[0,1,0]
	v_cvt_scalef32_pk_bf16_fp4 v56, v89, 1.0 op_sel:[1,1,0]
	s_lshr_b32 s26, s26, 7
	v_dot2c_f32_bf16_e32 v54, v48, v14
	v_dot2c_f32_bf16_e32 v46, v50, v12
	s_mov_b32 s27, s86
	v_dot2c_f32_bf16_e32 v54, v52, v18
	v_dot2c_f32_bf16_e32 v46, v56, v16
	v_cvt_scalef32_pk_bf16_fp4 v48, v90, 1.0
	v_cvt_scalef32_pk_bf16_fp4 v50, v90, 1.0 op_sel:[1,0,0]
	v_cvt_scalef32_pk_bf16_fp4 v52, v90, 1.0 op_sel:[0,1,0]
	v_cvt_scalef32_pk_bf16_fp4 v56, v90, 1.0 op_sel:[1,1,0]
	s_lshl_b64 s[26:27], s[26:27], 10
	v_dot2c_f32_bf16_e32 v54, v48, v22
	v_dot2c_f32_bf16_e32 v46, v50, v20
	s_add_u32 s26, s13, s26
	v_dot2c_f32_bf16_e32 v54, v52, v26
	v_dot2c_f32_bf16_e32 v46, v56, v24
	v_cvt_scalef32_pk_bf16_fp4 v48, v91, 1.0
	v_cvt_scalef32_pk_bf16_fp4 v50, v91, 1.0 op_sel:[1,0,0]
	v_cvt_scalef32_pk_bf16_fp4 v52, v91, 1.0 op_sel:[0,1,0]
	v_cvt_scalef32_pk_bf16_fp4 v56, v91, 1.0 op_sel:[1,1,0]
	s_addc_u32 s27, s12, s27
	v_dot2c_f32_bf16_e32 v54, v48, v30
	v_dot2c_f32_bf16_e32 v46, v50, v28
	s_nop 0
	v_dot2c_f32_bf16_e32 v54, v52, v36
	v_dot2c_f32_bf16_e32 v46, v56, v34
	v_mov_b32_e32 v56, 0
	s_nop 2
	v_add_f32_e32 v46, v54, v46
	v_lshl_add_u64 v[48:49], s[26:27], 0, v[32:33]
	global_load_dwordx4 v[88:91], v[48:49], off
	s_waitcnt vmcnt(15)
; #define P4_FOR16(M) M(0) M(1) M(2) M(3) M(4) M(5) M(6) M(7) M(8) M(9) M(10) M(11) M(12) M(13) M(14) M(15)
; #define P4_U(i) { P4_DOT(b##i, part[i]); const int nk_ = __builtin_amdgcn_readlane(ksel, nb + i); P4_LOAD(b##i, Ug, nk_); }
; #define P4_U(i) { P4_DOT(b##i, part[i]); const int nk_ = __builtin_amdgcn_readlane(kn, i); P4_LOAD(b##i, nbase, nk_); }
; __device__ __forceinline__ void peer_gather_f4p(const float* X, const int* __restrict__ IDX, const float* __restrict__ G, ...
;     ...
;         {
;     ...
;             P4_FOR16(P4_U)
	v_cvt_scalef32_pk_bf16_fp4 v48, v92, 1.0
	v_cvt_scalef32_pk_bf16_fp4 v50, v92, 1.0 op_sel:[1,0,0]
	v_cvt_scalef32_pk_bf16_fp4 v52, v92, 1.0 op_sel:[0,1,0]
	v_cvt_scalef32_pk_bf16_fp4 v54, v92, 1.0 op_sel:[1,1,0]
	v_readlane_b32 s26, v2, 6
	v_dot2c_f32_bf16_e32 v56, v48, v6
	v_mov_b32_e32 v48, 0
	v_dot2c_f32_bf16_e32 v48, v50, v4
	v_dot2c_f32_bf16_e32 v56, v52, v10
	s_lshr_b32 s26, s26, 7
	v_dot2c_f32_bf16_e32 v48, v54, v8
	v_cvt_scalef32_pk_bf16_fp4 v50, v93, 1.0
	v_cvt_scalef32_pk_bf16_fp4 v52, v93, 1.0 op_sel:[1,0,0]
	v_cvt_scalef32_pk_bf16_fp4 v54, v93, 1.0 op_sel:[0,1,0]
	v_cvt_scalef32_pk_bf16_fp4 v58, v93, 1.0 op_sel:[1,1,0]
	s_mov_b32 s27, s86
	v_dot2c_f32_bf16_e32 v56, v50, v14
	v_dot2c_f32_bf16_e32 v48, v52, v12
	s_lshl_b64 s[26:27], s[26:27], 10
	v_dot2c_f32_bf16_e32 v56, v54, v18
	v_dot2c_f32_bf16_e32 v48, v58, v16
	v_cvt_scalef32_pk_bf16_fp4 v50, v94, 1.0
	v_cvt_scalef32_pk_bf16_fp4 v52, v94, 1.0 op_sel:[1,0,0]
	v_cvt_scalef32_pk_bf16_fp4 v54, v94, 1.0 op_sel:[0,1,0]
	v_cvt_scalef32_pk_bf16_fp4 v58, v94, 1.0 op_sel:[1,1,0]
	s_add_u32 s26, s13, s26
	v_dot2c_f32_bf16_e32 v56, v50, v22
	v_dot2c_f32_bf16_e32 v48, v52, v20
	s_addc_u32 s27, s12, s27
	v_dot2c_f32_bf16_e32 v56, v54, v26
	v_dot2c_f32_bf16_e32 v48, v58, v24
	v_cvt_scalef32_pk_bf16_fp4 v50, v95, 1.0
	v_cvt_scalef32_pk_bf16_fp4 v52, v95, 1.0 op_sel:[1,0,0]
	v_cvt_scalef32_pk_bf16_fp4 v54, v95, 1.0 op_sel:[0,1,0]
	v_cvt_scalef32_pk_bf16_fp4 v58, v95, 1.0 op_sel:[1,1,0]
	s_nop 0
	v_dot2c_f32_bf16_e32 v56, v50, v30
	v_dot2c_f32_bf16_e32 v48, v52, v28
	s_nop 0
	v_dot2c_f32_bf16_e32 v56, v54, v36
	v_dot2c_f32_bf16_e32 v48, v58, v34
	s_nop 0
	s_nop 2
	v_add_f32_e32 v47, v56, v48
	v_lshl_add_u64 v[48:49], s[26:27], 0, v[32:33]
	global_load_dwordx4 v[92:95], v[48:49], off
	s_waitcnt vmcnt(15)
	v_cvt_scalef32_pk_bf16_fp4 v48, v96, 1.0
	v_mov_b32_e32 v56, 0
	v_cvt_scalef32_pk_bf16_fp4 v50, v96, 1.0 op_sel:[1,0,0]
	v_cvt_scalef32_pk_bf16_fp4 v52, v96, 1.0 op_sel:[0,1,0]
	v_cvt_scalef32_pk_bf16_fp4 v54, v96, 1.0 op_sel:[1,1,0]
	v_dot2c_f32_bf16_e32 v56, v48, v6
	v_mov_b32_e32 v48, 0
	v_dot2c_f32_bf16_e32 v48, v50, v4
	v_dot2c_f32_bf16_e32 v56, v52, v10
	v_readlane_b32 s26, v2, 7
	v_dot2c_f32_bf16_e32 v48, v54, v8
	v_cvt_scalef32_pk_bf16_fp4 v50, v97, 1.0
	v_cvt_scalef32_pk_bf16_fp4 v52, v97, 1.0 op_sel:[1,0,0]
	v_cvt_scalef32_pk_bf16_fp4 v54, v97, 1.0 op_sel:[0,1,0]
	v_cvt_scalef32_pk_bf16_fp4 v58, v97, 1.0 op_sel:[1,1,0]
	s_lshr_b32 s26, s26, 7
	v_dot2c_f32_bf16_e32 v56, v50, v14
	v_dot2c_f32_bf16_e32 v48, v52, v12
	s_mov_b32 s27, s86
	v_dot2c_f32_bf16_e32 v56, v54, v18
	v_dot2c_f32_bf16_e32 v48, v58, v16
	v_cvt_scalef32_pk_bf16_fp4 v50, v98, 1.0
	v_cvt_scalef32_pk_bf16_fp4 v52, v98, 1.0 op_sel:[1,0,0]
	v_cvt_scalef32_pk_bf16_fp4 v54, v98, 1.0 op_sel:[0,1,0]
	v_cvt_scalef32_pk_bf16_fp4 v58, v98, 1.0 op_sel:[1,1,0]
	s_lshl_b64 s[26:27], s[26:27], 10
	v_dot2c_f32_bf16_e32 v56, v50, v22
	v_dot2c_f32_bf16_e32 v48, v52, v20
	s_add_u32 s26, s13, s26
	v_dot2c_f32_bf16_e32 v56, v54, v26
	v_dot2c_f32_bf16_e32 v48, v58, v24
	v_cvt_scalef32_pk_bf16_fp4 v50, v99, 1.0
	v_cvt_scalef32_pk_bf16_fp4 v52, v99, 1.0 op_sel:[1,0,0]
	v_cvt_scalef32_pk_bf16_fp4 v54, v99, 1.0 op_sel:[0,1,0]
	v_cvt_scalef32_pk_bf16_fp4 v58, v99, 1.0 op_sel:[1,1,0]
	s_addc_u32 s27, s12, s27
	v_dot2c_f32_bf16_e32 v56, v50, v30
	v_dot2c_f32_bf16_e32 v48, v52, v28
	s_nop 0
	v_dot2c_f32_bf16_e32 v56, v54, v36
	v_dot2c_f32_bf16_e32 v48, v58, v34
	v_mov_b32_e32 v58, 0
	s_nop 2
	v_add_f32_e32 v48, v56, v48
	v_lshl_add_u64 v[50:51], s[26:27], 0, v[32:33]
	global_load_dwordx4 v[96:99], v[50:51], off
	s_waitcnt vmcnt(15)
	v_cvt_scalef32_pk_bf16_fp4 v50, v100, 1.0
	v_cvt_scalef32_pk_bf16_fp4 v52, v100, 1.0 op_sel:[1,0,0]
	v_cvt_scalef32_pk_bf16_fp4 v54, v100, 1.0 op_sel:[0,1,0]
	v_cvt_scalef32_pk_bf16_fp4 v56, v100, 1.0 op_sel:[1,1,0]
	v_readlane_b32 s26, v2, 8
	v_dot2c_f32_bf16_e32 v58, v50, v6
	v_mov_b32_e32 v50, 0
	v_dot2c_f32_bf16_e32 v50, v52, v4
	v_dot2c_f32_bf16_e32 v58, v54, v10
	s_lshr_b32 s26, s26, 7
	v_dot2c_f32_bf16_e32 v50, v56, v8
	v_cvt_scalef32_pk_bf16_fp4 v52, v101, 1.0
	v_cvt_scalef32_pk_bf16_fp4 v54, v101, 1.0 op_sel:[1,0,0]
	v_cvt_scalef32_pk_bf16_fp4 v56, v101, 1.0 op_sel:[0,1,0]
	v_cvt_scalef32_pk_bf16_fp4 v60, v101, 1.0 op_sel:[1,1,0]
	s_mov_b32 s27, s86
	v_dot2c_f32_bf16_e32 v58, v52, v14
	v_dot2c_f32_bf16_e32 v50, v54, v12
	s_lshl_b64 s[26:27], s[26:27], 10
	v_dot2c_f32_bf16_e32 v58, v56, v18
	v_dot2c_f32_bf16_e32 v50, v60, v16
	v_cvt_scalef32_pk_bf16_fp4 v52, v102, 1.0
	v_cvt_scalef32_pk_bf16_fp4 v54, v102, 1.0 op_sel:[1,0,0]
	v_cvt_scalef32_pk_bf16_fp4 v56, v102, 1.0 op_sel:[0,1,0]
	v_cvt_scalef32_pk_bf16_fp4 v60, v102, 1.0 op_sel:[1,1,0]
	s_add_u32 s26, s13, s26
	v_dot2c_f32_bf16_e32 v58, v52, v22
	v_dot2c_f32_bf16_e32 v50, v54, v20
	s_addc_u32 s27, s12, s27
	v_dot2c_f32_bf16_e32 v58, v56, v26
	v_dot2c_f32_bf16_e32 v50, v60, v24
	v_cvt_scalef32_pk_bf16_fp4 v52, v103, 1.0
	v_cvt_scalef32_pk_bf16_fp4 v54, v103, 1.0 op_sel:[1,0,0]
	v_cvt_scalef32_pk_bf16_fp4 v56, v103, 1.0 op_sel:[0,1,0]
	v_cvt_scalef32_pk_bf16_fp4 v60, v103, 1.0 op_sel:[1,1,0]
	s_nop 0
	v_dot2c_f32_bf16_e32 v58, v52, v30
	v_dot2c_f32_bf16_e32 v50, v54, v28
	s_nop 0
	v_dot2c_f32_bf16_e32 v58, v56, v36
	v_dot2c_f32_bf16_e32 v50, v60, v34
	s_nop 0
	s_nop 2
	v_add_f32_e32 v49, v58, v50
	v_lshl_add_u64 v[50:51], s[26:27], 0, v[32:33]
	global_load_dwordx4 v[100:103], v[50:51], off
	s_waitcnt vmcnt(15)
; #define P4_FOR16(M) M(0) M(1) M(2) M(3) M(4) M(5) M(6) M(7) M(8) M(9) M(10) M(11) M(12) M(13) M(14) M(15)
; #define P4_U(i) { P4_DOT(b##i, part[i]); const int nk_ = __builtin_amdgcn_readlane(ksel, nb + i); P4_LOAD(b##i, Ug, nk_); }
; #define P4_U(i) { P4_DOT(b##i, part[i]); const int nk_ = __builtin_amdgcn_readlane(kn, i); P4_LOAD(b##i, nbase, nk_); }
; __device__ __forceinline__ void peer_gather_f4p(const float* X, const int* __restrict__ IDX, const float* __restrict__ G, ...
;     ...
;         {
;     ...
;             P4_FOR16(P4_U)
	v_cvt_scalef32_pk_bf16_fp4 v50, v104, 1.0
	v_mov_b32_e32 v58, 0
	v_cvt_scalef32_pk_bf16_fp4 v52, v104, 1.0 op_sel:[1,0,0]
	v_cvt_scalef32_pk_bf16_fp4 v54, v104, 1.0 op_sel:[0,1,0]
	v_cvt_scalef32_pk_bf16_fp4 v56, v104, 1.0 op_sel:[1,1,0]
	v_dot2c_f32_bf16_e32 v58, v50, v6
	v_mov_b32_e32 v50, 0
	v_dot2c_f32_bf16_e32 v50, v52, v4
	v_dot2c_f32_bf16_e32 v58, v54, v10
	v_readlane_b32 s26, v2, 9
	v_dot2c_f32_bf16_e32 v50, v56, v8
	v_cvt_scalef32_pk_bf16_fp4 v52, v105, 1.0
	v_cvt_scalef32_pk_bf16_fp4 v54, v105, 1.0 op_sel:[1,0,0]
	v_cvt_scalef32_pk_bf16_fp4 v56, v105, 1.0 op_sel:[0,1,0]
	v_cvt_scalef32_pk_bf16_fp4 v60, v105, 1.0 op_sel:[1,1,0]
	s_lshr_b32 s26, s26, 7
	v_dot2c_f32_bf16_e32 v58, v52, v14
	v_dot2c_f32_bf16_e32 v50, v54, v12
	s_mov_b32 s27, s86
	v_dot2c_f32_bf16_e32 v58, v56, v18
	v_dot2c_f32_bf16_e32 v50, v60, v16
	v_cvt_scalef32_pk_bf16_fp4 v52, v106, 1.0
	v_cvt_scalef32_pk_bf16_fp4 v54, v106, 1.0 op_sel:[1,0,0]
	v_cvt_scalef32_pk_bf16_fp4 v56, v106, 1.0 op_sel:[0,1,0]
	v_cvt_scalef32_pk_bf16_fp4 v60, v106, 1.0 op_sel:[1,1,0]
	s_lshl_b64 s[26:27], s[26:27], 10
	v_dot2c_f32_bf16_e32 v58, v52, v22
	v_dot2c_f32_bf16_e32 v50, v54, v20
	s_add_u32 s26, s13, s26
	v_dot2c_f32_bf16_e32 v58, v56, v26
	v_dot2c_f32_bf16_e32 v50, v60, v24
	v_cvt_scalef32_pk_bf16_fp4 v52, v107, 1.0
	v_cvt_scalef32_pk_bf16_fp4 v54, v107, 1.0 op_sel:[1,0,0]
	v_cvt_scalef32_pk_bf16_fp4 v56, v107, 1.0 op_sel:[0,1,0]
	v_cvt_scalef32_pk_bf16_fp4 v60, v107, 1.0 op_sel:[1,1,0]
	s_addc_u32 s27, s12, s27
	v_dot2c_f32_bf16_e32 v58, v52, v30
	v_dot2c_f32_bf16_e32 v50, v54, v28
	s_nop 0
	v_dot2c_f32_bf16_e32 v58, v56, v36
	v_dot2c_f32_bf16_e32 v50, v60, v34
	v_mov_b32_e32 v60, 0
	s_nop 2
	v_add_f32_e32 v50, v58, v50
	v_lshl_add_u64 v[52:53], s[26:27], 0, v[32:33]
	global_load_dwordx4 v[104:107], v[52:53], off
	s_waitcnt vmcnt(15)
	v_cvt_scalef32_pk_bf16_fp4 v52, v108, 1.0
	v_cvt_scalef32_pk_bf16_fp4 v54, v108, 1.0 op_sel:[1,0,0]
	v_cvt_scalef32_pk_bf16_fp4 v56, v108, 1.0 op_sel:[0,1,0]
	v_cvt_scalef32_pk_bf16_fp4 v58, v108, 1.0 op_sel:[1,1,0]
	v_readlane_b32 s26, v2, 10
	v_dot2c_f32_bf16_e32 v60, v52, v6
	v_mov_b32_e32 v52, 0
	v_dot2c_f32_bf16_e32 v52, v54, v4
	v_dot2c_f32_bf16_e32 v60, v56, v10
	s_lshr_b32 s26, s26, 7
	v_dot2c_f32_bf16_e32 v52, v58, v8
	v_cvt_scalef32_pk_bf16_fp4 v54, v109, 1.0
	v_cvt_scalef32_pk_bf16_fp4 v56, v109, 1.0 op_sel:[1,0,0]
	v_cvt_scalef32_pk_bf16_fp4 v58, v109, 1.0 op_sel:[0,1,0]
	v_cvt_scalef32_pk_bf16_fp4 v62, v109, 1.0 op_sel:[1,1,0]
	s_mov_b32 s27, s86
	v_dot2c_f32_bf16_e32 v60, v54, v14
	v_dot2c_f32_bf16_e32 v52, v56, v12
	s_lshl_b64 s[26:27], s[26:27], 10
	v_dot2c_f32_bf16_e32 v60, v58, v18
	v_dot2c_f32_bf16_e32 v52, v62, v16
	v_cvt_scalef32_pk_bf16_fp4 v54, v110, 1.0
	v_cvt_scalef32_pk_bf16_fp4 v56, v110, 1.0 op_sel:[1,0,0]
	v_cvt_scalef32_pk_bf16_fp4 v58, v110, 1.0 op_sel:[0,1,0]
	v_cvt_scalef32_pk_bf16_fp4 v62, v110, 1.0 op_sel:[1,1,0]
	s_add_u32 s26, s13, s26
	v_dot2c_f32_bf16_e32 v60, v54, v22
	v_dot2c_f32_bf16_e32 v52, v56, v20
	s_addc_u32 s27, s12, s27
	v_dot2c_f32_bf16_e32 v60, v58, v26
	v_dot2c_f32_bf16_e32 v52, v62, v24
	v_cvt_scalef32_pk_bf16_fp4 v54, v111, 1.0
	v_cvt_scalef32_pk_bf16_fp4 v56, v111, 1.0 op_sel:[1,0,0]
	v_cvt_scalef32_pk_bf16_fp4 v58, v111, 1.0 op_sel:[0,1,0]
	v_cvt_scalef32_pk_bf16_fp4 v62, v111, 1.0 op_sel:[1,1,0]
	s_nop 0
	v_dot2c_f32_bf16_e32 v60, v54, v30
	v_dot2c_f32_bf16_e32 v52, v56, v28
	s_nop 0
	v_dot2c_f32_bf16_e32 v60, v58, v36
	v_dot2c_f32_bf16_e32 v52, v62, v34
	s_nop 0
	s_nop 2
	v_add_f32_e32 v51, v60, v52
	v_lshl_add_u64 v[52:53], s[26:27], 0, v[32:33]
	global_load_dwordx4 v[108:111], v[52:53], off
	s_waitcnt vmcnt(15)
	v_cvt_scalef32_pk_bf16_fp4 v52, v112, 1.0
	v_mov_b32_e32 v60, 0
	v_cvt_scalef32_pk_bf16_fp4 v54, v112, 1.0 op_sel:[1,0,0]
	v_cvt_scalef32_pk_bf16_fp4 v56, v112, 1.0 op_sel:[0,1,0]
	v_cvt_scalef32_pk_bf16_fp4 v58, v112, 1.0 op_sel:[1,1,0]
	v_dot2c_f32_bf16_e32 v60, v52, v6
	v_mov_b32_e32 v52, 0
	v_dot2c_f32_bf16_e32 v52, v54, v4
	v_dot2c_f32_bf16_e32 v60, v56, v10
	v_readlane_b32 s26, v2, 11
	v_dot2c_f32_bf16_e32 v52, v58, v8
	v_cvt_scalef32_pk_bf16_fp4 v54, v113, 1.0
	v_cvt_scalef32_pk_bf16_fp4 v56, v113, 1.0 op_sel:[1,0,0]
	v_cvt_scalef32_pk_bf16_fp4 v58, v113, 1.0 op_sel:[0,1,0]
	v_cvt_scalef32_pk_bf16_fp4 v62, v113, 1.0 op_sel:[1,1,0]
	s_lshr_b32 s26, s26, 7
	v_dot2c_f32_bf16_e32 v60, v54, v14
	v_dot2c_f32_bf16_e32 v52, v56, v12
	s_mov_b32 s27, s86
	v_dot2c_f32_bf16_e32 v60, v58, v18
	v_dot2c_f32_bf16_e32 v52, v62, v16
	v_cvt_scalef32_pk_bf16_fp4 v54, v114, 1.0
	v_cvt_scalef32_pk_bf16_fp4 v56, v114, 1.0 op_sel:[1,0,0]
	v_cvt_scalef32_pk_bf16_fp4 v58, v114, 1.0 op_sel:[0,1,0]
	v_cvt_scalef32_pk_bf16_fp4 v62, v114, 1.0 op_sel:[1,1,0]
	s_lshl_b64 s[26:27], s[26:27], 10
	v_dot2c_f32_bf16_e32 v60, v54, v22
	v_dot2c_f32_bf16_e32 v52, v56, v20
	s_add_u32 s26, s13, s26
	v_dot2c_f32_bf16_e32 v60, v58, v26
	v_dot2c_f32_bf16_e32 v52, v62, v24
	v_cvt_scalef32_pk_bf16_fp4 v54, v115, 1.0
	v_cvt_scalef32_pk_bf16_fp4 v56, v115, 1.0 op_sel:[1,0,0]
	v_cvt_scalef32_pk_bf16_fp4 v58, v115, 1.0 op_sel:[0,1,0]
	v_cvt_scalef32_pk_bf16_fp4 v62, v115, 1.0 op_sel:[1,1,0]
	s_addc_u32 s27, s12, s27
	v_dot2c_f32_bf16_e32 v60, v54, v30
	v_dot2c_f32_bf16_e32 v52, v56, v28
	s_nop 0
	v_dot2c_f32_bf16_e32 v60, v58, v36
	v_dot2c_f32_bf16_e32 v52, v62, v34
	s_nop 0
	s_nop 2
	v_add_f32_e32 v80, v60, v52
	v_lshl_add_u64 v[52:53], s[26:27], 0, v[32:33]
	global_load_dwordx4 v[112:115], v[52:53], off
	s_waitcnt vmcnt(15)
; #define P4_FOR16(M) M(0) M(1) M(2) M(3) M(4) M(5) M(6) M(7) M(8) M(9) M(10) M(11) M(12) M(13) M(14) M(15)
; #define P4_U(i) { P4_DOT(b##i, part[i]); const int nk_ = __builtin_amdgcn_readlane(ksel, nb + i); P4_LOAD(b##i, Ug, nk_); }
; #define P4_U(i) { P4_DOT(b##i, part[i]); const int nk_ = __builtin_amdgcn_readlane(kn, i); P4_LOAD(b##i, nbase, nk_); }
; __device__ __forceinline__ void peer_gather_f4p(const float* X, const int* __restrict__ IDX, const float* __restrict__ G, ...
;     ...
;         {
;     ...
;             P4_FOR16(P4_U)
	v_cvt_scalef32_pk_bf16_fp4 v52, v116, 1.0
	v_mov_b32_e32 v60, 0
	v_cvt_scalef32_pk_bf16_fp4 v54, v116, 1.0 op_sel:[1,0,0]
	v_cvt_scalef32_pk_bf16_fp4 v56, v116, 1.0 op_sel:[0,1,0]
	v_cvt_scalef32_pk_bf16_fp4 v58, v116, 1.0 op_sel:[1,1,0]
	v_dot2c_f32_bf16_e32 v60, v52, v6
	v_mov_b32_e32 v52, 0
	v_dot2c_f32_bf16_e32 v52, v54, v4
	v_dot2c_f32_bf16_e32 v60, v56, v10
	v_readlane_b32 s26, v2, 12
	v_dot2c_f32_bf16_e32 v52, v58, v8
	v_cvt_scalef32_pk_bf16_fp4 v54, v117, 1.0
	v_cvt_scalef32_pk_bf16_fp4 v56, v117, 1.0 op_sel:[1,0,0]
	v_cvt_scalef32_pk_bf16_fp4 v58, v117, 1.0 op_sel:[0,1,0]
	v_cvt_scalef32_pk_bf16_fp4 v62, v117, 1.0 op_sel:[1,1,0]
	s_lshr_b32 s26, s26, 7
	v_dot2c_f32_bf16_e32 v60, v54, v14
	v_dot2c_f32_bf16_e32 v52, v56, v12
	s_mov_b32 s27, s86
	v_dot2c_f32_bf16_e32 v60, v58, v18
	v_dot2c_f32_bf16_e32 v52, v62, v16
	v_cvt_scalef32_pk_bf16_fp4 v54, v118, 1.0
	v_cvt_scalef32_pk_bf16_fp4 v56, v118, 1.0 op_sel:[1,0,0]
	v_cvt_scalef32_pk_bf16_fp4 v58, v118, 1.0 op_sel:[0,1,0]
	v_cvt_scalef32_pk_bf16_fp4 v62, v118, 1.0 op_sel:[1,1,0]
	s_lshl_b64 s[26:27], s[26:27], 10
	v_dot2c_f32_bf16_e32 v60, v54, v22
	v_dot2c_f32_bf16_e32 v52, v56, v20
	s_add_u32 s26, s13, s26
	v_dot2c_f32_bf16_e32 v60, v58, v26
	v_dot2c_f32_bf16_e32 v52, v62, v24
	v_cvt_scalef32_pk_bf16_fp4 v54, v119, 1.0
	v_cvt_scalef32_pk_bf16_fp4 v56, v119, 1.0 op_sel:[1,0,0]
	v_cvt_scalef32_pk_bf16_fp4 v58, v119, 1.0 op_sel:[0,1,0]
	v_cvt_scalef32_pk_bf16_fp4 v62, v119, 1.0 op_sel:[1,1,0]
	s_addc_u32 s27, s12, s27
	v_dot2c_f32_bf16_e32 v60, v54, v30
	v_dot2c_f32_bf16_e32 v52, v56, v28
	s_nop 0
	v_dot2c_f32_bf16_e32 v60, v58, v36
	v_dot2c_f32_bf16_e32 v52, v62, v34
	s_nop 0
	s_nop 2
	v_add_f32_e32 v81, v60, v52
	v_lshl_add_u64 v[52:53], s[26:27], 0, v[32:33]
	global_load_dwordx4 v[116:119], v[52:53], off
	s_waitcnt vmcnt(15)
	v_cvt_scalef32_pk_bf16_fp4 v52, v120, 1.0
	v_mov_b32_e32 v60, 0
	v_cvt_scalef32_pk_bf16_fp4 v54, v120, 1.0 op_sel:[1,0,0]
	v_cvt_scalef32_pk_bf16_fp4 v56, v120, 1.0 op_sel:[0,1,0]
	v_cvt_scalef32_pk_bf16_fp4 v58, v120, 1.0 op_sel:[1,1,0]
	v_dot2c_f32_bf16_e32 v60, v52, v6
	v_mov_b32_e32 v52, 0
	v_dot2c_f32_bf16_e32 v52, v54, v4
	v_dot2c_f32_bf16_e32 v60, v56, v10
	v_readlane_b32 s26, v2, 13
	v_dot2c_f32_bf16_e32 v52, v58, v8
	v_cvt_scalef32_pk_bf16_fp4 v54, v121, 1.0
	v_cvt_scalef32_pk_bf16_fp4 v56, v121, 1.0 op_sel:[1,0,0]
	v_cvt_scalef32_pk_bf16_fp4 v58, v121, 1.0 op_sel:[0,1,0]
	v_cvt_scalef32_pk_bf16_fp4 v62, v121, 1.0 op_sel:[1,1,0]
	s_lshr_b32 s26, s26, 7
	v_dot2c_f32_bf16_e32 v60, v54, v14
	v_dot2c_f32_bf16_e32 v52, v56, v12
	s_mov_b32 s27, s86
	v_dot2c_f32_bf16_e32 v60, v58, v18
	v_dot2c_f32_bf16_e32 v52, v62, v16
	v_cvt_scalef32_pk_bf16_fp4 v54, v122, 1.0
	v_cvt_scalef32_pk_bf16_fp4 v56, v122, 1.0 op_sel:[1,0,0]
	v_cvt_scalef32_pk_bf16_fp4 v58, v122, 1.0 op_sel:[0,1,0]
	v_cvt_scalef32_pk_bf16_fp4 v62, v122, 1.0 op_sel:[1,1,0]
	s_lshl_b64 s[26:27], s[26:27], 10
	v_dot2c_f32_bf16_e32 v60, v54, v22
	v_dot2c_f32_bf16_e32 v52, v56, v20
	s_add_u32 s26, s13, s26
	v_dot2c_f32_bf16_e32 v60, v58, v26
	v_dot2c_f32_bf16_e32 v52, v62, v24
	v_cvt_scalef32_pk_bf16_fp4 v54, v123, 1.0
	v_cvt_scalef32_pk_bf16_fp4 v56, v123, 1.0 op_sel:[1,0,0]
	v_cvt_scalef32_pk_bf16_fp4 v58, v123, 1.0 op_sel:[0,1,0]
	v_cvt_scalef32_pk_bf16_fp4 v62, v123, 1.0 op_sel:[1,1,0]
	s_addc_u32 s27, s12, s27
	v_dot2c_f32_bf16_e32 v60, v54, v30
	v_dot2c_f32_bf16_e32 v52, v56, v28
	s_nop 0
	v_dot2c_f32_bf16_e32 v60, v58, v36
	v_dot2c_f32_bf16_e32 v52, v62, v34
	s_nop 0
	s_nop 2
	v_add_f32_e32 v82, v60, v52
	v_lshl_add_u64 v[52:53], s[26:27], 0, v[32:33]
	global_load_dwordx4 v[120:123], v[52:53], off
	s_waitcnt vmcnt(15)
	v_cvt_scalef32_pk_bf16_fp4 v52, v124, 1.0
	v_mov_b32_e32 v60, 0
	v_cvt_scalef32_pk_bf16_fp4 v54, v124, 1.0 op_sel:[1,0,0]
	v_cvt_scalef32_pk_bf16_fp4 v56, v124, 1.0 op_sel:[0,1,0]
	v_cvt_scalef32_pk_bf16_fp4 v58, v124, 1.0 op_sel:[1,1,0]
	v_dot2c_f32_bf16_e32 v60, v52, v6
	v_mov_b32_e32 v52, 0
	v_dot2c_f32_bf16_e32 v52, v54, v4
	v_dot2c_f32_bf16_e32 v60, v56, v10
	v_readlane_b32 s26, v2, 14
	v_dot2c_f32_bf16_e32 v52, v58, v8
	v_cvt_scalef32_pk_bf16_fp4 v54, v125, 1.0
	v_cvt_scalef32_pk_bf16_fp4 v56, v125, 1.0 op_sel:[1,0,0]
	v_cvt_scalef32_pk_bf16_fp4 v58, v125, 1.0 op_sel:[0,1,0]
	v_cvt_scalef32_pk_bf16_fp4 v62, v125, 1.0 op_sel:[1,1,0]
	s_lshr_b32 s26, s26, 7
	v_dot2c_f32_bf16_e32 v60, v54, v14
	v_dot2c_f32_bf16_e32 v52, v56, v12
	s_mov_b32 s27, s86
	v_dot2c_f32_bf16_e32 v60, v58, v18
	v_dot2c_f32_bf16_e32 v52, v62, v16
	v_cvt_scalef32_pk_bf16_fp4 v54, v126, 1.0
	v_cvt_scalef32_pk_bf16_fp4 v56, v126, 1.0 op_sel:[1,0,0]
	v_cvt_scalef32_pk_bf16_fp4 v58, v126, 1.0 op_sel:[0,1,0]
	v_cvt_scalef32_pk_bf16_fp4 v62, v126, 1.0 op_sel:[1,1,0]
	s_lshl_b64 s[26:27], s[26:27], 10
	v_dot2c_f32_bf16_e32 v60, v54, v22
	v_dot2c_f32_bf16_e32 v52, v56, v20
	s_add_u32 s26, s13, s26
	v_dot2c_f32_bf16_e32 v60, v58, v26
	v_dot2c_f32_bf16_e32 v52, v62, v24
	v_cvt_scalef32_pk_bf16_fp4 v54, v127, 1.0
	v_cvt_scalef32_pk_bf16_fp4 v56, v127, 1.0 op_sel:[1,0,0]
	v_cvt_scalef32_pk_bf16_fp4 v58, v127, 1.0 op_sel:[0,1,0]
	v_cvt_scalef32_pk_bf16_fp4 v62, v127, 1.0 op_sel:[1,1,0]
	s_addc_u32 s27, s12, s27
	v_dot2c_f32_bf16_e32 v60, v54, v30
	v_dot2c_f32_bf16_e32 v52, v56, v28
	s_nop 0
	v_dot2c_f32_bf16_e32 v60, v58, v36
	v_dot2c_f32_bf16_e32 v52, v62, v34
	s_nop 0
	s_nop 2
	v_add_f32_e32 v62, v60, v52
	v_lshl_add_u64 v[52:53], s[26:27], 0, v[32:33]
	v_mov_b32_e32 v60, 0
	global_load_dwordx4 v[124:127], v[52:53], off
	s_waitcnt vmcnt(15)
	v_cvt_scalef32_pk_bf16_fp4 v52, v128, 1.0
	v_cvt_scalef32_pk_bf16_fp4 v54, v128, 1.0 op_sel:[1,0,0]
	v_cvt_scalef32_pk_bf16_fp4 v56, v128, 1.0 op_sel:[0,1,0]
	v_cvt_scalef32_pk_bf16_fp4 v58, v128, 1.0 op_sel:[1,1,0]
	v_readlane_b32 s26, v2, 15
	v_dot2c_f32_bf16_e32 v60, v52, v6
	v_dot2c_f32_bf16_e32 v38, v54, v4
	s_lshr_b32 s26, s26, 7
	v_dot2c_f32_bf16_e32 v60, v56, v10
	v_dot2c_f32_bf16_e32 v38, v58, v8
	v_cvt_scalef32_pk_bf16_fp4 v4, v129, 1.0
	v_cvt_scalef32_pk_bf16_fp4 v6, v129, 1.0 op_sel:[1,0,0]
	v_cvt_scalef32_pk_bf16_fp4 v8, v129, 1.0 op_sel:[0,1,0]
	v_cvt_scalef32_pk_bf16_fp4 v10, v129, 1.0 op_sel:[1,1,0]
	s_mov_b32 s27, s86
	v_dot2c_f32_bf16_e32 v60, v4, v14
	v_dot2c_f32_bf16_e32 v38, v6, v12
	s_lshl_b64 s[26:27], s[26:27], 10
	v_dot2c_f32_bf16_e32 v60, v8, v18
	v_dot2c_f32_bf16_e32 v38, v10, v16
	v_cvt_scalef32_pk_bf16_fp4 v4, v130, 1.0
	v_cvt_scalef32_pk_bf16_fp4 v6, v130, 1.0 op_sel:[1,0,0]
	v_cvt_scalef32_pk_bf16_fp4 v8, v130, 1.0 op_sel:[0,1,0]
	v_cvt_scalef32_pk_bf16_fp4 v10, v130, 1.0 op_sel:[1,1,0]
	s_add_u32 s26, s13, s26
	v_dot2c_f32_bf16_e32 v60, v4, v22
	v_dot2c_f32_bf16_e32 v38, v6, v20
	s_addc_u32 s27, s12, s27
	v_dot2c_f32_bf16_e32 v60, v8, v26
	v_dot2c_f32_bf16_e32 v38, v10, v24
	v_cvt_scalef32_pk_bf16_fp4 v4, v131, 1.0
	v_cvt_scalef32_pk_bf16_fp4 v6, v131, 1.0 op_sel:[1,0,0]
	v_cvt_scalef32_pk_bf16_fp4 v8, v131, 1.0 op_sel:[0,1,0]
	v_cvt_scalef32_pk_bf16_fp4 v10, v131, 1.0 op_sel:[1,1,0]
	v_cndmask_b32_e64 v2, v49, v41, s[46:47]
	v_dot2c_f32_bf16_e32 v60, v4, v30
	v_dot2c_f32_bf16_e32 v38, v6, v28
	v_cndmask_b32_e64 v7, v43, v51, s[46:47]
	v_dot2c_f32_bf16_e32 v60, v8, v36
	v_dot2c_f32_bf16_e32 v38, v10, v34
	ds_swizzle_b32 v7, v7 offset:swizzle(SWAP,8)
	s_nop 2
	v_add_f32_e32 v6, v60, v38
	v_lshl_add_u64 v[4:5], s[26:27], 0, v[32:33]
	global_load_dwordx4 v[128:131], v[4:5], off
	v_cndmask_b32_e64 v4, v41, v49, s[46:47]
	ds_swizzle_b32 v4, v4 offset:swizzle(SWAP,8)
	v_cndmask_b32_e64 v5, v42, v50, s[46:47]
	ds_swizzle_b32 v5, v5 offset:swizzle(SWAP,8)
	v_cndmask_b32_e64 v8, v44, v80, s[46:47]
	ds_swizzle_b32 v8, v8 offset:swizzle(SWAP,8)
	v_cndmask_b32_e64 v9, v45, v81, s[46:47]
	ds_swizzle_b32 v9, v9 offset:swizzle(SWAP,8)
	v_cndmask_b32_e64 v10, v46, v82, s[46:47]
	s_waitcnt lgkmcnt(3)
	v_add_f32_e32 v2, v2, v4
	v_cndmask_b32_e64 v4, v50, v42, s[46:47]
	ds_swizzle_b32 v10, v10 offset:swizzle(SWAP,8)
	v_cndmask_b32_e64 v11, v47, v62, s[46:47]
	s_waitcnt lgkmcnt(3)
	v_add_f32_e32 v4, v4, v5
	v_cndmask_b32_e64 v5, v51, v43, s[46:47]
	ds_swizzle_b32 v11, v11 offset:swizzle(SWAP,8)
	v_add_f32_e32 v5, v5, v7
	v_cndmask_b32_e64 v7, v80, v44, s[46:47]
	s_waitcnt lgkmcnt(3)
	v_add_f32_e32 v7, v7, v8
	v_cndmask_b32_e64 v8, v81, v45, s[46:47]
	s_waitcnt lgkmcnt(2)
	v_add_f32_e32 v8, v8, v9
	v_cndmask_b32_e64 v9, v82, v46, s[46:47]
	s_waitcnt lgkmcnt(1)
	v_add_f32_e32 v9, v9, v10
	v_cndmask_b32_e64 v10, v62, v47, s[46:47]
	s_waitcnt lgkmcnt(0)
	v_add_f32_e32 v10, v10, v11
	v_cndmask_b32_e64 v11, v6, v48, s[46:47]
	v_cndmask_b32_e64 v6, v48, v6, s[46:47]
	ds_swizzle_b32 v6, v6 offset:swizzle(SWAP,8)
	s_waitcnt lgkmcnt(0)
	v_add_f32_e32 v6, v11, v6
	v_cndmask_b32_e64 v11, v8, v2, s[44:45]
	v_cndmask_b32_e64 v2, v2, v8, s[44:45]
	v_cndmask_b32_e64 v8, v9, v4, s[44:45]
	v_cndmask_b32_e64 v4, v4, v9, s[44:45]
	ds_swizzle_b32 v4, v4 offset:swizzle(SWAP,4)
	ds_swizzle_b32 v2, v2 offset:swizzle(SWAP,4)
	s_waitcnt lgkmcnt(1)
	v_add_f32_e32 v4, v8, v4
	v_cndmask_b32_e64 v8, v10, v5, s[44:45]
	v_cndmask_b32_e64 v5, v5, v10, s[44:45]
	ds_swizzle_b32 v5, v5 offset:swizzle(SWAP,4)
	s_waitcnt lgkmcnt(1)
	v_add_f32_e32 v2, v11, v2
	s_waitcnt lgkmcnt(0)
	v_add_f32_e32 v5, v8, v5
	v_cndmask_b32_e64 v8, v6, v7, s[44:45]
	v_cndmask_b32_e64 v6, v7, v6, s[44:45]
	ds_swizzle_b32 v6, v6 offset:swizzle(SWAP,4)
	v_cndmask_b32_e64 v7, v5, v2, s[42:43]
	v_cndmask_b32_e64 v2, v2, v5, s[42:43]
	ds_swizzle_b32 v2, v2 offset:swizzle(SWAP,2)
	s_waitcnt lgkmcnt(1)
	v_add_f32_e32 v6, v8, v6
	v_cndmask_b32_e64 v5, v6, v4, s[42:43]
	v_cndmask_b32_e64 v4, v4, v6, s[42:43]
	ds_swizzle_b32 v4, v4 offset:swizzle(SWAP,2)
	s_waitcnt lgkmcnt(1)
	v_add_f32_e32 v2, v7, v2
	s_waitcnt lgkmcnt(0)
	v_add_f32_e32 v4, v5, v4
	v_cndmask_b32_e64 v5, v4, v2, s[40:41]
	v_cndmask_b32_e64 v2, v2, v4, s[40:41]
	ds_swizzle_b32 v2, v2 offset:swizzle(SWAP,1)
	s_waitcnt lgkmcnt(0)
	v_add_f32_e32 v2, v5, v2
	ds_swizzle_b32 v4, v2 offset:swizzle(SWAP,16)
	s_waitcnt lgkmcnt(0)
	v_add_f32_e32 v2, v2, v4
	v_mov_b32_e32 v4, v2
	s_nop 1
	v_permlane32_swap_b32_e32 v2, v4
	v_add_f32_e32 v6, v2, v4
	v_lshl_add_u32 v2, v40, 2, s14
	v_add_u32_e32 v4, 0xc0, v2
	ds_read2st64_b32 v[4:5], v4 offset0:9 offset1:17
	s_waitcnt lgkmcnt(0)
	v_mul_f32_e32 v4, v4, v6
	v_mul_f32_e32 v6, 0x3d372713, v4
	v_mul_f32_e32 v6, v4, v6
	v_fma_f32 v6, v4, v6, v4
	v_mul_f32_e32 v6, 0x3f4c422a, v6
	v_cmp_nlt_f32_e64 s[12:13], |v6|, s25
	s_and_saveexec_b64 s[26:27], s[12:13]
	s_xor_b64 s[12:13], exec, s[26:27]
	s_cbranch_execz .LBB0_1240
	v_add_f32_e64 v7, |v6|, |v6|
	v_mul_f32_e32 v8, 0x3fb8aa3b, v7
	v_rndne_f32_e32 v9, v8
	v_sub_f32_e32 v10, v8, v9
	v_fma_f32 v8, v7, s70, -v8
	v_fmac_f32_e32 v8, 0x32a5705f, v7
	v_add_f32_e32 v8, v10, v8
	v_cvt_i32_f32_e32 v9, v9
	v_exp_f32_e32 v8, v8
	v_cmp_ngt_f32_e64 s[40:41], s67, v7
	v_ldexp_f32 v8, v8, v9
	s_nop 0
	v_cndmask_b32_e64 v8, 0, v8, s[40:41]
	v_cmp_nlt_f32_e64 s[40:41], s68, v7
	s_nop 1
	v_cndmask_b32_e64 v7, v205, v8, s[40:41]
	v_add_f32_e32 v7, 1.0, v7
	v_rcp_f32_e32 v7, v7
	s_nop 0
	v_fma_f32 v7, v7, -2.0, 1.0
	s_andn2_saveexec_b64 s[12:13], s[12:13]
	s_cbranch_execnz .LBB0_1241
